# X hand-off between resid GEMM and fused norm at agent scope (sc1 stores and loads) instead of system scope
# speedup vs baseline: 1.0392x; 1.0036x over previous
.Lr6_loop:
	s_waitcnt vmcnt(8)
	s_barrier
	ds_read_b128 v[64:67], v252 offset:0
	ds_read_b128 v[96:99], v254 offset:32768
	ds_read_b128 v[100:103], v254 offset:34816
	ds_read_b128 v[104:107], v254 offset:36864
	ds_read_b128 v[108:111], v254 offset:38912
	ds_read_b128 v[68:71], v252 offset:2048
	ds_read_b128 v[72:75], v252 offset:4096
	ds_read_b128 v[76:79], v252 offset:6144
	v_mfma_f32_16x16x32_bf16 v[0:3], v[80:83], v[112:115], v[0:3]
	v_mfma_f32_16x16x32_bf16 v[4:7], v[80:83], v[116:119], v[4:7]
	v_mfma_f32_16x16x32_bf16 v[8:11], v[80:83], v[120:123], v[8:11]
	v_mfma_f32_16x16x32_bf16 v[12:15], v[80:83], v[124:127], v[12:15]
	v_mfma_f32_16x16x32_bf16 v[16:19], v[84:87], v[112:115], v[16:19]
	v_mfma_f32_16x16x32_bf16 v[20:23], v[84:87], v[116:119], v[20:23]
	v_mfma_f32_16x16x32_bf16 v[24:27], v[84:87], v[120:123], v[24:27]
	v_mfma_f32_16x16x32_bf16 v[28:31], v[84:87], v[124:127], v[28:31]
	v_mfma_f32_16x16x32_bf16 v[32:35], v[88:91], v[112:115], v[32:35]
	v_mfma_f32_16x16x32_bf16 v[36:39], v[88:91], v[116:119], v[36:39]
	v_mfma_f32_16x16x32_bf16 v[40:43], v[88:91], v[120:123], v[40:43]
	v_mfma_f32_16x16x32_bf16 v[44:47], v[88:91], v[124:127], v[44:47]
	v_mfma_f32_16x16x32_bf16 v[48:51], v[92:95], v[112:115], v[48:51]
	v_mfma_f32_16x16x32_bf16 v[52:55], v[92:95], v[116:119], v[52:55]
	v_mfma_f32_16x16x32_bf16 v[56:59], v[92:95], v[120:123], v[56:59]
	v_mfma_f32_16x16x32_bf16 v[60:63], v[92:95], v[124:127], v[60:63]
	ds_read_b128 v[80:83], v253 offset:0
	ds_read_b128 v[112:115], v255 offset:32768
	ds_read_b128 v[116:119], v255 offset:34816
	ds_read_b128 v[120:123], v255 offset:36864
	ds_read_b128 v[124:127], v255 offset:38912
	ds_read_b128 v[84:87], v253 offset:2048
	ds_read_b128 v[88:91], v253 offset:4096
	ds_read_b128 v[92:95], v253 offset:6144
	s_waitcnt lgkmcnt(14)
	v_mfma_f32_16x16x32_bf16 v[0:3], v[64:67], v[96:99], v[0:3]
	s_waitcnt lgkmcnt(13)
	v_mfma_f32_16x16x32_bf16 v[4:7], v[64:67], v[100:103], v[4:7]
	s_waitcnt lgkmcnt(12)
	v_mfma_f32_16x16x32_bf16 v[8:11], v[64:67], v[104:107], v[8:11]
	s_waitcnt lgkmcnt(11)
	v_mfma_f32_16x16x32_bf16 v[12:15], v[64:67], v[108:111], v[12:15]
	s_waitcnt lgkmcnt(10)
	v_mfma_f32_16x16x32_bf16 v[16:19], v[68:71], v[96:99], v[16:19]
	v_mfma_f32_16x16x32_bf16 v[20:23], v[68:71], v[100:103], v[20:23]
	v_mfma_f32_16x16x32_bf16 v[24:27], v[68:71], v[104:107], v[24:27]
	v_mfma_f32_16x16x32_bf16 v[28:31], v[68:71], v[108:111], v[28:31]
	s_waitcnt lgkmcnt(0)
	s_barrier
	s_add_u32 m0, s12, 0x0
	v_mfma_f32_16x16x32_bf16 v[32:35], v[72:75], v[96:99], v[32:35]
	global_load_lds_dwordx4 v248, s[8:9]
	s_add_u32 m0, s12, 0x400
	v_mfma_f32_16x16x32_bf16 v[36:39], v[72:75], v[100:103], v[36:39]
	global_load_lds_dwordx4 v249, s[8:9]
	s_add_u32 m0, s12, 0x800
	v_mfma_f32_16x16x32_bf16 v[40:43], v[72:75], v[104:107], v[40:43]
	global_load_lds_dwordx4 v250, s[8:9]
	s_add_u32 m0, s12, 0xc00
	v_mfma_f32_16x16x32_bf16 v[44:47], v[72:75], v[108:111], v[44:47]
	global_load_lds_dwordx4 v251, s[8:9]
	s_add_u32 m0, s12, 0x8000
	v_mfma_f32_16x16x32_bf16 v[48:51], v[76:79], v[96:99], v[48:51]
	global_load_lds_dwordx4 v248, s[10:11] sc1
	s_add_u32 m0, s12, 0x8400
	v_mfma_f32_16x16x32_bf16 v[52:55], v[76:79], v[100:103], v[52:55]
	global_load_lds_dwordx4 v249, s[10:11] sc1
	s_add_u32 m0, s12, 0x8800
	v_mfma_f32_16x16x32_bf16 v[56:59], v[76:79], v[104:107], v[56:59]
	global_load_lds_dwordx4 v250, s[10:11] sc1
	s_add_u32 m0, s12, 0x8c00
	v_mfma_f32_16x16x32_bf16 v[60:63], v[76:79], v[108:111], v[60:63]
	global_load_lds_dwordx4 v251, s[10:11] sc1
	s_add_u32 s8, s8, 0x80
	s_addc_u32 s9, s9, 0
	s_add_u32 s10, s10, 0x80
	s_addc_u32 s11, s11, 0
	s_waitcnt vmcnt(8)
	s_barrier
	ds_read_b128 v[64:67], v252 offset:16384
	ds_read_b128 v[96:99], v254 offset:49152
	ds_read_b128 v[100:103], v254 offset:51200
	ds_read_b128 v[104:107], v254 offset:53248
	ds_read_b128 v[108:111], v254 offset:55296
	ds_read_b128 v[68:71], v252 offset:18432
	ds_read_b128 v[72:75], v252 offset:20480
	ds_read_b128 v[76:79], v252 offset:22528
	v_mfma_f32_16x16x32_bf16 v[0:3], v[80:83], v[112:115], v[0:3]
	v_mfma_f32_16x16x32_bf16 v[4:7], v[80:83], v[116:119], v[4:7]
	v_mfma_f32_16x16x32_bf16 v[8:11], v[80:83], v[120:123], v[8:11]
	v_mfma_f32_16x16x32_bf16 v[12:15], v[80:83], v[124:127], v[12:15]
	v_mfma_f32_16x16x32_bf16 v[16:19], v[84:87], v[112:115], v[16:19]
	v_mfma_f32_16x16x32_bf16 v[20:23], v[84:87], v[116:119], v[20:23]
	v_mfma_f32_16x16x32_bf16 v[24:27], v[84:87], v[120:123], v[24:27]
	v_mfma_f32_16x16x32_bf16 v[28:31], v[84:87], v[124:127], v[28:31]
	v_mfma_f32_16x16x32_bf16 v[32:35], v[88:91], v[112:115], v[32:35]
	v_mfma_f32_16x16x32_bf16 v[36:39], v[88:91], v[116:119], v[36:39]
	v_mfma_f32_16x16x32_bf16 v[40:43], v[88:91], v[120:123], v[40:43]
	v_mfma_f32_16x16x32_bf16 v[44:47], v[88:91], v[124:127], v[44:47]
	v_mfma_f32_16x16x32_bf16 v[48:51], v[92:95], v[112:115], v[48:51]
	v_mfma_f32_16x16x32_bf16 v[52:55], v[92:95], v[116:119], v[52:55]
	v_mfma_f32_16x16x32_bf16 v[56:59], v[92:95], v[120:123], v[56:59]
	v_mfma_f32_16x16x32_bf16 v[60:63], v[92:95], v[124:127], v[60:63]
	ds_read_b128 v[80:83], v253 offset:16384
	ds_read_b128 v[112:115], v255 offset:49152
	ds_read_b128 v[116:119], v255 offset:51200
	ds_read_b128 v[120:123], v255 offset:53248
	ds_read_b128 v[124:127], v255 offset:55296
	ds_read_b128 v[84:87], v253 offset:18432
	ds_read_b128 v[88:91], v253 offset:20480
	ds_read_b128 v[92:95], v253 offset:22528
	s_waitcnt lgkmcnt(14)
	v_mfma_f32_16x16x32_bf16 v[0:3], v[64:67], v[96:99], v[0:3]
	s_waitcnt lgkmcnt(13)
	v_mfma_f32_16x16x32_bf16 v[4:7], v[64:67], v[100:103], v[4:7]
	s_waitcnt lgkmcnt(12)
	v_mfma_f32_16x16x32_bf16 v[8:11], v[64:67], v[104:107], v[8:11]
	s_waitcnt lgkmcnt(11)
	v_mfma_f32_16x16x32_bf16 v[12:15], v[64:67], v[108:111], v[12:15]
	s_waitcnt lgkmcnt(10)
	v_mfma_f32_16x16x32_bf16 v[16:19], v[68:71], v[96:99], v[16:19]
	v_mfma_f32_16x16x32_bf16 v[20:23], v[68:71], v[100:103], v[20:23]
	v_mfma_f32_16x16x32_bf16 v[24:27], v[68:71], v[104:107], v[24:27]
	v_mfma_f32_16x16x32_bf16 v[28:31], v[68:71], v[108:111], v[28:31]
	s_waitcnt lgkmcnt(0)
	s_barrier
	s_add_u32 m0, s12, 0x4000
	v_mfma_f32_16x16x32_bf16 v[32:35], v[72:75], v[96:99], v[32:35]
	global_load_lds_dwordx4 v248, s[8:9]
	s_add_u32 m0, s12, 0x4400
	v_mfma_f32_16x16x32_bf16 v[36:39], v[72:75], v[100:103], v[36:39]
	global_load_lds_dwordx4 v249, s[8:9]
	s_add_u32 m0, s12, 0x4800
	v_mfma_f32_16x16x32_bf16 v[40:43], v[72:75], v[104:107], v[40:43]
	global_load_lds_dwordx4 v250, s[8:9]
	s_add_u32 m0, s12, 0x4c00
	v_mfma_f32_16x16x32_bf16 v[44:47], v[72:75], v[108:111], v[44:47]
	global_load_lds_dwordx4 v251, s[8:9]
	s_add_u32 m0, s12, 0xc000
	v_mfma_f32_16x16x32_bf16 v[48:51], v[76:79], v[96:99], v[48:51]
	global_load_lds_dwordx4 v248, s[10:11] sc1
	s_add_u32 m0, s12, 0xc400
	v_mfma_f32_16x16x32_bf16 v[52:55], v[76:79], v[100:103], v[52:55]
	global_load_lds_dwordx4 v249, s[10:11] sc1
	s_add_u32 m0, s12, 0xc800
	v_mfma_f32_16x16x32_bf16 v[56:59], v[76:79], v[104:107], v[56:59]
	global_load_lds_dwordx4 v250, s[10:11] sc1
	s_add_u32 m0, s12, 0xcc00
	v_mfma_f32_16x16x32_bf16 v[60:63], v[76:79], v[108:111], v[60:63]
	global_load_lds_dwordx4 v251, s[10:11] sc1
	s_add_u32 s8, s8, 0x80
	s_addc_u32 s9, s9, 0
	s_add_u32 s10, s10, 0x80
	s_addc_u32 s11, s11, 0
	s_sub_u32 s13, s13, 1
	s_cmp_lg_u32 s13, 0
	s_cbranch_scc1 .Lr6_loop
	s_waitcnt vmcnt(8)
	s_barrier
	ds_read_b128 v[64:67], v252 offset:0
	ds_read_b128 v[96:99], v254 offset:32768
	ds_read_b128 v[100:103], v254 offset:34816
	ds_read_b128 v[104:107], v254 offset:36864
	ds_read_b128 v[108:111], v254 offset:38912
	ds_read_b128 v[68:71], v252 offset:2048
	ds_read_b128 v[72:75], v252 offset:4096
	ds_read_b128 v[76:79], v252 offset:6144
	v_mfma_f32_16x16x32_bf16 v[0:3], v[80:83], v[112:115], v[0:3]
	v_mfma_f32_16x16x32_bf16 v[4:7], v[80:83], v[116:119], v[4:7]
	v_mfma_f32_16x16x32_bf16 v[8:11], v[80:83], v[120:123], v[8:11]
	v_mfma_f32_16x16x32_bf16 v[12:15], v[80:83], v[124:127], v[12:15]
	v_mfma_f32_16x16x32_bf16 v[16:19], v[84:87], v[112:115], v[16:19]
	v_mfma_f32_16x16x32_bf16 v[20:23], v[84:87], v[116:119], v[20:23]
	v_mfma_f32_16x16x32_bf16 v[24:27], v[84:87], v[120:123], v[24:27]
	v_mfma_f32_16x16x32_bf16 v[28:31], v[84:87], v[124:127], v[28:31]
	v_mfma_f32_16x16x32_bf16 v[32:35], v[88:91], v[112:115], v[32:35]
	v_mfma_f32_16x16x32_bf16 v[36:39], v[88:91], v[116:119], v[36:39]
	v_mfma_f32_16x16x32_bf16 v[40:43], v[88:91], v[120:123], v[40:43]
	v_mfma_f32_16x16x32_bf16 v[44:47], v[88:91], v[124:127], v[44:47]
	v_mfma_f32_16x16x32_bf16 v[48:51], v[92:95], v[112:115], v[48:51]
	v_mfma_f32_16x16x32_bf16 v[52:55], v[92:95], v[116:119], v[52:55]
	v_mfma_f32_16x16x32_bf16 v[56:59], v[92:95], v[120:123], v[56:59]
	v_mfma_f32_16x16x32_bf16 v[60:63], v[92:95], v[124:127], v[60:63]
	ds_read_b128 v[80:83], v253 offset:0
	ds_read_b128 v[112:115], v255 offset:32768
	ds_read_b128 v[116:119], v255 offset:34816
	ds_read_b128 v[120:123], v255 offset:36864
	ds_read_b128 v[124:127], v255 offset:38912
	ds_read_b128 v[84:87], v253 offset:2048
	ds_read_b128 v[88:91], v253 offset:4096
	ds_read_b128 v[92:95], v253 offset:6144
	s_waitcnt lgkmcnt(14)
	v_mfma_f32_16x16x32_bf16 v[0:3], v[64:67], v[96:99], v[0:3]
	s_waitcnt lgkmcnt(13)
	v_mfma_f32_16x16x32_bf16 v[4:7], v[64:67], v[100:103], v[4:7]
	s_waitcnt lgkmcnt(12)
	v_mfma_f32_16x16x32_bf16 v[8:11], v[64:67], v[104:107], v[8:11]
	s_waitcnt lgkmcnt(11)
	v_mfma_f32_16x16x32_bf16 v[12:15], v[64:67], v[108:111], v[12:15]
	s_waitcnt lgkmcnt(10)
	v_mfma_f32_16x16x32_bf16 v[16:19], v[68:71], v[96:99], v[16:19]
	v_mfma_f32_16x16x32_bf16 v[20:23], v[68:71], v[100:103], v[20:23]
	v_mfma_f32_16x16x32_bf16 v[24:27], v[68:71], v[104:107], v[24:27]
	v_mfma_f32_16x16x32_bf16 v[28:31], v[68:71], v[108:111], v[28:31]
	s_waitcnt lgkmcnt(0)
	s_barrier
	v_mfma_f32_16x16x32_bf16 v[32:35], v[72:75], v[96:99], v[32:35]
	v_mfma_f32_16x16x32_bf16 v[36:39], v[72:75], v[100:103], v[36:39]
	v_mfma_f32_16x16x32_bf16 v[40:43], v[72:75], v[104:107], v[40:43]
	v_mfma_f32_16x16x32_bf16 v[44:47], v[72:75], v[108:111], v[44:47]
	v_mfma_f32_16x16x32_bf16 v[48:51], v[76:79], v[96:99], v[48:51]
	v_mfma_f32_16x16x32_bf16 v[52:55], v[76:79], v[100:103], v[52:55]
	v_mfma_f32_16x16x32_bf16 v[56:59], v[76:79], v[104:107], v[56:59]
	v_mfma_f32_16x16x32_bf16 v[60:63], v[76:79], v[108:111], v[60:63]
	s_waitcnt vmcnt(0)
	s_barrier
	ds_read_b128 v[64:67], v252 offset:16384
	ds_read_b128 v[96:99], v254 offset:49152
	ds_read_b128 v[100:103], v254 offset:51200
	ds_read_b128 v[104:107], v254 offset:53248
	ds_read_b128 v[108:111], v254 offset:55296
	ds_read_b128 v[68:71], v252 offset:18432
	ds_read_b128 v[72:75], v252 offset:20480
	ds_read_b128 v[76:79], v252 offset:22528
	v_mfma_f32_16x16x32_bf16 v[0:3], v[80:83], v[112:115], v[0:3]
	v_mfma_f32_16x16x32_bf16 v[4:7], v[80:83], v[116:119], v[4:7]
	v_mfma_f32_16x16x32_bf16 v[8:11], v[80:83], v[120:123], v[8:11]
	v_mfma_f32_16x16x32_bf16 v[12:15], v[80:83], v[124:127], v[12:15]
	v_mfma_f32_16x16x32_bf16 v[16:19], v[84:87], v[112:115], v[16:19]
	v_mfma_f32_16x16x32_bf16 v[20:23], v[84:87], v[116:119], v[20:23]
	v_mfma_f32_16x16x32_bf16 v[24:27], v[84:87], v[120:123], v[24:27]
	v_mfma_f32_16x16x32_bf16 v[28:31], v[84:87], v[124:127], v[28:31]
	v_mfma_f32_16x16x32_bf16 v[32:35], v[88:91], v[112:115], v[32:35]
	v_mfma_f32_16x16x32_bf16 v[36:39], v[88:91], v[116:119], v[36:39]
	v_mfma_f32_16x16x32_bf16 v[40:43], v[88:91], v[120:123], v[40:43]
	v_mfma_f32_16x16x32_bf16 v[44:47], v[88:91], v[124:127], v[44:47]
	v_mfma_f32_16x16x32_bf16 v[48:51], v[92:95], v[112:115], v[48:51]
	v_mfma_f32_16x16x32_bf16 v[52:55], v[92:95], v[116:119], v[52:55]
	v_mfma_f32_16x16x32_bf16 v[56:59], v[92:95], v[120:123], v[56:59]
	v_mfma_f32_16x16x32_bf16 v[60:63], v[92:95], v[124:127], v[60:63]
	ds_read_b128 v[80:83], v253 offset:16384
	ds_read_b128 v[112:115], v255 offset:49152
	ds_read_b128 v[116:119], v255 offset:51200
	ds_read_b128 v[120:123], v255 offset:53248
	ds_read_b128 v[124:127], v255 offset:55296
	ds_read_b128 v[84:87], v253 offset:18432
	ds_read_b128 v[88:91], v253 offset:20480
	ds_read_b128 v[92:95], v253 offset:22528
	s_waitcnt lgkmcnt(14)
	v_mfma_f32_16x16x32_bf16 v[0:3], v[64:67], v[96:99], v[0:3]
	s_waitcnt lgkmcnt(13)
	v_mfma_f32_16x16x32_bf16 v[4:7], v[64:67], v[100:103], v[4:7]
	s_waitcnt lgkmcnt(12)
	v_mfma_f32_16x16x32_bf16 v[8:11], v[64:67], v[104:107], v[8:11]
	s_waitcnt lgkmcnt(11)
	v_mfma_f32_16x16x32_bf16 v[12:15], v[64:67], v[108:111], v[12:15]
	s_waitcnt lgkmcnt(10)
	v_mfma_f32_16x16x32_bf16 v[16:19], v[68:71], v[96:99], v[16:19]
	v_mfma_f32_16x16x32_bf16 v[20:23], v[68:71], v[100:103], v[20:23]
	v_mfma_f32_16x16x32_bf16 v[24:27], v[68:71], v[104:107], v[24:27]
	v_mfma_f32_16x16x32_bf16 v[28:31], v[68:71], v[108:111], v[28:31]
	s_waitcnt lgkmcnt(0)
	s_barrier
	v_mfma_f32_16x16x32_bf16 v[32:35], v[72:75], v[96:99], v[32:35]
	v_mfma_f32_16x16x32_bf16 v[36:39], v[72:75], v[100:103], v[36:39]
	v_mfma_f32_16x16x32_bf16 v[40:43], v[72:75], v[104:107], v[40:43]
	v_mfma_f32_16x16x32_bf16 v[44:47], v[72:75], v[108:111], v[44:47]
	v_mfma_f32_16x16x32_bf16 v[48:51], v[76:79], v[96:99], v[48:51]
	v_mfma_f32_16x16x32_bf16 v[52:55], v[76:79], v[100:103], v[52:55]
	v_mfma_f32_16x16x32_bf16 v[56:59], v[76:79], v[104:107], v[56:59]
	v_mfma_f32_16x16x32_bf16 v[60:63], v[76:79], v[108:111], v[60:63]
	v_mfma_f32_16x16x32_bf16 v[0:3], v[80:83], v[112:115], v[0:3]
	v_mfma_f32_16x16x32_bf16 v[4:7], v[80:83], v[116:119], v[4:7]
	v_mfma_f32_16x16x32_bf16 v[8:11], v[80:83], v[120:123], v[8:11]
	v_mfma_f32_16x16x32_bf16 v[12:15], v[80:83], v[124:127], v[12:15]
	v_mfma_f32_16x16x32_bf16 v[16:19], v[84:87], v[112:115], v[16:19]
	v_mfma_f32_16x16x32_bf16 v[20:23], v[84:87], v[116:119], v[20:23]
	v_mfma_f32_16x16x32_bf16 v[24:27], v[84:87], v[120:123], v[24:27]
	v_mfma_f32_16x16x32_bf16 v[28:31], v[84:87], v[124:127], v[28:31]
	v_mfma_f32_16x16x32_bf16 v[32:35], v[88:91], v[112:115], v[32:35]
	v_mfma_f32_16x16x32_bf16 v[36:39], v[88:91], v[116:119], v[36:39]
	v_mfma_f32_16x16x32_bf16 v[40:43], v[88:91], v[120:123], v[40:43]
	v_mfma_f32_16x16x32_bf16 v[44:47], v[88:91], v[124:127], v[44:47]
	v_mfma_f32_16x16x32_bf16 v[48:51], v[92:95], v[112:115], v[48:51]
	v_mfma_f32_16x16x32_bf16 v[52:55], v[92:95], v[116:119], v[52:55]
	v_mfma_f32_16x16x32_bf16 v[56:59], v[92:95], v[120:123], v[56:59]
	v_mfma_f32_16x16x32_bf16 v[60:63], v[92:95], v[124:127], v[60:63]
	s_nop 7
	s_nop 1
	s_mov_b64 s[18:19], s[20:21]
	v_fma_f32 v129, v201, v0, v129
	v_fma_f32 v130, v202, v4, v130
	v_fma_f32 v131, v203, v8, v131
	v_fma_f32 v132, v204, v12, v132
	global_store_dword v246, v129, s[18:19] offset:0 sc1
	global_store_dword v246, v130, s[18:19] offset:64 sc1
	global_store_dword v246, v131, s[18:19] offset:128 sc1
	global_store_dword v246, v132, s[18:19] offset:192 sc1
	s_add_u32 s18, s18, 0x1000
	s_addc_u32 s19, s19, 0
	v_fma_f32 v133, v201, v1, v133
	v_fma_f32 v134, v202, v5, v134
	v_fma_f32 v135, v203, v9, v135
	v_fma_f32 v136, v204, v13, v136
	global_store_dword v246, v133, s[18:19] offset:0 sc1
	global_store_dword v246, v134, s[18:19] offset:64 sc1
	global_store_dword v246, v135, s[18:19] offset:128 sc1
	global_store_dword v246, v136, s[18:19] offset:192 sc1
	s_add_u32 s18, s18, 0x1000
	s_addc_u32 s19, s19, 0
	v_fma_f32 v137, v201, v2, v137
	v_fma_f32 v138, v202, v6, v138
	v_fma_f32 v139, v203, v10, v139
	v_fma_f32 v140, v204, v14, v140
	global_store_dword v246, v137, s[18:19] offset:0 sc1
	global_store_dword v246, v138, s[18:19] offset:64 sc1
	global_store_dword v246, v139, s[18:19] offset:128 sc1
	global_store_dword v246, v140, s[18:19] offset:192 sc1
	s_add_u32 s18, s18, 0x1000
	s_addc_u32 s19, s19, 0
	v_fma_f32 v141, v201, v3, v141
	v_fma_f32 v142, v202, v7, v142
	v_fma_f32 v143, v203, v11, v143
	v_fma_f32 v144, v204, v15, v144
	global_store_dword v246, v141, s[18:19] offset:0 sc1
	global_store_dword v246, v142, s[18:19] offset:64 sc1
	global_store_dword v246, v143, s[18:19] offset:128 sc1
	global_store_dword v246, v144, s[18:19] offset:192 sc1
	s_add_u32 s18, s18, 0xd000
	s_addc_u32 s19, s19, 0
	v_fma_f32 v145, v201, v16, v145
	v_fma_f32 v146, v202, v20, v146
	v_fma_f32 v147, v203, v24, v147
	v_fma_f32 v148, v204, v28, v148
	global_store_dword v246, v145, s[18:19] offset:0 sc1
	global_store_dword v246, v146, s[18:19] offset:64 sc1
	global_store_dword v246, v147, s[18:19] offset:128 sc1
	global_store_dword v246, v148, s[18:19] offset:192 sc1
	s_add_u32 s18, s18, 0x1000
	s_addc_u32 s19, s19, 0
	v_fma_f32 v149, v201, v17, v149
	v_fma_f32 v150, v202, v21, v150
	v_fma_f32 v151, v203, v25, v151
	v_fma_f32 v152, v204, v29, v152
	global_store_dword v246, v149, s[18:19] offset:0 sc1
	global_store_dword v246, v150, s[18:19] offset:64 sc1
	global_store_dword v246, v151, s[18:19] offset:128 sc1
	global_store_dword v246, v152, s[18:19] offset:192 sc1
	s_add_u32 s18, s18, 0x1000
	s_addc_u32 s19, s19, 0
	v_fma_f32 v153, v201, v18, v153
	v_fma_f32 v154, v202, v22, v154
	v_fma_f32 v155, v203, v26, v155
	v_fma_f32 v156, v204, v30, v156
	global_store_dword v246, v153, s[18:19] offset:0 sc1
	global_store_dword v246, v154, s[18:19] offset:64 sc1
	global_store_dword v246, v155, s[18:19] offset:128 sc1
	global_store_dword v246, v156, s[18:19] offset:192 sc1
	s_add_u32 s18, s18, 0x1000
	s_addc_u32 s19, s19, 0
	v_fma_f32 v157, v201, v19, v157
	v_fma_f32 v158, v202, v23, v158
	v_fma_f32 v159, v203, v27, v159
	v_fma_f32 v160, v204, v31, v160
	global_store_dword v246, v157, s[18:19] offset:0 sc1
	global_store_dword v246, v158, s[18:19] offset:64 sc1
	global_store_dword v246, v159, s[18:19] offset:128 sc1
	global_store_dword v246, v160, s[18:19] offset:192 sc1
	s_add_u32 s18, s18, 0xd000
	s_addc_u32 s19, s19, 0
	v_fma_f32 v161, v201, v32, v161
	v_fma_f32 v170, v202, v36, v170
	v_fma_f32 v171, v203, v40, v171
	v_fma_f32 v172, v204, v44, v172
	global_store_dword v246, v161, s[18:19] offset:0 sc1
	global_store_dword v246, v170, s[18:19] offset:64 sc1
	global_store_dword v246, v171, s[18:19] offset:128 sc1
	global_store_dword v246, v172, s[18:19] offset:192 sc1
	s_add_u32 s18, s18, 0x1000
	s_addc_u32 s19, s19, 0
	v_fma_f32 v173, v201, v33, v173
	v_fma_f32 v174, v202, v37, v174
	v_fma_f32 v175, v203, v41, v175
	v_fma_f32 v176, v204, v45, v176
	global_store_dword v246, v173, s[18:19] offset:0 sc1
	global_store_dword v246, v174, s[18:19] offset:64 sc1
	global_store_dword v246, v175, s[18:19] offset:128 sc1
	global_store_dword v246, v176, s[18:19] offset:192 sc1
	s_add_u32 s18, s18, 0x1000
	s_addc_u32 s19, s19, 0
	v_fma_f32 v177, v201, v34, v177
	v_fma_f32 v178, v202, v38, v178
	v_fma_f32 v179, v203, v42, v179
	v_fma_f32 v180, v204, v46, v180
	global_store_dword v246, v177, s[18:19] offset:0 sc1
	global_store_dword v246, v178, s[18:19] offset:64 sc1
	global_store_dword v246, v179, s[18:19] offset:128 sc1
	global_store_dword v246, v180, s[18:19] offset:192 sc1
	s_add_u32 s18, s18, 0x1000
	s_addc_u32 s19, s19, 0
	v_fma_f32 v181, v201, v35, v181
	v_fma_f32 v182, v202, v39, v182
	v_fma_f32 v183, v203, v43, v183
	v_fma_f32 v184, v204, v47, v184
	global_store_dword v246, v181, s[18:19] offset:0 sc1
	global_store_dword v246, v182, s[18:19] offset:64 sc1
	global_store_dword v246, v183, s[18:19] offset:128 sc1
	global_store_dword v246, v184, s[18:19] offset:192 sc1
	s_add_u32 s18, s18, 0xd000
	s_addc_u32 s19, s19, 0
	v_fma_f32 v185, v201, v48, v185
	v_fma_f32 v186, v202, v52, v186
	v_fma_f32 v187, v203, v56, v187
	v_fma_f32 v188, v204, v60, v188
	global_store_dword v246, v185, s[18:19] offset:0 sc1
	global_store_dword v246, v186, s[18:19] offset:64 sc1
	global_store_dword v246, v187, s[18:19] offset:128 sc1
	global_store_dword v246, v188, s[18:19] offset:192 sc1
	s_add_u32 s18, s18, 0x1000
	s_addc_u32 s19, s19, 0
	v_fma_f32 v189, v201, v49, v189
	v_fma_f32 v190, v202, v53, v190
	v_fma_f32 v191, v203, v57, v191
	v_fma_f32 v192, v204, v61, v192
	global_store_dword v246, v189, s[18:19] offset:0 sc1
	global_store_dword v246, v190, s[18:19] offset:64 sc1
	global_store_dword v246, v191, s[18:19] offset:128 sc1
	global_store_dword v246, v192, s[18:19] offset:192 sc1
	s_add_u32 s18, s18, 0x1000
	s_addc_u32 s19, s19, 0
	v_fma_f32 v193, v201, v50, v193
	v_fma_f32 v194, v202, v54, v194
	v_fma_f32 v195, v203, v58, v195
	v_fma_f32 v196, v204, v62, v196
	global_store_dword v246, v193, s[18:19] offset:0 sc1
	global_store_dword v246, v194, s[18:19] offset:64 sc1
	global_store_dword v246, v195, s[18:19] offset:128 sc1
	global_store_dword v246, v196, s[18:19] offset:192 sc1
	s_add_u32 s18, s18, 0x1000
	s_addc_u32 s19, s19, 0
	v_fma_f32 v197, v201, v51, v197
	v_fma_f32 v198, v202, v55, v198
	v_fma_f32 v199, v203, v59, v199
	v_fma_f32 v200, v204, v63, v200
	global_store_dword v246, v197, s[18:19] offset:0 sc1
	global_store_dword v246, v198, s[18:19] offset:64 sc1
	global_store_dword v246, v199, s[18:19] offset:128 sc1
	global_store_dword v246, v200, s[18:19] offset:192 sc1
	s_add_u32 s15, s15, s16
	s_branch .Lr6_tile

.LBB0_896:
	v_lshl_add_u64 v[16:17], s[12:13], 0, v[48:49]
	v_lshl_add_u64 v[4:5], s[12:13], 0, v[46:47]
	v_add_co_u32_e32 v8, vcc, 0x6b7a000, v16
	v_add_co_u32_e64 v60, s[4:5], s28, v4
	s_nop 0
	v_addc_co_u32_e32 v9, vcc, 0, v17, vcc
	v_addc_co_u32_e64 v61, s[4:5], 0, v5, s[4:5]
	v_add_u32_e32 v6, 0xfffff000, v40
	v_add_co_u32_e64 v62, s[4:5], s29, v4
	v_add_co_u32_e32 v12, vcc, s15, v16
	v_lshrrev_b32_e32 v6, 10, v6
	v_addc_co_u32_e64 v63, s[4:5], 0, v5, s[4:5]
	v_addc_co_u32_e32 v13, vcc, 0, v17, vcc
	v_add_u32_e32 v10, 1, v6
	v_cmp_lt_i32_e64 s[4:5], s2, v40
	v_add_co_u32_e32 v18, vcc, s25, v16
	global_load_dwordx4 v[0:3], v[44:45], off
	global_load_dwordx4 v[74:77], v[8:9], off offset:256 sc1
	global_load_dwordx4 v[36:39], v[8:9], off offset:1280 sc1
	global_load_dwordx4 v[20:23], v[8:9], off offset:2304 sc1
	global_load_dwordx4 v[4:7], v[8:9], off offset:3328 sc1
	v_cndmask_b32_e64 v14, 0, v10, s[4:5]
	v_addc_co_u32_e32 v19, vcc, 0, v17, vcc
	global_load_dwordx4 v[78:81], v[12:13], off offset:256 sc1
	global_load_dwordx4 v[82:85], v[12:13], off offset:1280 sc1
	global_load_dwordx4 v[24:27], v[12:13], off offset:2304 sc1
	global_load_dwordx4 v[8:11], v[12:13], off offset:3328 sc1
	v_mad_u64_u32 v[32:33], s[4:5], v14, s3, v[50:51]
	v_add_co_u32_e32 v102, vcc, s26, v16
	global_load_dwordx4 v[86:89], v[18:19], off offset:256 sc1
	global_load_dwordx4 v[90:93], v[18:19], off offset:1280 sc1
	global_load_dwordx4 v[28:31], v[18:19], off offset:2304 sc1
	global_load_dwordx4 v[12:15], v[18:19], off offset:3328 sc1
	v_lshl_add_u64 v[66:67], v[32:33], 0, s[22:23]
	v_lshl_add_u64 v[64:65], v[32:33], 0, v[42:43]
	v_addc_co_u32_e32 v103, vcc, 0, v17, vcc
	global_load_dwordx4 v[94:97], v[102:103], off offset:256 sc1
	global_load_dwordx4 v[98:101], v[102:103], off offset:1280 sc1
	global_load_dwordx4 v[32:35], v[102:103], off offset:2304 sc1
	global_load_dwordx4 v[16:19], v[102:103], off offset:3328 sc1
	v_lshl_add_u64 v[110:111], v[66:67], 0, v[42:43]
	global_load_dwordx4 v[102:105], v[64:65], off
	global_load_dwordx4 v[106:109], v[110:111], off
	v_lshl_add_u64 v[112:113], v[66:67], 0, v[52:53]
	v_add_u32_e32 v40, s14, v40
	v_lshl_add_u64 v[46:47], v[46:47], 0, s[16:17]
	v_lshl_add_u64 v[48:49], v[48:49], 0, s[18:19]
	s_waitcnt vmcnt(17)
	v_mov_b32_e32 v118, v75
	s_waitcnt vmcnt(16)
	v_mov_b32_e32 v119, v37
	v_mov_b32_e32 v116, v74
	v_mov_b32_e32 v117, v36
	s_waitcnt vmcnt(15)
	v_mov_b32_e32 v126, v21
	s_waitcnt vmcnt(14)
	v_mov_b32_e32 v127, v5
	v_pk_mul_f32 v[118:119], v[118:119], v[118:119]
	s_waitcnt vmcnt(13)
	v_mov_b32_e32 v136, v79
	s_waitcnt vmcnt(12)
	v_mov_b32_e32 v137, v83
	v_mov_b32_e32 v110, v76
	v_mov_b32_e32 v111, v38
	v_mov_b32_e32 v124, v20
	v_mov_b32_e32 v125, v4
	v_mov_b32_e32 v134, v78
	v_mov_b32_e32 v135, v82
	v_pk_mul_f32 v[126:127], v[126:127], v[126:127]
	s_waitcnt vmcnt(11)
	v_mov_b32_e32 v144, v25
	s_waitcnt vmcnt(10)
	v_mov_b32_e32 v145, v9
	v_pk_fma_f32 v[116:117], v[116:117], v[116:117], v[118:119]
	v_pk_mul_f32 v[118:119], v[136:137], v[136:137]
	s_waitcnt vmcnt(9)
	v_mov_b32_e32 v150, v87
	s_waitcnt vmcnt(8)
	v_mov_b32_e32 v151, v91
	v_mov_b32_e32 v114, v77
	v_mov_b32_e32 v115, v39
	v_mov_b32_e32 v120, v22
	v_mov_b32_e32 v121, v6
	v_mov_b32_e32 v130, v80
	v_mov_b32_e32 v131, v84
	v_mov_b32_e32 v142, v24
	v_mov_b32_e32 v143, v8
	v_mov_b32_e32 v148, v86
	v_mov_b32_e32 v149, v90
	v_pk_fma_f32 v[124:125], v[124:125], v[124:125], v[126:127]
	v_pk_mul_f32 v[126:127], v[144:145], v[144:145]
	s_waitcnt vmcnt(7)
	v_mov_b32_e32 v156, v29
	s_waitcnt vmcnt(6)
	v_mov_b32_e32 v157, v13
	v_pk_fma_f32 v[110:111], v[110:111], v[110:111], v[116:117]
	v_pk_fma_f32 v[116:117], v[134:135], v[134:135], v[118:119]
	v_pk_mul_f32 v[118:119], v[150:151], v[150:151]
	s_waitcnt vmcnt(5)
	v_mov_b32_e32 v160, v95
	s_waitcnt vmcnt(4)
	v_mov_b32_e32 v161, v99
	v_mov_b32_e32 v122, v23
	v_mov_b32_e32 v123, v7
	v_mov_b32_e32 v132, v81
	v_mov_b32_e32 v133, v85
	v_mov_b32_e32 v138, v26
	v_mov_b32_e32 v139, v10
	v_mov_b32_e32 v154, v28
	v_mov_b32_e32 v155, v12
	v_mov_b32_e32 v158, v94
	v_mov_b32_e32 v159, v98
	v_pk_fma_f32 v[120:121], v[120:121], v[120:121], v[124:125]
	v_pk_fma_f32 v[124:125], v[142:143], v[142:143], v[126:127]
	v_pk_mul_f32 v[126:127], v[156:157], v[156:157]
	s_waitcnt vmcnt(3)
	v_mov_b32_e32 v172, v33
	s_waitcnt vmcnt(2)
	v_mov_b32_e32 v173, v17
	s_waitcnt vmcnt(0)
	v_pk_add_f32 v[106:107], v[106:107], 1.0 op_sel_hi:[1,0]
	v_pk_fma_f32 v[110:111], v[114:115], v[114:115], v[110:111]
	v_pk_fma_f32 v[114:115], v[130:131], v[130:131], v[116:117]
	v_pk_fma_f32 v[116:117], v[148:149], v[148:149], v[118:119]
	v_pk_mul_f32 v[118:119], v[160:161], v[160:161]
	v_mov_b32_e32 v140, v27
	v_mov_b32_e32 v141, v11
	v_mov_b32_e32 v136, v88
	v_mov_b32_e32 v137, v92
	v_mov_b32_e32 v134, v96
	v_mov_b32_e32 v135, v100
	v_mov_b32_e32 v170, v32
	v_mov_b32_e32 v171, v16
	v_pk_add_f32 v[108:109], v[108:109], 1.0 op_sel_hi:[1,0]
	v_pk_fma_f32 v[120:121], v[122:123], v[122:123], v[120:121]
	v_pk_fma_f32 v[122:123], v[138:139], v[138:139], v[124:125]
	v_pk_fma_f32 v[124:125], v[154:155], v[154:155], v[126:127]
	v_pk_mul_f32 v[126:127], v[172:173], v[172:173]
	v_pk_mul_f32 v[0:1], v[0:1], v[106:107]
	v_pk_fma_f32 v[106:107], v[132:133], v[132:133], v[114:115]
	v_pk_fma_f32 v[114:115], v[158:159], v[158:159], v[118:119]
	v_mov_b32_e32 v146, v89
	v_mov_b32_e32 v147, v93
	v_mov_b32_e32 v144, v30
	v_mov_b32_e32 v145, v14
	v_mov_b32_e32 v150, v97
	v_mov_b32_e32 v151, v101
	v_mov_b32_e32 v142, v34
	v_mov_b32_e32 v143, v18
	v_pk_mul_f32 v[2:3], v[2:3], v[108:109]
	v_pk_fma_f32 v[108:109], v[136:137], v[136:137], v[116:117]
	v_pk_fma_f32 v[116:117], v[140:141], v[140:141], v[122:123]
	v_mov_b32_e32 v119, v110
	v_pk_fma_f32 v[126:127], v[170:171], v[170:171], v[126:127]
	v_pk_fma_f32 v[114:115], v[134:135], v[134:135], v[114:115]
	v_mov_b32_e32 v118, v106
	v_mov_b32_e32 v110, v107
	v_mov_b32_e32 v152, v31
	v_mov_b32_e32 v153, v15
	v_mov_b32_e32 v156, v35
	v_mov_b32_e32 v157, v19
	v_mov_b32_e32 v123, v120
	v_pk_fma_f32 v[124:125], v[144:145], v[144:145], v[124:125]
	v_pk_fma_f32 v[108:109], v[146:147], v[146:147], v[108:109]
	v_mov_b32_e32 v122, v116
	v_mov_b32_e32 v120, v117
	v_pk_fma_f32 v[116:117], v[142:143], v[142:143], v[126:127]
	v_pk_fma_f32 v[114:115], v[150:151], v[150:151], v[114:115]
	v_pk_add_f32 v[110:111], v[118:119], v[110:111]
	v_pk_fma_f32 v[106:107], v[152:153], v[152:153], v[124:125]
	v_pk_fma_f32 v[116:117], v[156:157], v[156:157], v[116:117]
	v_mov_b32_e32 v119, v108
	v_pk_add_f32 v[110:111], v[110:111], v[122:123]
	v_mov_b32_e32 v118, v114
	v_mov_b32_e32 v108, v115
	v_mov_b32_e32 v125, v106
	v_mov_b32_e32 v124, v116
	v_pk_add_f32 v[110:111], v[110:111], v[120:121]
	v_pk_add_f32 v[108:109], v[118:119], v[108:109]
	v_mov_b32_e32 v106, v117
	ds_bpermute_b32 v115, v68, v111
	ds_bpermute_b32 v114, v68, v110
	v_pk_add_f32 v[108:109], v[108:109], v[124:125]
	s_waitcnt lgkmcnt(0)
	v_pk_add_f32 v[110:111], v[110:111], v[114:115]
	v_pk_add_f32 v[106:107], v[108:109], v[106:107]
	ds_bpermute_b32 v109, v68, v107
	ds_bpermute_b32 v108, v68, v106
	ds_bpermute_b32 v115, v69, v111
	ds_bpermute_b32 v114, v69, v110
	s_waitcnt lgkmcnt(2)
	v_pk_add_f32 v[106:107], v[106:107], v[108:109]
	ds_bpermute_b32 v109, v69, v107
	ds_bpermute_b32 v108, v69, v106
	s_waitcnt lgkmcnt(2)
	v_pk_add_f32 v[110:111], v[110:111], v[114:115]
	ds_bpermute_b32 v115, v70, v111
	ds_bpermute_b32 v114, v70, v110
	s_waitcnt lgkmcnt(2)
	v_pk_add_f32 v[106:107], v[106:107], v[108:109]
	ds_bpermute_b32 v109, v70, v107
	ds_bpermute_b32 v108, v70, v106
	s_waitcnt lgkmcnt(2)
	v_pk_add_f32 v[110:111], v[110:111], v[114:115]
	ds_bpermute_b32 v115, v71, v111
	ds_bpermute_b32 v114, v71, v110
	s_waitcnt lgkmcnt(2)
	v_pk_add_f32 v[106:107], v[106:107], v[108:109]
	ds_bpermute_b32 v109, v71, v107
	ds_bpermute_b32 v108, v71, v106
	s_waitcnt lgkmcnt(2)
	v_pk_add_f32 v[110:111], v[110:111], v[114:115]
	ds_bpermute_b32 v115, v72, v111
	ds_bpermute_b32 v114, v72, v110
	s_waitcnt lgkmcnt(2)
	v_pk_add_f32 v[106:107], v[106:107], v[108:109]
	ds_bpermute_b32 v109, v72, v107
	ds_bpermute_b32 v108, v72, v106
	s_waitcnt lgkmcnt(2)
	v_pk_add_f32 v[110:111], v[110:111], v[114:115]
	ds_bpermute_b32 v115, v73, v111
	ds_bpermute_b32 v114, v73, v110
	s_waitcnt lgkmcnt(2)
	v_pk_add_f32 v[106:107], v[106:107], v[108:109]
	ds_bpermute_b32 v109, v73, v107
	ds_bpermute_b32 v108, v73, v106
	s_waitcnt lgkmcnt(2)
	v_pk_add_f32 v[110:111], v[110:111], v[114:115]
	s_waitcnt lgkmcnt(0)
	v_pk_add_f32 v[106:107], v[106:107], v[108:109]
	v_pk_fma_f32 v[110:111], v[110:111], s[24:25], v[58:59] op_sel_hi:[1,0,0]
	v_pk_fma_f32 v[106:107], v[106:107], s[24:25], v[58:59] op_sel_hi:[1,0,0]
	v_mul_f32_e32 v41, 0x4b800000, v111
	v_mul_f32_e32 v114, 0x4b800000, v110
	v_cmp_gt_f32_e32 vcc, s27, v110
	v_cmp_gt_f32_e64 s[4:5], s27, v111
	v_mul_f32_e32 v109, 0x4b800000, v107
	v_cndmask_b32_e32 v108, v110, v114, vcc
	v_cndmask_b32_e64 v41, v111, v41, s[4:5]
	v_rsq_f32_e32 v41, v41
	v_rsq_f32_e32 v108, v108
	v_mul_f32_e32 v110, 0x4b800000, v106
	v_cmp_gt_f32_e64 s[6:7], s27, v106
	v_cmp_gt_f32_e64 s[8:9], s27, v107
	s_nop 0
	v_cndmask_b32_e64 v106, v106, v110, s[6:7]
	v_cndmask_b32_e64 v107, v107, v109, s[8:9]
	v_rsq_f32_e32 v107, v107
	v_rsq_f32_e32 v109, v106
	v_mul_f32_e32 v106, 0x45800000, v41
	v_mul_f32_e32 v110, 0x45800000, v108
	v_cndmask_b32_e64 v106, v41, v106, s[4:5]
	v_cndmask_b32_e32 v108, v108, v110, vcc
	v_pk_mul_f32 v[74:75], v[74:75], v[106:107] op_sel_hi:[1,0]
	v_pk_mul_f32 v[76:77], v[76:77], v[106:107] op_sel_hi:[1,0]
	v_pk_mul_f32 v[78:79], v[78:79], v[108:109] op_sel_hi:[1,0]
	v_pk_mul_f32 v[80:81], v[80:81], v[108:109] op_sel_hi:[1,0]
	v_mul_f32_e32 v41, 0x45800000, v107
	v_mul_f32_e32 v111, 0x45800000, v109
	v_pk_fma_f32 v[74:75], v[74:75], v[0:1], v[102:103]
	v_pk_fma_f32 v[76:77], v[76:77], v[2:3], v[104:105]
	v_pk_fma_f32 v[78:79], v[78:79], v[0:1], v[102:103]
	v_pk_fma_f32 v[80:81], v[80:81], v[2:3], v[104:105]
	v_cndmask_b32_e64 v110, v107, v41, s[8:9]
	v_cndmask_b32_e64 v114, v109, v111, s[6:7]
	v_cvt_pk_bf16_f32 v74, v74, v75
	v_cvt_pk_bf16_f32 v75, v76, v77
	v_cvt_pk_bf16_f32 v76, v78, v79
	v_cvt_pk_bf16_f32 v77, v80, v81
	v_pk_mul_f32 v[78:79], v[86:87], v[110:111] op_sel_hi:[1,0]
	v_pk_mul_f32 v[80:81], v[88:89], v[110:111] op_sel_hi:[1,0]
	v_pk_mul_f32 v[86:87], v[94:95], v[114:115] op_sel_hi:[1,0]
	v_pk_mul_f32 v[88:89], v[96:97], v[114:115] op_sel_hi:[1,0]
	v_pk_fma_f32 v[78:79], v[78:79], v[0:1], v[102:103]
	v_pk_fma_f32 v[80:81], v[80:81], v[2:3], v[104:105]
	v_pk_fma_f32 v[0:1], v[86:87], v[0:1], v[102:103]
	v_pk_fma_f32 v[2:3], v[88:89], v[2:3], v[104:105]
	global_store_dwordx2 v[60:61], v[74:75], off offset:256
	global_store_dwordx2 v[60:61], v[76:77], off offset:2304
	v_cvt_pk_bf16_f32 v74, v78, v79
	v_cvt_pk_bf16_f32 v75, v80, v81
	v_cvt_pk_bf16_f32 v0, v0, v1
	v_cvt_pk_bf16_f32 v1, v2, v3
	global_store_dwordx2 v[62:63], v[74:75], off offset:256
	global_store_dwordx2 v[62:63], v[0:1], off offset:2304
	global_load_dwordx4 v[0:3], v[112:113], off
	s_nop 0
	global_load_dwordx4 v[74:77], v[64:65], off offset:1024
	global_load_dwordx4 v[78:81], v[44:45], off offset:1024
	v_pk_mul_f32 v[36:37], v[36:37], v[106:107] op_sel_hi:[1,0]
	v_pk_mul_f32 v[38:39], v[38:39], v[106:107] op_sel_hi:[1,0]
	v_pk_mul_f32 v[82:83], v[82:83], v[108:109] op_sel_hi:[1,0]
	v_pk_mul_f32 v[84:85], v[84:85], v[108:109] op_sel_hi:[1,0]
	v_pk_mul_f32 v[88:89], v[90:91], v[110:111] op_sel_hi:[1,0]
	v_pk_mul_f32 v[90:91], v[92:93], v[110:111] op_sel_hi:[1,0]
	v_pk_mul_f32 v[92:93], v[98:99], v[114:115] op_sel_hi:[1,0]
	v_pk_mul_f32 v[94:95], v[100:101], v[114:115] op_sel_hi:[1,0]
	v_lshl_add_u64 v[86:87], v[66:67], 0, v[54:55]
	v_pk_mul_f32 v[20:21], v[20:21], v[106:107] op_sel_hi:[1,0]
	v_pk_mul_f32 v[22:23], v[22:23], v[106:107] op_sel_hi:[1,0]
	v_pk_mul_f32 v[24:25], v[24:25], v[108:109] op_sel_hi:[1,0]
	v_pk_mul_f32 v[26:27], v[26:27], v[108:109] op_sel_hi:[1,0]
	v_pk_mul_f32 v[28:29], v[28:29], v[110:111] op_sel_hi:[1,0]
	v_pk_mul_f32 v[30:31], v[30:31], v[110:111] op_sel_hi:[1,0]
	v_pk_mul_f32 v[32:33], v[32:33], v[114:115] op_sel_hi:[1,0]
	v_pk_mul_f32 v[34:35], v[34:35], v[114:115] op_sel_hi:[1,0]
	v_lshl_add_u64 v[66:67], v[66:67], 0, v[56:57]
	v_pk_mul_f32 v[4:5], v[4:5], v[106:107] op_sel_hi:[1,0]
	v_pk_mul_f32 v[6:7], v[6:7], v[106:107] op_sel_hi:[1,0]
	v_cmp_lt_i32_e32 vcc, s30, v40
	v_pk_mul_f32 v[8:9], v[8:9], v[108:109] op_sel_hi:[1,0]
	v_pk_mul_f32 v[10:11], v[10:11], v[108:109] op_sel_hi:[1,0]
	v_pk_mul_f32 v[12:13], v[12:13], v[110:111] op_sel_hi:[1,0]
	v_pk_mul_f32 v[14:15], v[14:15], v[110:111] op_sel_hi:[1,0]
	v_pk_mul_f32 v[16:17], v[16:17], v[114:115] op_sel_hi:[1,0]
	v_pk_mul_f32 v[18:19], v[18:19], v[114:115] op_sel_hi:[1,0]
	s_or_b64 s[20:21], vcc, s[20:21]
	s_waitcnt vmcnt(2)
	v_pk_add_f32 v[0:1], v[0:1], 1.0 op_sel_hi:[1,0]
	v_pk_add_f32 v[2:3], v[2:3], 1.0 op_sel_hi:[1,0]
	s_waitcnt vmcnt(0)
	v_pk_mul_f32 v[0:1], v[78:79], v[0:1]
	v_pk_mul_f32 v[2:3], v[80:81], v[2:3]
	v_pk_fma_f32 v[36:37], v[36:37], v[0:1], v[74:75]
	v_pk_fma_f32 v[38:39], v[38:39], v[2:3], v[76:77]
	v_pk_fma_f32 v[78:79], v[82:83], v[0:1], v[74:75]
	v_pk_fma_f32 v[80:81], v[84:85], v[2:3], v[76:77]
	v_pk_fma_f32 v[82:83], v[88:89], v[0:1], v[74:75]
	v_pk_fma_f32 v[84:85], v[90:91], v[2:3], v[76:77]
	v_pk_fma_f32 v[0:1], v[92:93], v[0:1], v[74:75]
	v_pk_fma_f32 v[2:3], v[94:95], v[2:3], v[76:77]
	v_cvt_pk_bf16_f32 v36, v36, v37
	v_cvt_pk_bf16_f32 v37, v38, v39
	v_cvt_pk_bf16_f32 v38, v78, v79
	v_cvt_pk_bf16_f32 v39, v80, v81
	v_cvt_pk_bf16_f32 v74, v82, v83
	v_cvt_pk_bf16_f32 v75, v84, v85
	v_cvt_pk_bf16_f32 v0, v0, v1
	v_cvt_pk_bf16_f32 v1, v2, v3
	global_store_dwordx2 v[60:61], v[36:37], off offset:768
	global_store_dwordx2 v[60:61], v[38:39], off offset:2816
	global_store_dwordx2 v[62:63], v[74:75], off offset:768
	global_store_dwordx2 v[62:63], v[0:1], off offset:2816
	global_load_dwordx4 v[0:3], v[86:87], off
	s_nop 0
	global_load_dwordx4 v[36:39], v[64:65], off offset:2048
	global_load_dwordx4 v[74:77], v[44:45], off offset:2048
	s_waitcnt vmcnt(2)
	v_pk_add_f32 v[0:1], v[0:1], 1.0 op_sel_hi:[1,0]
	v_pk_add_f32 v[2:3], v[2:3], 1.0 op_sel_hi:[1,0]
	s_waitcnt vmcnt(0)
	v_pk_mul_f32 v[0:1], v[74:75], v[0:1]
	v_pk_mul_f32 v[2:3], v[76:77], v[2:3]
	v_pk_fma_f32 v[20:21], v[20:21], v[0:1], v[36:37]
	v_pk_fma_f32 v[22:23], v[22:23], v[2:3], v[38:39]
	v_pk_fma_f32 v[24:25], v[24:25], v[0:1], v[36:37]
	v_pk_fma_f32 v[26:27], v[26:27], v[2:3], v[38:39]
	v_pk_fma_f32 v[28:29], v[28:29], v[0:1], v[36:37]
	v_pk_fma_f32 v[30:31], v[30:31], v[2:3], v[38:39]
	v_pk_fma_f32 v[0:1], v[32:33], v[0:1], v[36:37]
	v_pk_fma_f32 v[2:3], v[34:35], v[2:3], v[38:39]
	v_cvt_pk_bf16_f32 v20, v20, v21
	v_cvt_pk_bf16_f32 v21, v22, v23
	v_cvt_pk_bf16_f32 v22, v24, v25
	v_cvt_pk_bf16_f32 v23, v26, v27
	v_cvt_pk_bf16_f32 v24, v28, v29
	v_cvt_pk_bf16_f32 v25, v30, v31
	v_cvt_pk_bf16_f32 v0, v0, v1
	v_cvt_pk_bf16_f32 v1, v2, v3
	global_store_dwordx2 v[60:61], v[20:21], off offset:1280
	global_store_dwordx2 v[60:61], v[22:23], off offset:3328
	global_store_dwordx2 v[62:63], v[24:25], off offset:1280
	global_store_dwordx2 v[62:63], v[0:1], off offset:3328
	global_load_dwordx4 v[0:3], v[66:67], off
	s_nop 0
	global_load_dwordx4 v[20:23], v[64:65], off offset:3072
	global_load_dwordx4 v[24:27], v[44:45], off offset:3072
	s_waitcnt vmcnt(2)
	v_pk_add_f32 v[0:1], v[0:1], 1.0 op_sel_hi:[1,0]
	v_pk_add_f32 v[2:3], v[2:3], 1.0 op_sel_hi:[1,0]
	s_waitcnt vmcnt(0)
	v_pk_mul_f32 v[0:1], v[24:25], v[0:1]
	v_pk_mul_f32 v[2:3], v[26:27], v[2:3]
	v_pk_fma_f32 v[4:5], v[4:5], v[0:1], v[20:21]
	v_pk_fma_f32 v[6:7], v[6:7], v[2:3], v[22:23]
	v_pk_fma_f32 v[8:9], v[8:9], v[0:1], v[20:21]
	v_pk_fma_f32 v[10:11], v[10:11], v[2:3], v[22:23]
	v_pk_fma_f32 v[12:13], v[12:13], v[0:1], v[20:21]
	v_pk_fma_f32 v[14:15], v[14:15], v[2:3], v[22:23]
	v_pk_fma_f32 v[0:1], v[16:17], v[0:1], v[20:21]
	v_pk_fma_f32 v[2:3], v[18:19], v[2:3], v[22:23]
	v_cvt_pk_bf16_f32 v4, v4, v5
	v_cvt_pk_bf16_f32 v5, v6, v7
	v_cvt_pk_bf16_f32 v6, v8, v9
	v_cvt_pk_bf16_f32 v7, v10, v11
	v_cvt_pk_bf16_f32 v8, v12, v13
	v_cvt_pk_bf16_f32 v9, v14, v15
	v_cvt_pk_bf16_f32 v0, v0, v1
	v_cvt_pk_bf16_f32 v1, v2, v3
	global_store_dwordx2 v[60:61], v[4:5], off offset:1792
	global_store_dwordx2 v[60:61], v[6:7], off offset:3840
	global_store_dwordx2 v[62:63], v[8:9], off offset:1792
	global_store_dwordx2 v[62:63], v[0:1], off offset:3840
	s_andn2_b64 exec, exec, s[20:21]
	s_cbranch_execnz .LBB0_896

.LBB0_1078:
	v_lshl_add_u64 v[16:17], s[12:13], 0, v[54:55]
	v_lshl_add_u64 v[4:5], s[12:13], 0, v[52:53]
	v_add_co_u32_e32 v8, vcc, 0x6b7a000, v16
	v_add_co_u32_e64 v66, s[4:5], s28, v4
	s_nop 0
	v_addc_co_u32_e32 v9, vcc, 0, v17, vcc
	v_addc_co_u32_e64 v67, s[4:5], 0, v5, s[4:5]
	v_add_u32_e32 v6, 0xfffff000, v40
	v_add_co_u32_e64 v68, s[4:5], s29, v4
	v_add_co_u32_e32 v12, vcc, s17, v16
	v_lshrrev_b32_e32 v6, 10, v6
	v_addc_co_u32_e64 v69, s[4:5], 0, v5, s[4:5]
	v_addc_co_u32_e32 v13, vcc, 0, v17, vcc
	v_add_u32_e32 v10, 6, v6
	v_cmp_lt_i32_e64 s[4:5], s2, v40
	v_add_co_u32_e32 v18, vcc, s25, v16
	global_load_dwordx4 v[0:3], v[44:45], off
	global_load_dwordx4 v[80:83], v[8:9], off offset:256 sc1
	global_load_dwordx4 v[36:39], v[8:9], off offset:1280 sc1
	global_load_dwordx4 v[20:23], v[8:9], off offset:2304 sc1
	global_load_dwordx4 v[4:7], v[8:9], off offset:3328 sc1
	v_cndmask_b32_e64 v14, 5, v10, s[4:5]
	v_addc_co_u32_e32 v19, vcc, 0, v17, vcc
	global_load_dwordx4 v[84:87], v[12:13], off offset:256 sc1
	global_load_dwordx4 v[88:91], v[12:13], off offset:1280 sc1
	global_load_dwordx4 v[24:27], v[12:13], off offset:2304 sc1
	global_load_dwordx4 v[8:11], v[12:13], off offset:3328 sc1
	v_mad_u64_u32 v[32:33], s[4:5], v14, s3, v[56:57]
	v_add_co_u32_e32 v108, vcc, s26, v16
	global_load_dwordx4 v[92:95], v[18:19], off offset:256 sc1
	global_load_dwordx4 v[96:99], v[18:19], off offset:1280 sc1
	global_load_dwordx4 v[28:31], v[18:19], off offset:2304 sc1
	global_load_dwordx4 v[12:15], v[18:19], off offset:3328 sc1
	v_lshl_add_u64 v[72:73], v[32:33], 0, s[14:15]
	v_lshl_add_u64 v[70:71], v[32:33], 0, v[42:43]
	v_addc_co_u32_e32 v109, vcc, 0, v17, vcc
	global_load_dwordx4 v[100:103], v[108:109], off offset:256 sc1
	global_load_dwordx4 v[104:107], v[108:109], off offset:1280 sc1
	global_load_dwordx4 v[32:35], v[108:109], off offset:2304 sc1
	global_load_dwordx4 v[16:19], v[108:109], off offset:3328 sc1
	v_lshl_add_u64 v[116:117], v[72:73], 0, v[42:43]
	global_load_dwordx4 v[108:111], v[70:71], off
	global_load_dwordx4 v[112:115], v[116:117], off
	v_lshl_add_u64 v[118:119], v[72:73], 0, v[58:59]
	v_add_u32_e32 v40, s16, v40
	v_lshl_add_u64 v[52:53], v[52:53], 0, s[18:19]
	v_lshl_add_u64 v[54:55], v[54:55], 0, s[20:21]
	s_waitcnt vmcnt(17)
	v_mov_b32_e32 v124, v81
	s_waitcnt vmcnt(16)
	v_mov_b32_e32 v125, v37
	v_mov_b32_e32 v122, v80
	v_mov_b32_e32 v123, v36
	s_waitcnt vmcnt(15)
	v_mov_b32_e32 v134, v21
	s_waitcnt vmcnt(14)
	v_mov_b32_e32 v135, v5
	v_pk_mul_f32 v[124:125], v[124:125], v[124:125]
	s_waitcnt vmcnt(13)
	v_mov_b32_e32 v142, v85
	s_waitcnt vmcnt(12)
	v_mov_b32_e32 v143, v89
	v_mov_b32_e32 v116, v82
	v_mov_b32_e32 v117, v38
	v_mov_b32_e32 v132, v20
	v_mov_b32_e32 v133, v4
	v_mov_b32_e32 v140, v84
	v_mov_b32_e32 v141, v88
	v_pk_mul_f32 v[134:135], v[134:135], v[134:135]
	s_waitcnt vmcnt(11)
	v_mov_b32_e32 v150, v25
	s_waitcnt vmcnt(10)
	v_mov_b32_e32 v151, v9
	v_pk_fma_f32 v[122:123], v[122:123], v[122:123], v[124:125]
	v_pk_mul_f32 v[124:125], v[142:143], v[142:143]
	s_waitcnt vmcnt(9)
	v_mov_b32_e32 v156, v93
	s_waitcnt vmcnt(8)
	v_mov_b32_e32 v157, v97
	v_mov_b32_e32 v120, v83
	v_mov_b32_e32 v121, v39
	v_mov_b32_e32 v126, v22
	v_mov_b32_e32 v127, v6
	v_mov_b32_e32 v136, v86
	v_mov_b32_e32 v137, v90
	v_mov_b32_e32 v148, v24
	v_mov_b32_e32 v149, v8
	v_mov_b32_e32 v154, v92
	v_mov_b32_e32 v155, v96
	v_pk_fma_f32 v[132:133], v[132:133], v[132:133], v[134:135]
	v_pk_mul_f32 v[134:135], v[150:151], v[150:151]
	s_waitcnt vmcnt(7)
	v_mov_b32_e32 v170, v29
	s_waitcnt vmcnt(6)
	v_mov_b32_e32 v171, v13
	v_pk_fma_f32 v[116:117], v[116:117], v[116:117], v[122:123]
	v_pk_fma_f32 v[122:123], v[140:141], v[140:141], v[124:125]
	v_pk_mul_f32 v[124:125], v[156:157], v[156:157]
	s_waitcnt vmcnt(5)
	v_mov_b32_e32 v174, v101
	s_waitcnt vmcnt(4)
	v_mov_b32_e32 v175, v105
	v_mov_b32_e32 v130, v23
	v_mov_b32_e32 v131, v7
	v_mov_b32_e32 v138, v87
	v_mov_b32_e32 v139, v91
	v_mov_b32_e32 v144, v26
	v_mov_b32_e32 v145, v10
	v_mov_b32_e32 v160, v28
	v_mov_b32_e32 v161, v12
	v_mov_b32_e32 v172, v100
	v_mov_b32_e32 v173, v104
	v_pk_fma_f32 v[126:127], v[126:127], v[126:127], v[132:133]
	v_pk_fma_f32 v[132:133], v[148:149], v[148:149], v[134:135]
	v_pk_mul_f32 v[134:135], v[170:171], v[170:171]
	s_waitcnt vmcnt(3)
	v_mov_b32_e32 v178, v33
	s_waitcnt vmcnt(2)
	v_mov_b32_e32 v179, v17
	s_waitcnt vmcnt(0)
	v_pk_add_f32 v[112:113], v[112:113], 1.0 op_sel_hi:[1,0]
	v_pk_fma_f32 v[116:117], v[120:121], v[120:121], v[116:117]
	v_pk_fma_f32 v[120:121], v[136:137], v[136:137], v[122:123]
	v_pk_fma_f32 v[122:123], v[154:155], v[154:155], v[124:125]
	v_pk_mul_f32 v[124:125], v[174:175], v[174:175]
	v_mov_b32_e32 v146, v27
	v_mov_b32_e32 v147, v11
	v_mov_b32_e32 v142, v94
	v_mov_b32_e32 v143, v98
	v_mov_b32_e32 v140, v102
	v_mov_b32_e32 v141, v106
	v_mov_b32_e32 v176, v32
	v_mov_b32_e32 v177, v16
	v_pk_add_f32 v[114:115], v[114:115], 1.0 op_sel_hi:[1,0]
	v_pk_fma_f32 v[126:127], v[130:131], v[130:131], v[126:127]
	v_pk_fma_f32 v[130:131], v[144:145], v[144:145], v[132:133]
	v_pk_fma_f32 v[132:133], v[160:161], v[160:161], v[134:135]
	v_pk_mul_f32 v[134:135], v[178:179], v[178:179]
	v_pk_mul_f32 v[0:1], v[0:1], v[112:113]
	v_pk_fma_f32 v[112:113], v[138:139], v[138:139], v[120:121]
	v_pk_fma_f32 v[120:121], v[172:173], v[172:173], v[124:125]
	v_mov_b32_e32 v152, v95
	v_mov_b32_e32 v153, v99
	v_mov_b32_e32 v150, v30
	v_mov_b32_e32 v151, v14
	v_mov_b32_e32 v156, v103
	v_mov_b32_e32 v157, v107
	v_mov_b32_e32 v148, v34
	v_mov_b32_e32 v149, v18
	v_pk_mul_f32 v[2:3], v[2:3], v[114:115]
	v_pk_fma_f32 v[114:115], v[142:143], v[142:143], v[122:123]
	v_pk_fma_f32 v[122:123], v[146:147], v[146:147], v[130:131]
	v_mov_b32_e32 v125, v116
	v_pk_fma_f32 v[134:135], v[176:177], v[176:177], v[134:135]
	v_pk_fma_f32 v[120:121], v[140:141], v[140:141], v[120:121]
	v_mov_b32_e32 v124, v112
	v_mov_b32_e32 v116, v113
	v_mov_b32_e32 v158, v31
	v_mov_b32_e32 v159, v15
	v_mov_b32_e32 v170, v35
	v_mov_b32_e32 v171, v19
	v_mov_b32_e32 v131, v126
	v_pk_fma_f32 v[132:133], v[150:151], v[150:151], v[132:133]
	v_pk_fma_f32 v[114:115], v[152:153], v[152:153], v[114:115]
	v_mov_b32_e32 v130, v122
	v_mov_b32_e32 v126, v123
	v_pk_fma_f32 v[122:123], v[148:149], v[148:149], v[134:135]
	v_pk_fma_f32 v[120:121], v[156:157], v[156:157], v[120:121]
	v_pk_add_f32 v[116:117], v[124:125], v[116:117]
	v_pk_fma_f32 v[112:113], v[158:159], v[158:159], v[132:133]
	v_pk_fma_f32 v[122:123], v[170:171], v[170:171], v[122:123]
	v_mov_b32_e32 v125, v114
	v_pk_add_f32 v[116:117], v[116:117], v[130:131]
	v_mov_b32_e32 v124, v120
	v_mov_b32_e32 v114, v121
	v_mov_b32_e32 v133, v112
	v_mov_b32_e32 v132, v122
	v_pk_add_f32 v[116:117], v[116:117], v[126:127]
	v_pk_add_f32 v[114:115], v[124:125], v[114:115]
	v_mov_b32_e32 v112, v123
	ds_bpermute_b32 v121, v74, v117
	ds_bpermute_b32 v120, v74, v116
	v_pk_add_f32 v[114:115], v[114:115], v[132:133]
	s_waitcnt lgkmcnt(0)
	v_pk_add_f32 v[116:117], v[116:117], v[120:121]
	v_pk_add_f32 v[112:113], v[114:115], v[112:113]
	ds_bpermute_b32 v115, v74, v113
	ds_bpermute_b32 v114, v74, v112
	ds_bpermute_b32 v121, v75, v117
	ds_bpermute_b32 v120, v75, v116
	s_waitcnt lgkmcnt(2)
	v_pk_add_f32 v[112:113], v[112:113], v[114:115]
	ds_bpermute_b32 v115, v75, v113
	ds_bpermute_b32 v114, v75, v112
	s_waitcnt lgkmcnt(2)
	v_pk_add_f32 v[116:117], v[116:117], v[120:121]
	ds_bpermute_b32 v121, v76, v117
	ds_bpermute_b32 v120, v76, v116
	s_waitcnt lgkmcnt(2)
	v_pk_add_f32 v[112:113], v[112:113], v[114:115]
	ds_bpermute_b32 v115, v76, v113
	ds_bpermute_b32 v114, v76, v112
	s_waitcnt lgkmcnt(2)
	v_pk_add_f32 v[116:117], v[116:117], v[120:121]
	ds_bpermute_b32 v121, v77, v117
	ds_bpermute_b32 v120, v77, v116
	s_waitcnt lgkmcnt(2)
	v_pk_add_f32 v[112:113], v[112:113], v[114:115]
	ds_bpermute_b32 v115, v77, v113
	ds_bpermute_b32 v114, v77, v112
	s_waitcnt lgkmcnt(2)
	v_pk_add_f32 v[116:117], v[116:117], v[120:121]
	ds_bpermute_b32 v121, v78, v117
	ds_bpermute_b32 v120, v78, v116
	s_waitcnt lgkmcnt(2)
	v_pk_add_f32 v[112:113], v[112:113], v[114:115]
	ds_bpermute_b32 v115, v78, v113
	ds_bpermute_b32 v114, v78, v112
	s_waitcnt lgkmcnt(2)
	v_pk_add_f32 v[116:117], v[116:117], v[120:121]
	ds_bpermute_b32 v121, v79, v117
	ds_bpermute_b32 v120, v79, v116
	s_waitcnt lgkmcnt(2)
	v_pk_add_f32 v[112:113], v[112:113], v[114:115]
	ds_bpermute_b32 v115, v79, v113
	ds_bpermute_b32 v114, v79, v112
	s_waitcnt lgkmcnt(2)
	v_pk_add_f32 v[116:117], v[116:117], v[120:121]
	s_waitcnt lgkmcnt(0)
	v_pk_add_f32 v[112:113], v[112:113], v[114:115]
	v_pk_fma_f32 v[116:117], v[116:117], s[24:25], v[64:65] op_sel_hi:[1,0,0]
	v_pk_fma_f32 v[112:113], v[112:113], s[24:25], v[64:65] op_sel_hi:[1,0,0]
	v_mul_f32_e32 v41, 0x4b800000, v117
	v_mul_f32_e32 v120, 0x4b800000, v116
	v_cmp_gt_f32_e32 vcc, s27, v116
	v_cmp_gt_f32_e64 s[4:5], s27, v117
	v_mul_f32_e32 v115, 0x4b800000, v113
	v_cndmask_b32_e32 v114, v116, v120, vcc
	v_cndmask_b32_e64 v41, v117, v41, s[4:5]
	v_rsq_f32_e32 v41, v41
	v_rsq_f32_e32 v114, v114
	v_mul_f32_e32 v116, 0x4b800000, v112
	v_cmp_gt_f32_e64 s[6:7], s27, v112
	v_cmp_gt_f32_e64 s[8:9], s27, v113
	s_nop 0
	v_cndmask_b32_e64 v112, v112, v116, s[6:7]
	v_cndmask_b32_e64 v113, v113, v115, s[8:9]
	v_rsq_f32_e32 v113, v113
	v_rsq_f32_e32 v115, v112
	v_mul_f32_e32 v112, 0x45800000, v41
	v_mul_f32_e32 v116, 0x45800000, v114
	v_cndmask_b32_e64 v112, v41, v112, s[4:5]
	v_cndmask_b32_e32 v114, v114, v116, vcc
	v_pk_mul_f32 v[80:81], v[80:81], v[112:113] op_sel_hi:[1,0]
	v_pk_mul_f32 v[82:83], v[82:83], v[112:113] op_sel_hi:[1,0]
	v_pk_mul_f32 v[84:85], v[84:85], v[114:115] op_sel_hi:[1,0]
	v_pk_mul_f32 v[86:87], v[86:87], v[114:115] op_sel_hi:[1,0]
	v_mul_f32_e32 v41, 0x45800000, v113
	v_mul_f32_e32 v117, 0x45800000, v115
	v_pk_fma_f32 v[80:81], v[80:81], v[0:1], v[108:109]
	v_pk_fma_f32 v[82:83], v[82:83], v[2:3], v[110:111]
	v_pk_fma_f32 v[84:85], v[84:85], v[0:1], v[108:109]
	v_pk_fma_f32 v[86:87], v[86:87], v[2:3], v[110:111]
	v_cndmask_b32_e64 v116, v113, v41, s[8:9]
	v_cndmask_b32_e64 v120, v115, v117, s[6:7]
	v_cvt_pk_bf16_f32 v80, v80, v81
	v_cvt_pk_bf16_f32 v81, v82, v83
	v_cvt_pk_bf16_f32 v82, v84, v85
	v_cvt_pk_bf16_f32 v83, v86, v87
	v_pk_mul_f32 v[84:85], v[92:93], v[116:117] op_sel_hi:[1,0]
	v_pk_mul_f32 v[86:87], v[94:95], v[116:117] op_sel_hi:[1,0]
	v_pk_mul_f32 v[92:93], v[100:101], v[120:121] op_sel_hi:[1,0]
	v_pk_mul_f32 v[94:95], v[102:103], v[120:121] op_sel_hi:[1,0]
	v_pk_fma_f32 v[84:85], v[84:85], v[0:1], v[108:109]
	v_pk_fma_f32 v[86:87], v[86:87], v[2:3], v[110:111]
	v_pk_fma_f32 v[0:1], v[92:93], v[0:1], v[108:109]
	v_pk_fma_f32 v[2:3], v[94:95], v[2:3], v[110:111]
	global_store_dwordx2 v[66:67], v[80:81], off offset:256
	global_store_dwordx2 v[66:67], v[82:83], off offset:2304
	v_cvt_pk_bf16_f32 v80, v84, v85
	v_cvt_pk_bf16_f32 v81, v86, v87
	v_cvt_pk_bf16_f32 v0, v0, v1
	v_cvt_pk_bf16_f32 v1, v2, v3
	global_store_dwordx2 v[68:69], v[80:81], off offset:256
	global_store_dwordx2 v[68:69], v[0:1], off offset:2304
	global_load_dwordx4 v[0:3], v[118:119], off
	s_nop 0
	global_load_dwordx4 v[80:83], v[70:71], off offset:1024
	global_load_dwordx4 v[84:87], v[46:47], off
	v_pk_mul_f32 v[36:37], v[36:37], v[112:113] op_sel_hi:[1,0]
	v_pk_mul_f32 v[38:39], v[38:39], v[112:113] op_sel_hi:[1,0]
	v_pk_mul_f32 v[88:89], v[88:89], v[114:115] op_sel_hi:[1,0]
	v_pk_mul_f32 v[90:91], v[90:91], v[114:115] op_sel_hi:[1,0]
	v_pk_mul_f32 v[94:95], v[96:97], v[116:117] op_sel_hi:[1,0]
	v_pk_mul_f32 v[96:97], v[98:99], v[116:117] op_sel_hi:[1,0]
	v_pk_mul_f32 v[98:99], v[104:105], v[120:121] op_sel_hi:[1,0]
	v_pk_mul_f32 v[100:101], v[106:107], v[120:121] op_sel_hi:[1,0]
	v_lshl_add_u64 v[92:93], v[72:73], 0, v[60:61]
	v_pk_mul_f32 v[20:21], v[20:21], v[112:113] op_sel_hi:[1,0]
	v_pk_mul_f32 v[22:23], v[22:23], v[112:113] op_sel_hi:[1,0]
	v_pk_mul_f32 v[24:25], v[24:25], v[114:115] op_sel_hi:[1,0]
	v_pk_mul_f32 v[26:27], v[26:27], v[114:115] op_sel_hi:[1,0]
	v_pk_mul_f32 v[28:29], v[28:29], v[116:117] op_sel_hi:[1,0]
	v_pk_mul_f32 v[30:31], v[30:31], v[116:117] op_sel_hi:[1,0]
	v_pk_mul_f32 v[32:33], v[32:33], v[120:121] op_sel_hi:[1,0]
	v_pk_mul_f32 v[34:35], v[34:35], v[120:121] op_sel_hi:[1,0]
	v_lshl_add_u64 v[72:73], v[72:73], 0, v[62:63]
	v_pk_mul_f32 v[4:5], v[4:5], v[112:113] op_sel_hi:[1,0]
	v_pk_mul_f32 v[6:7], v[6:7], v[112:113] op_sel_hi:[1,0]
	v_cmp_lt_i32_e32 vcc, s30, v40
	v_pk_mul_f32 v[8:9], v[8:9], v[114:115] op_sel_hi:[1,0]
	v_pk_mul_f32 v[10:11], v[10:11], v[114:115] op_sel_hi:[1,0]
	v_pk_mul_f32 v[12:13], v[12:13], v[116:117] op_sel_hi:[1,0]
	v_pk_mul_f32 v[14:15], v[14:15], v[116:117] op_sel_hi:[1,0]
	v_pk_mul_f32 v[16:17], v[16:17], v[120:121] op_sel_hi:[1,0]
	v_pk_mul_f32 v[18:19], v[18:19], v[120:121] op_sel_hi:[1,0]
	s_or_b64 s[22:23], vcc, s[22:23]
	s_waitcnt vmcnt(2)
	v_pk_add_f32 v[0:1], v[0:1], 1.0 op_sel_hi:[1,0]
	v_pk_add_f32 v[2:3], v[2:3], 1.0 op_sel_hi:[1,0]
	s_waitcnt vmcnt(0)
	v_pk_mul_f32 v[0:1], v[84:85], v[0:1]
	v_pk_mul_f32 v[2:3], v[86:87], v[2:3]
	v_pk_fma_f32 v[36:37], v[36:37], v[0:1], v[80:81]
	v_pk_fma_f32 v[38:39], v[38:39], v[2:3], v[82:83]
	v_pk_fma_f32 v[84:85], v[88:89], v[0:1], v[80:81]
	v_pk_fma_f32 v[86:87], v[90:91], v[2:3], v[82:83]
	v_pk_fma_f32 v[88:89], v[94:95], v[0:1], v[80:81]
	v_pk_fma_f32 v[90:91], v[96:97], v[2:3], v[82:83]
	v_pk_fma_f32 v[0:1], v[98:99], v[0:1], v[80:81]
	v_pk_fma_f32 v[2:3], v[100:101], v[2:3], v[82:83]
	v_cvt_pk_bf16_f32 v36, v36, v37
	v_cvt_pk_bf16_f32 v37, v38, v39
	v_cvt_pk_bf16_f32 v38, v84, v85
	v_cvt_pk_bf16_f32 v39, v86, v87
	v_cvt_pk_bf16_f32 v80, v88, v89
	v_cvt_pk_bf16_f32 v81, v90, v91
	v_cvt_pk_bf16_f32 v0, v0, v1
	v_cvt_pk_bf16_f32 v1, v2, v3
	global_store_dwordx2 v[66:67], v[36:37], off offset:768
	global_store_dwordx2 v[66:67], v[38:39], off offset:2816
	global_store_dwordx2 v[68:69], v[80:81], off offset:768
	global_store_dwordx2 v[68:69], v[0:1], off offset:2816
	global_load_dwordx4 v[0:3], v[92:93], off
	s_nop 0
	global_load_dwordx4 v[36:39], v[70:71], off offset:2048
	global_load_dwordx4 v[80:83], v[48:49], off
	s_waitcnt vmcnt(2)
	v_pk_add_f32 v[0:1], v[0:1], 1.0 op_sel_hi:[1,0]
	v_pk_add_f32 v[2:3], v[2:3], 1.0 op_sel_hi:[1,0]
	s_waitcnt vmcnt(0)
	v_pk_mul_f32 v[0:1], v[80:81], v[0:1]
	v_pk_mul_f32 v[2:3], v[82:83], v[2:3]
	v_pk_fma_f32 v[20:21], v[20:21], v[0:1], v[36:37]
	v_pk_fma_f32 v[22:23], v[22:23], v[2:3], v[38:39]
	v_pk_fma_f32 v[24:25], v[24:25], v[0:1], v[36:37]
	v_pk_fma_f32 v[26:27], v[26:27], v[2:3], v[38:39]
	v_pk_fma_f32 v[28:29], v[28:29], v[0:1], v[36:37]
	v_pk_fma_f32 v[30:31], v[30:31], v[2:3], v[38:39]
	v_pk_fma_f32 v[0:1], v[32:33], v[0:1], v[36:37]
	v_pk_fma_f32 v[2:3], v[34:35], v[2:3], v[38:39]
	v_cvt_pk_bf16_f32 v20, v20, v21
	v_cvt_pk_bf16_f32 v21, v22, v23
	v_cvt_pk_bf16_f32 v22, v24, v25
	v_cvt_pk_bf16_f32 v23, v26, v27
	v_cvt_pk_bf16_f32 v24, v28, v29
	v_cvt_pk_bf16_f32 v25, v30, v31
	v_cvt_pk_bf16_f32 v0, v0, v1
	v_cvt_pk_bf16_f32 v1, v2, v3
	global_store_dwordx2 v[66:67], v[20:21], off offset:1280
	global_store_dwordx2 v[66:67], v[22:23], off offset:3328
	global_store_dwordx2 v[68:69], v[24:25], off offset:1280
	global_store_dwordx2 v[68:69], v[0:1], off offset:3328
	global_load_dwordx4 v[0:3], v[72:73], off
	s_nop 0
	global_load_dwordx4 v[20:23], v[70:71], off offset:3072
	global_load_dwordx4 v[24:27], v[50:51], off
	s_waitcnt vmcnt(2)
	v_pk_add_f32 v[0:1], v[0:1], 1.0 op_sel_hi:[1,0]
	v_pk_add_f32 v[2:3], v[2:3], 1.0 op_sel_hi:[1,0]
	s_waitcnt vmcnt(0)
	v_pk_mul_f32 v[0:1], v[24:25], v[0:1]
	v_pk_mul_f32 v[2:3], v[26:27], v[2:3]
	v_pk_fma_f32 v[4:5], v[4:5], v[0:1], v[20:21]
	v_pk_fma_f32 v[6:7], v[6:7], v[2:3], v[22:23]
	v_pk_fma_f32 v[8:9], v[8:9], v[0:1], v[20:21]
	v_pk_fma_f32 v[10:11], v[10:11], v[2:3], v[22:23]
	v_pk_fma_f32 v[12:13], v[12:13], v[0:1], v[20:21]
	v_pk_fma_f32 v[14:15], v[14:15], v[2:3], v[22:23]
	v_pk_fma_f32 v[0:1], v[16:17], v[0:1], v[20:21]
	v_pk_fma_f32 v[2:3], v[18:19], v[2:3], v[22:23]
	v_cvt_pk_bf16_f32 v4, v4, v5
	v_cvt_pk_bf16_f32 v5, v6, v7
	v_cvt_pk_bf16_f32 v6, v8, v9
	v_cvt_pk_bf16_f32 v7, v10, v11
	v_cvt_pk_bf16_f32 v8, v12, v13
	v_cvt_pk_bf16_f32 v9, v14, v15
	v_cvt_pk_bf16_f32 v0, v0, v1
	v_cvt_pk_bf16_f32 v1, v2, v3
	global_store_dwordx2 v[66:67], v[4:5], off offset:1792
	global_store_dwordx2 v[66:67], v[6:7], off offset:3840
	global_store_dwordx2 v[68:69], v[8:9], off offset:1792
	global_store_dwordx2 v[68:69], v[0:1], off offset:3840
	s_andn2_b64 exec, exec, s[22:23]
	s_cbranch_execnz .LBB0_1078

.Lr13_loop:
	s_waitcnt vmcnt(8)
	s_barrier
	ds_read_b128 v[64:67], v252 offset:0
	ds_read_b128 v[96:99], v254 offset:32768
	ds_read_b128 v[100:103], v254 offset:34816
	ds_read_b128 v[104:107], v254 offset:36864
	ds_read_b128 v[108:111], v254 offset:38912
	ds_read_b128 v[68:71], v252 offset:2048
	ds_read_b128 v[72:75], v252 offset:4096
	ds_read_b128 v[76:79], v252 offset:6144
	v_mfma_f32_16x16x32_bf16 v[0:3], v[80:83], v[112:115], v[0:3]
	v_mfma_f32_16x16x32_bf16 v[4:7], v[80:83], v[116:119], v[4:7]
	v_mfma_f32_16x16x32_bf16 v[8:11], v[80:83], v[120:123], v[8:11]
	v_mfma_f32_16x16x32_bf16 v[12:15], v[80:83], v[124:127], v[12:15]
	v_mfma_f32_16x16x32_bf16 v[16:19], v[84:87], v[112:115], v[16:19]
	v_mfma_f32_16x16x32_bf16 v[20:23], v[84:87], v[116:119], v[20:23]
	v_mfma_f32_16x16x32_bf16 v[24:27], v[84:87], v[120:123], v[24:27]
	v_mfma_f32_16x16x32_bf16 v[28:31], v[84:87], v[124:127], v[28:31]
	v_mfma_f32_16x16x32_bf16 v[32:35], v[88:91], v[112:115], v[32:35]
	v_mfma_f32_16x16x32_bf16 v[36:39], v[88:91], v[116:119], v[36:39]
	v_mfma_f32_16x16x32_bf16 v[40:43], v[88:91], v[120:123], v[40:43]
	v_mfma_f32_16x16x32_bf16 v[44:47], v[88:91], v[124:127], v[44:47]
	v_mfma_f32_16x16x32_bf16 v[48:51], v[92:95], v[112:115], v[48:51]
	v_mfma_f32_16x16x32_bf16 v[52:55], v[92:95], v[116:119], v[52:55]
	v_mfma_f32_16x16x32_bf16 v[56:59], v[92:95], v[120:123], v[56:59]
	v_mfma_f32_16x16x32_bf16 v[60:63], v[92:95], v[124:127], v[60:63]
	ds_read_b128 v[80:83], v253 offset:0
	ds_read_b128 v[112:115], v255 offset:32768
	ds_read_b128 v[116:119], v255 offset:34816
	ds_read_b128 v[120:123], v255 offset:36864
	ds_read_b128 v[124:127], v255 offset:38912
	ds_read_b128 v[84:87], v253 offset:2048
	ds_read_b128 v[88:91], v253 offset:4096
	ds_read_b128 v[92:95], v253 offset:6144
	s_waitcnt lgkmcnt(14)
	v_mfma_f32_16x16x32_bf16 v[0:3], v[64:67], v[96:99], v[0:3]
	s_waitcnt lgkmcnt(13)
	v_mfma_f32_16x16x32_bf16 v[4:7], v[64:67], v[100:103], v[4:7]
	s_waitcnt lgkmcnt(12)
	v_mfma_f32_16x16x32_bf16 v[8:11], v[64:67], v[104:107], v[8:11]
	s_waitcnt lgkmcnt(11)
	v_mfma_f32_16x16x32_bf16 v[12:15], v[64:67], v[108:111], v[12:15]
	s_waitcnt lgkmcnt(10)
	v_mfma_f32_16x16x32_bf16 v[16:19], v[68:71], v[96:99], v[16:19]
	v_mfma_f32_16x16x32_bf16 v[20:23], v[68:71], v[100:103], v[20:23]
	v_mfma_f32_16x16x32_bf16 v[24:27], v[68:71], v[104:107], v[24:27]
	v_mfma_f32_16x16x32_bf16 v[28:31], v[68:71], v[108:111], v[28:31]
	s_waitcnt lgkmcnt(0)
	s_barrier
	s_add_u32 m0, s12, 0x0
	v_mfma_f32_16x16x32_bf16 v[32:35], v[72:75], v[96:99], v[32:35]
	global_load_lds_dwordx4 v248, s[8:9]
	s_add_u32 m0, s12, 0x400
	v_mfma_f32_16x16x32_bf16 v[36:39], v[72:75], v[100:103], v[36:39]
	global_load_lds_dwordx4 v249, s[8:9]
	s_add_u32 m0, s12, 0x800
	v_mfma_f32_16x16x32_bf16 v[40:43], v[72:75], v[104:107], v[40:43]
	global_load_lds_dwordx4 v250, s[8:9]
	s_add_u32 m0, s12, 0xc00
	v_mfma_f32_16x16x32_bf16 v[44:47], v[72:75], v[108:111], v[44:47]
	global_load_lds_dwordx4 v251, s[8:9]
	s_add_u32 m0, s12, 0x8000
	v_mfma_f32_16x16x32_bf16 v[48:51], v[76:79], v[96:99], v[48:51]
	global_load_lds_dwordx4 v248, s[10:11] sc1
	s_add_u32 m0, s12, 0x8400
	v_mfma_f32_16x16x32_bf16 v[52:55], v[76:79], v[100:103], v[52:55]
	global_load_lds_dwordx4 v249, s[10:11] sc1
	s_add_u32 m0, s12, 0x8800
	v_mfma_f32_16x16x32_bf16 v[56:59], v[76:79], v[104:107], v[56:59]
	global_load_lds_dwordx4 v250, s[10:11] sc1
	s_add_u32 m0, s12, 0x8c00
	v_mfma_f32_16x16x32_bf16 v[60:63], v[76:79], v[108:111], v[60:63]
	global_load_lds_dwordx4 v251, s[10:11] sc1
	s_add_u32 s8, s8, 0x80
	s_addc_u32 s9, s9, 0
	s_add_u32 s10, s10, 0x80
	s_addc_u32 s11, s11, 0
	s_waitcnt vmcnt(8)
	s_barrier
	ds_read_b128 v[64:67], v252 offset:16384
	ds_read_b128 v[96:99], v254 offset:49152
	ds_read_b128 v[100:103], v254 offset:51200
	ds_read_b128 v[104:107], v254 offset:53248
	ds_read_b128 v[108:111], v254 offset:55296
	ds_read_b128 v[68:71], v252 offset:18432
	ds_read_b128 v[72:75], v252 offset:20480
	ds_read_b128 v[76:79], v252 offset:22528
	v_mfma_f32_16x16x32_bf16 v[0:3], v[80:83], v[112:115], v[0:3]
	v_mfma_f32_16x16x32_bf16 v[4:7], v[80:83], v[116:119], v[4:7]
	v_mfma_f32_16x16x32_bf16 v[8:11], v[80:83], v[120:123], v[8:11]
	v_mfma_f32_16x16x32_bf16 v[12:15], v[80:83], v[124:127], v[12:15]
	v_mfma_f32_16x16x32_bf16 v[16:19], v[84:87], v[112:115], v[16:19]
	v_mfma_f32_16x16x32_bf16 v[20:23], v[84:87], v[116:119], v[20:23]
	v_mfma_f32_16x16x32_bf16 v[24:27], v[84:87], v[120:123], v[24:27]
	v_mfma_f32_16x16x32_bf16 v[28:31], v[84:87], v[124:127], v[28:31]
	v_mfma_f32_16x16x32_bf16 v[32:35], v[88:91], v[112:115], v[32:35]
	v_mfma_f32_16x16x32_bf16 v[36:39], v[88:91], v[116:119], v[36:39]
	v_mfma_f32_16x16x32_bf16 v[40:43], v[88:91], v[120:123], v[40:43]
	v_mfma_f32_16x16x32_bf16 v[44:47], v[88:91], v[124:127], v[44:47]
	v_mfma_f32_16x16x32_bf16 v[48:51], v[92:95], v[112:115], v[48:51]
	v_mfma_f32_16x16x32_bf16 v[52:55], v[92:95], v[116:119], v[52:55]
	v_mfma_f32_16x16x32_bf16 v[56:59], v[92:95], v[120:123], v[56:59]
	v_mfma_f32_16x16x32_bf16 v[60:63], v[92:95], v[124:127], v[60:63]
	ds_read_b128 v[80:83], v253 offset:16384
	ds_read_b128 v[112:115], v255 offset:49152
	ds_read_b128 v[116:119], v255 offset:51200
	ds_read_b128 v[120:123], v255 offset:53248
	ds_read_b128 v[124:127], v255 offset:55296
	ds_read_b128 v[84:87], v253 offset:18432
	ds_read_b128 v[88:91], v253 offset:20480
	ds_read_b128 v[92:95], v253 offset:22528
	s_waitcnt lgkmcnt(14)
	v_mfma_f32_16x16x32_bf16 v[0:3], v[64:67], v[96:99], v[0:3]
	s_waitcnt lgkmcnt(13)
	v_mfma_f32_16x16x32_bf16 v[4:7], v[64:67], v[100:103], v[4:7]
	s_waitcnt lgkmcnt(12)
	v_mfma_f32_16x16x32_bf16 v[8:11], v[64:67], v[104:107], v[8:11]
	s_waitcnt lgkmcnt(11)
	v_mfma_f32_16x16x32_bf16 v[12:15], v[64:67], v[108:111], v[12:15]
	s_waitcnt lgkmcnt(10)
	v_mfma_f32_16x16x32_bf16 v[16:19], v[68:71], v[96:99], v[16:19]
	v_mfma_f32_16x16x32_bf16 v[20:23], v[68:71], v[100:103], v[20:23]
	v_mfma_f32_16x16x32_bf16 v[24:27], v[68:71], v[104:107], v[24:27]
	v_mfma_f32_16x16x32_bf16 v[28:31], v[68:71], v[108:111], v[28:31]
	s_waitcnt lgkmcnt(0)
	s_barrier
	s_add_u32 m0, s12, 0x4000
	v_mfma_f32_16x16x32_bf16 v[32:35], v[72:75], v[96:99], v[32:35]
	global_load_lds_dwordx4 v248, s[8:9]
	s_add_u32 m0, s12, 0x4400
	v_mfma_f32_16x16x32_bf16 v[36:39], v[72:75], v[100:103], v[36:39]
	global_load_lds_dwordx4 v249, s[8:9]
	s_add_u32 m0, s12, 0x4800
	v_mfma_f32_16x16x32_bf16 v[40:43], v[72:75], v[104:107], v[40:43]
	global_load_lds_dwordx4 v250, s[8:9]
	s_add_u32 m0, s12, 0x4c00
	v_mfma_f32_16x16x32_bf16 v[44:47], v[72:75], v[108:111], v[44:47]
	global_load_lds_dwordx4 v251, s[8:9]
	s_add_u32 m0, s12, 0xc000
	v_mfma_f32_16x16x32_bf16 v[48:51], v[76:79], v[96:99], v[48:51]
	global_load_lds_dwordx4 v248, s[10:11] sc1
	s_add_u32 m0, s12, 0xc400
	v_mfma_f32_16x16x32_bf16 v[52:55], v[76:79], v[100:103], v[52:55]
	global_load_lds_dwordx4 v249, s[10:11] sc1
	s_add_u32 m0, s12, 0xc800
	v_mfma_f32_16x16x32_bf16 v[56:59], v[76:79], v[104:107], v[56:59]
	global_load_lds_dwordx4 v250, s[10:11] sc1
	s_add_u32 m0, s12, 0xcc00
	v_mfma_f32_16x16x32_bf16 v[60:63], v[76:79], v[108:111], v[60:63]
	global_load_lds_dwordx4 v251, s[10:11] sc1
	s_add_u32 s8, s8, 0x80
	s_addc_u32 s9, s9, 0
	s_add_u32 s10, s10, 0x80
	s_addc_u32 s11, s11, 0
	s_sub_u32 s13, s13, 1
	s_cmp_lg_u32 s13, 0
	s_cbranch_scc1 .Lr13_loop
	s_waitcnt vmcnt(8)
	s_barrier
	ds_read_b128 v[64:67], v252 offset:0
	ds_read_b128 v[96:99], v254 offset:32768
	ds_read_b128 v[100:103], v254 offset:34816
	ds_read_b128 v[104:107], v254 offset:36864
	ds_read_b128 v[108:111], v254 offset:38912
	ds_read_b128 v[68:71], v252 offset:2048
	ds_read_b128 v[72:75], v252 offset:4096
	ds_read_b128 v[76:79], v252 offset:6144
	v_mfma_f32_16x16x32_bf16 v[0:3], v[80:83], v[112:115], v[0:3]
	v_mfma_f32_16x16x32_bf16 v[4:7], v[80:83], v[116:119], v[4:7]
	v_mfma_f32_16x16x32_bf16 v[8:11], v[80:83], v[120:123], v[8:11]
	v_mfma_f32_16x16x32_bf16 v[12:15], v[80:83], v[124:127], v[12:15]
	v_mfma_f32_16x16x32_bf16 v[16:19], v[84:87], v[112:115], v[16:19]
	v_mfma_f32_16x16x32_bf16 v[20:23], v[84:87], v[116:119], v[20:23]
	v_mfma_f32_16x16x32_bf16 v[24:27], v[84:87], v[120:123], v[24:27]
	v_mfma_f32_16x16x32_bf16 v[28:31], v[84:87], v[124:127], v[28:31]
	v_mfma_f32_16x16x32_bf16 v[32:35], v[88:91], v[112:115], v[32:35]
	v_mfma_f32_16x16x32_bf16 v[36:39], v[88:91], v[116:119], v[36:39]
	v_mfma_f32_16x16x32_bf16 v[40:43], v[88:91], v[120:123], v[40:43]
	v_mfma_f32_16x16x32_bf16 v[44:47], v[88:91], v[124:127], v[44:47]
	v_mfma_f32_16x16x32_bf16 v[48:51], v[92:95], v[112:115], v[48:51]
	v_mfma_f32_16x16x32_bf16 v[52:55], v[92:95], v[116:119], v[52:55]
	v_mfma_f32_16x16x32_bf16 v[56:59], v[92:95], v[120:123], v[56:59]
	v_mfma_f32_16x16x32_bf16 v[60:63], v[92:95], v[124:127], v[60:63]
	ds_read_b128 v[80:83], v253 offset:0
	ds_read_b128 v[112:115], v255 offset:32768
	ds_read_b128 v[116:119], v255 offset:34816
	ds_read_b128 v[120:123], v255 offset:36864
	ds_read_b128 v[124:127], v255 offset:38912
	ds_read_b128 v[84:87], v253 offset:2048
	ds_read_b128 v[88:91], v253 offset:4096
	ds_read_b128 v[92:95], v253 offset:6144
	s_waitcnt lgkmcnt(14)
	v_mfma_f32_16x16x32_bf16 v[0:3], v[64:67], v[96:99], v[0:3]
	s_waitcnt lgkmcnt(13)
	v_mfma_f32_16x16x32_bf16 v[4:7], v[64:67], v[100:103], v[4:7]
	s_waitcnt lgkmcnt(12)
	v_mfma_f32_16x16x32_bf16 v[8:11], v[64:67], v[104:107], v[8:11]
	s_waitcnt lgkmcnt(11)
	v_mfma_f32_16x16x32_bf16 v[12:15], v[64:67], v[108:111], v[12:15]
	s_waitcnt lgkmcnt(10)
	v_mfma_f32_16x16x32_bf16 v[16:19], v[68:71], v[96:99], v[16:19]
	v_mfma_f32_16x16x32_bf16 v[20:23], v[68:71], v[100:103], v[20:23]
	v_mfma_f32_16x16x32_bf16 v[24:27], v[68:71], v[104:107], v[24:27]
	v_mfma_f32_16x16x32_bf16 v[28:31], v[68:71], v[108:111], v[28:31]
	s_waitcnt lgkmcnt(0)
	s_barrier
	v_mfma_f32_16x16x32_bf16 v[32:35], v[72:75], v[96:99], v[32:35]
	v_mfma_f32_16x16x32_bf16 v[36:39], v[72:75], v[100:103], v[36:39]
	v_mfma_f32_16x16x32_bf16 v[40:43], v[72:75], v[104:107], v[40:43]
	v_mfma_f32_16x16x32_bf16 v[44:47], v[72:75], v[108:111], v[44:47]
	v_mfma_f32_16x16x32_bf16 v[48:51], v[76:79], v[96:99], v[48:51]
	v_mfma_f32_16x16x32_bf16 v[52:55], v[76:79], v[100:103], v[52:55]
	v_mfma_f32_16x16x32_bf16 v[56:59], v[76:79], v[104:107], v[56:59]
	v_mfma_f32_16x16x32_bf16 v[60:63], v[76:79], v[108:111], v[60:63]
	s_waitcnt vmcnt(0)
	s_barrier
	ds_read_b128 v[64:67], v252 offset:16384
	ds_read_b128 v[96:99], v254 offset:49152
	ds_read_b128 v[100:103], v254 offset:51200
	ds_read_b128 v[104:107], v254 offset:53248
	ds_read_b128 v[108:111], v254 offset:55296
	ds_read_b128 v[68:71], v252 offset:18432
	ds_read_b128 v[72:75], v252 offset:20480
	ds_read_b128 v[76:79], v252 offset:22528
	v_mfma_f32_16x16x32_bf16 v[0:3], v[80:83], v[112:115], v[0:3]
	v_mfma_f32_16x16x32_bf16 v[4:7], v[80:83], v[116:119], v[4:7]
	v_mfma_f32_16x16x32_bf16 v[8:11], v[80:83], v[120:123], v[8:11]
	v_mfma_f32_16x16x32_bf16 v[12:15], v[80:83], v[124:127], v[12:15]
	v_mfma_f32_16x16x32_bf16 v[16:19], v[84:87], v[112:115], v[16:19]
	v_mfma_f32_16x16x32_bf16 v[20:23], v[84:87], v[116:119], v[20:23]
	v_mfma_f32_16x16x32_bf16 v[24:27], v[84:87], v[120:123], v[24:27]
	v_mfma_f32_16x16x32_bf16 v[28:31], v[84:87], v[124:127], v[28:31]
	v_mfma_f32_16x16x32_bf16 v[32:35], v[88:91], v[112:115], v[32:35]
	v_mfma_f32_16x16x32_bf16 v[36:39], v[88:91], v[116:119], v[36:39]
	v_mfma_f32_16x16x32_bf16 v[40:43], v[88:91], v[120:123], v[40:43]
	v_mfma_f32_16x16x32_bf16 v[44:47], v[88:91], v[124:127], v[44:47]
	v_mfma_f32_16x16x32_bf16 v[48:51], v[92:95], v[112:115], v[48:51]
	v_mfma_f32_16x16x32_bf16 v[52:55], v[92:95], v[116:119], v[52:55]
	v_mfma_f32_16x16x32_bf16 v[56:59], v[92:95], v[120:123], v[56:59]
	v_mfma_f32_16x16x32_bf16 v[60:63], v[92:95], v[124:127], v[60:63]
	ds_read_b128 v[80:83], v253 offset:16384
	ds_read_b128 v[112:115], v255 offset:49152
	ds_read_b128 v[116:119], v255 offset:51200
	ds_read_b128 v[120:123], v255 offset:53248
	ds_read_b128 v[124:127], v255 offset:55296
	ds_read_b128 v[84:87], v253 offset:18432
	ds_read_b128 v[88:91], v253 offset:20480
	ds_read_b128 v[92:95], v253 offset:22528
	s_waitcnt lgkmcnt(14)
	v_mfma_f32_16x16x32_bf16 v[0:3], v[64:67], v[96:99], v[0:3]
	s_waitcnt lgkmcnt(13)
	v_mfma_f32_16x16x32_bf16 v[4:7], v[64:67], v[100:103], v[4:7]
	s_waitcnt lgkmcnt(12)
	v_mfma_f32_16x16x32_bf16 v[8:11], v[64:67], v[104:107], v[8:11]
	s_waitcnt lgkmcnt(11)
	v_mfma_f32_16x16x32_bf16 v[12:15], v[64:67], v[108:111], v[12:15]
	s_waitcnt lgkmcnt(10)
	v_mfma_f32_16x16x32_bf16 v[16:19], v[68:71], v[96:99], v[16:19]
	v_mfma_f32_16x16x32_bf16 v[20:23], v[68:71], v[100:103], v[20:23]
	v_mfma_f32_16x16x32_bf16 v[24:27], v[68:71], v[104:107], v[24:27]
	v_mfma_f32_16x16x32_bf16 v[28:31], v[68:71], v[108:111], v[28:31]
	s_waitcnt lgkmcnt(0)
	s_barrier
	v_mfma_f32_16x16x32_bf16 v[32:35], v[72:75], v[96:99], v[32:35]
	v_mfma_f32_16x16x32_bf16 v[36:39], v[72:75], v[100:103], v[36:39]
	v_mfma_f32_16x16x32_bf16 v[40:43], v[72:75], v[104:107], v[40:43]
	v_mfma_f32_16x16x32_bf16 v[44:47], v[72:75], v[108:111], v[44:47]
	v_mfma_f32_16x16x32_bf16 v[48:51], v[76:79], v[96:99], v[48:51]
	v_mfma_f32_16x16x32_bf16 v[52:55], v[76:79], v[100:103], v[52:55]
	v_mfma_f32_16x16x32_bf16 v[56:59], v[76:79], v[104:107], v[56:59]
	v_mfma_f32_16x16x32_bf16 v[60:63], v[76:79], v[108:111], v[60:63]
	v_mfma_f32_16x16x32_bf16 v[0:3], v[80:83], v[112:115], v[0:3]
	v_mfma_f32_16x16x32_bf16 v[4:7], v[80:83], v[116:119], v[4:7]
	v_mfma_f32_16x16x32_bf16 v[8:11], v[80:83], v[120:123], v[8:11]
	v_mfma_f32_16x16x32_bf16 v[12:15], v[80:83], v[124:127], v[12:15]
	v_mfma_f32_16x16x32_bf16 v[16:19], v[84:87], v[112:115], v[16:19]
	v_mfma_f32_16x16x32_bf16 v[20:23], v[84:87], v[116:119], v[20:23]
	v_mfma_f32_16x16x32_bf16 v[24:27], v[84:87], v[120:123], v[24:27]
	v_mfma_f32_16x16x32_bf16 v[28:31], v[84:87], v[124:127], v[28:31]
	v_mfma_f32_16x16x32_bf16 v[32:35], v[88:91], v[112:115], v[32:35]
	v_mfma_f32_16x16x32_bf16 v[36:39], v[88:91], v[116:119], v[36:39]
	v_mfma_f32_16x16x32_bf16 v[40:43], v[88:91], v[120:123], v[40:43]
	v_mfma_f32_16x16x32_bf16 v[44:47], v[88:91], v[124:127], v[44:47]
	v_mfma_f32_16x16x32_bf16 v[48:51], v[92:95], v[112:115], v[48:51]
	v_mfma_f32_16x16x32_bf16 v[52:55], v[92:95], v[116:119], v[52:55]
	v_mfma_f32_16x16x32_bf16 v[56:59], v[92:95], v[120:123], v[56:59]
	v_mfma_f32_16x16x32_bf16 v[60:63], v[92:95], v[124:127], v[60:63]
	s_nop 7
	s_nop 1
	s_mov_b64 s[18:19], s[20:21]
	v_add_f32_e32 v0, v0, v205
	v_add_f32_e32 v4, v4, v206
	v_add_f32_e32 v8, v8, v207
	v_add_f32_e32 v12, v12, v208
	v_fma_f32 v129, v201, v0, v129
	v_fma_f32 v130, v202, v4, v130
	v_fma_f32 v131, v203, v8, v131
	v_fma_f32 v132, v204, v12, v132
	global_store_dword v246, v129, s[18:19] offset:0 sc1
	global_store_dword v246, v130, s[18:19] offset:64 sc1
	global_store_dword v246, v131, s[18:19] offset:128 sc1
	global_store_dword v246, v132, s[18:19] offset:192 sc1
	s_add_u32 s18, s18, 0x1000
	s_addc_u32 s19, s19, 0
	v_add_f32_e32 v1, v1, v205
	v_add_f32_e32 v5, v5, v206
	v_add_f32_e32 v9, v9, v207
	v_add_f32_e32 v13, v13, v208
	v_fma_f32 v133, v201, v1, v133
	v_fma_f32 v134, v202, v5, v134
	v_fma_f32 v135, v203, v9, v135
	v_fma_f32 v136, v204, v13, v136
	global_store_dword v246, v133, s[18:19] offset:0 sc1
	global_store_dword v246, v134, s[18:19] offset:64 sc1
	global_store_dword v246, v135, s[18:19] offset:128 sc1
	global_store_dword v246, v136, s[18:19] offset:192 sc1
	s_add_u32 s18, s18, 0x1000
	s_addc_u32 s19, s19, 0
	v_add_f32_e32 v2, v2, v205
	v_add_f32_e32 v6, v6, v206
	v_add_f32_e32 v10, v10, v207
	v_add_f32_e32 v14, v14, v208
	v_fma_f32 v137, v201, v2, v137
	v_fma_f32 v138, v202, v6, v138
	v_fma_f32 v139, v203, v10, v139
	v_fma_f32 v140, v204, v14, v140
	global_store_dword v246, v137, s[18:19] offset:0 sc1
	global_store_dword v246, v138, s[18:19] offset:64 sc1
	global_store_dword v246, v139, s[18:19] offset:128 sc1
	global_store_dword v246, v140, s[18:19] offset:192 sc1
	s_add_u32 s18, s18, 0x1000
	s_addc_u32 s19, s19, 0
	v_add_f32_e32 v3, v3, v205
	v_add_f32_e32 v7, v7, v206
	v_add_f32_e32 v11, v11, v207
	v_add_f32_e32 v15, v15, v208
	v_fma_f32 v141, v201, v3, v141
	v_fma_f32 v142, v202, v7, v142
	v_fma_f32 v143, v203, v11, v143
	v_fma_f32 v144, v204, v15, v144
	global_store_dword v246, v141, s[18:19] offset:0 sc1
	global_store_dword v246, v142, s[18:19] offset:64 sc1
	global_store_dword v246, v143, s[18:19] offset:128 sc1
	global_store_dword v246, v144, s[18:19] offset:192 sc1
	s_add_u32 s18, s18, 0xd000
	s_addc_u32 s19, s19, 0
	v_add_f32_e32 v16, v16, v205
	v_add_f32_e32 v20, v20, v206
	v_add_f32_e32 v24, v24, v207
	v_add_f32_e32 v28, v28, v208
	v_fma_f32 v145, v201, v16, v145
	v_fma_f32 v146, v202, v20, v146
	v_fma_f32 v147, v203, v24, v147
	v_fma_f32 v148, v204, v28, v148
	global_store_dword v246, v145, s[18:19] offset:0 sc1
	global_store_dword v246, v146, s[18:19] offset:64 sc1
	global_store_dword v246, v147, s[18:19] offset:128 sc1
	global_store_dword v246, v148, s[18:19] offset:192 sc1
	s_add_u32 s18, s18, 0x1000
	s_addc_u32 s19, s19, 0
	v_add_f32_e32 v17, v17, v205
	v_add_f32_e32 v21, v21, v206
	v_add_f32_e32 v25, v25, v207
	v_add_f32_e32 v29, v29, v208
	v_fma_f32 v149, v201, v17, v149
	v_fma_f32 v150, v202, v21, v150
	v_fma_f32 v151, v203, v25, v151
	v_fma_f32 v152, v204, v29, v152
	global_store_dword v246, v149, s[18:19] offset:0 sc1
	global_store_dword v246, v150, s[18:19] offset:64 sc1
	global_store_dword v246, v151, s[18:19] offset:128 sc1
	global_store_dword v246, v152, s[18:19] offset:192 sc1
	s_add_u32 s18, s18, 0x1000
	s_addc_u32 s19, s19, 0
	v_add_f32_e32 v18, v18, v205
	v_add_f32_e32 v22, v22, v206
	v_add_f32_e32 v26, v26, v207
	v_add_f32_e32 v30, v30, v208
	v_fma_f32 v153, v201, v18, v153
	v_fma_f32 v154, v202, v22, v154
	v_fma_f32 v155, v203, v26, v155
	v_fma_f32 v156, v204, v30, v156
	global_store_dword v246, v153, s[18:19] offset:0 sc1
	global_store_dword v246, v154, s[18:19] offset:64 sc1
	global_store_dword v246, v155, s[18:19] offset:128 sc1
	global_store_dword v246, v156, s[18:19] offset:192 sc1
	s_add_u32 s18, s18, 0x1000
	s_addc_u32 s19, s19, 0
	v_add_f32_e32 v19, v19, v205
	v_add_f32_e32 v23, v23, v206
	v_add_f32_e32 v27, v27, v207
	v_add_f32_e32 v31, v31, v208
	v_fma_f32 v157, v201, v19, v157
	v_fma_f32 v158, v202, v23, v158
	v_fma_f32 v159, v203, v27, v159
	v_fma_f32 v160, v204, v31, v160
	global_store_dword v246, v157, s[18:19] offset:0 sc1
	global_store_dword v246, v158, s[18:19] offset:64 sc1
	global_store_dword v246, v159, s[18:19] offset:128 sc1
	global_store_dword v246, v160, s[18:19] offset:192 sc1
	s_add_u32 s18, s18, 0xd000
	s_addc_u32 s19, s19, 0
	v_add_f32_e32 v32, v32, v205
	v_add_f32_e32 v36, v36, v206
	v_add_f32_e32 v40, v40, v207
	v_add_f32_e32 v44, v44, v208
	v_fma_f32 v161, v201, v32, v161
	v_fma_f32 v170, v202, v36, v170
	v_fma_f32 v171, v203, v40, v171
	v_fma_f32 v172, v204, v44, v172
	global_store_dword v246, v161, s[18:19] offset:0 sc1
	global_store_dword v246, v170, s[18:19] offset:64 sc1
	global_store_dword v246, v171, s[18:19] offset:128 sc1
	global_store_dword v246, v172, s[18:19] offset:192 sc1
	s_add_u32 s18, s18, 0x1000
	s_addc_u32 s19, s19, 0
	v_add_f32_e32 v33, v33, v205
	v_add_f32_e32 v37, v37, v206
	v_add_f32_e32 v41, v41, v207
	v_add_f32_e32 v45, v45, v208
	v_fma_f32 v173, v201, v33, v173
	v_fma_f32 v174, v202, v37, v174
	v_fma_f32 v175, v203, v41, v175
	v_fma_f32 v176, v204, v45, v176
	global_store_dword v246, v173, s[18:19] offset:0 sc1
	global_store_dword v246, v174, s[18:19] offset:64 sc1
	global_store_dword v246, v175, s[18:19] offset:128 sc1
	global_store_dword v246, v176, s[18:19] offset:192 sc1
	s_add_u32 s18, s18, 0x1000
	s_addc_u32 s19, s19, 0
	v_add_f32_e32 v34, v34, v205
	v_add_f32_e32 v38, v38, v206
	v_add_f32_e32 v42, v42, v207
	v_add_f32_e32 v46, v46, v208
	v_fma_f32 v177, v201, v34, v177
	v_fma_f32 v178, v202, v38, v178
	v_fma_f32 v179, v203, v42, v179
	v_fma_f32 v180, v204, v46, v180
	global_store_dword v246, v177, s[18:19] offset:0 sc1
	global_store_dword v246, v178, s[18:19] offset:64 sc1
	global_store_dword v246, v179, s[18:19] offset:128 sc1
	global_store_dword v246, v180, s[18:19] offset:192 sc1
	s_add_u32 s18, s18, 0x1000
	s_addc_u32 s19, s19, 0
	v_add_f32_e32 v35, v35, v205
	v_add_f32_e32 v39, v39, v206
	v_add_f32_e32 v43, v43, v207
	v_add_f32_e32 v47, v47, v208
	v_fma_f32 v181, v201, v35, v181
	v_fma_f32 v182, v202, v39, v182
	v_fma_f32 v183, v203, v43, v183
	v_fma_f32 v184, v204, v47, v184
	global_store_dword v246, v181, s[18:19] offset:0 sc1
	global_store_dword v246, v182, s[18:19] offset:64 sc1
	global_store_dword v246, v183, s[18:19] offset:128 sc1
	global_store_dword v246, v184, s[18:19] offset:192 sc1
	s_add_u32 s18, s18, 0xd000
	s_addc_u32 s19, s19, 0
	v_add_f32_e32 v48, v48, v205
	v_add_f32_e32 v52, v52, v206
	v_add_f32_e32 v56, v56, v207
	v_add_f32_e32 v60, v60, v208
	v_fma_f32 v185, v201, v48, v185
	v_fma_f32 v186, v202, v52, v186
	v_fma_f32 v187, v203, v56, v187
	v_fma_f32 v188, v204, v60, v188
	global_store_dword v246, v185, s[18:19] offset:0 sc1
	global_store_dword v246, v186, s[18:19] offset:64 sc1
	global_store_dword v246, v187, s[18:19] offset:128 sc1
	global_store_dword v246, v188, s[18:19] offset:192 sc1
	s_add_u32 s18, s18, 0x1000
	s_addc_u32 s19, s19, 0
	v_add_f32_e32 v49, v49, v205
	v_add_f32_e32 v53, v53, v206
	v_add_f32_e32 v57, v57, v207
	v_add_f32_e32 v61, v61, v208
	v_fma_f32 v189, v201, v49, v189
	v_fma_f32 v190, v202, v53, v190
	v_fma_f32 v191, v203, v57, v191
	v_fma_f32 v192, v204, v61, v192
	global_store_dword v246, v189, s[18:19] offset:0 sc1
	global_store_dword v246, v190, s[18:19] offset:64 sc1
	global_store_dword v246, v191, s[18:19] offset:128 sc1
	global_store_dword v246, v192, s[18:19] offset:192 sc1
	s_add_u32 s18, s18, 0x1000
	s_addc_u32 s19, s19, 0
	v_add_f32_e32 v50, v50, v205
	v_add_f32_e32 v54, v54, v206
	v_add_f32_e32 v58, v58, v207
	v_add_f32_e32 v62, v62, v208
	v_fma_f32 v193, v201, v50, v193
	v_fma_f32 v194, v202, v54, v194
	v_fma_f32 v195, v203, v58, v195
	v_fma_f32 v196, v204, v62, v196
	global_store_dword v246, v193, s[18:19] offset:0 sc1
	global_store_dword v246, v194, s[18:19] offset:64 sc1
	global_store_dword v246, v195, s[18:19] offset:128 sc1
	global_store_dword v246, v196, s[18:19] offset:192 sc1
	s_add_u32 s18, s18, 0x1000
	s_addc_u32 s19, s19, 0
	v_add_f32_e32 v51, v51, v205
	v_add_f32_e32 v55, v55, v206
	v_add_f32_e32 v59, v59, v207
	v_add_f32_e32 v63, v63, v208
	v_fma_f32 v197, v201, v51, v197
	v_fma_f32 v198, v202, v55, v198
	v_fma_f32 v199, v203, v59, v199
	v_fma_f32 v200, v204, v63, v200
	global_store_dword v246, v197, s[18:19] offset:0 sc1
	global_store_dword v246, v198, s[18:19] offset:64 sc1
	global_store_dword v246, v199, s[18:19] offset:128 sc1
	global_store_dword v246, v200, s[18:19] offset:192 sc1
	s_add_u32 s15, s15, s16
	s_branch .Lr13_tile

.LBB0_1513:
	v_lshl_add_u64 v[16:17], s[14:15], 0, v[54:55]
	v_lshl_add_u64 v[4:5], s[14:15], 0, v[52:53]
	v_add_co_u32_e32 v8, vcc, 0x6b7a000, v16
	v_add_co_u32_e64 v66, s[4:5], s35, v4
	s_nop 0
	v_addc_co_u32_e32 v9, vcc, 0, v17, vcc
	v_addc_co_u32_e64 v67, s[4:5], 0, v5, s[4:5]
	v_add_u32_e32 v6, 0xfffff000, v40
	v_add_co_u32_e64 v68, s[4:5], s36, v4
	v_add_co_u32_e32 v12, vcc, s29, v16
	v_lshrrev_b32_e32 v6, 10, v6
	v_addc_co_u32_e64 v69, s[4:5], 0, v5, s[4:5]
	v_addc_co_u32_e32 v13, vcc, 0, v17, vcc
	v_add_u32_e32 v10, 11, v6
	v_cmp_lt_i32_e64 s[4:5], s3, v40
	v_add_co_u32_e32 v18, vcc, s30, v16
	global_load_dwordx4 v[0:3], v[44:45], off
	global_load_dwordx4 v[80:83], v[8:9], off offset:256 sc1
	global_load_dwordx4 v[36:39], v[8:9], off offset:1280 sc1
	global_load_dwordx4 v[20:23], v[8:9], off offset:2304 sc1
	global_load_dwordx4 v[4:7], v[8:9], off offset:3328 sc1
	v_cndmask_b32_e64 v14, 10, v10, s[4:5]
	v_addc_co_u32_e32 v19, vcc, 0, v17, vcc
	global_load_dwordx4 v[84:87], v[12:13], off offset:256 sc1
	global_load_dwordx4 v[88:91], v[12:13], off offset:1280 sc1
	global_load_dwordx4 v[24:27], v[12:13], off offset:2304 sc1
	global_load_dwordx4 v[8:11], v[12:13], off offset:3328 sc1
	v_mad_u64_u32 v[32:33], s[4:5], v14, s19, v[56:57]
	v_add_co_u32_e32 v108, vcc, s31, v16
	global_load_dwordx4 v[92:95], v[18:19], off offset:256 sc1
	global_load_dwordx4 v[96:99], v[18:19], off offset:1280 sc1
	global_load_dwordx4 v[28:31], v[18:19], off offset:2304 sc1
	global_load_dwordx4 v[12:15], v[18:19], off offset:3328 sc1
	v_lshl_add_u64 v[72:73], v[32:33], 0, s[26:27]
	v_lshl_add_u64 v[70:71], v[32:33], 0, v[42:43]
	v_addc_co_u32_e32 v109, vcc, 0, v17, vcc
	global_load_dwordx4 v[100:103], v[108:109], off offset:256 sc1
	global_load_dwordx4 v[104:107], v[108:109], off offset:1280 sc1
	global_load_dwordx4 v[32:35], v[108:109], off offset:2304 sc1
	global_load_dwordx4 v[16:19], v[108:109], off offset:3328 sc1
	v_lshl_add_u64 v[116:117], v[72:73], 0, v[42:43]
	global_load_dwordx4 v[108:111], v[70:71], off
	global_load_dwordx4 v[112:115], v[116:117], off
	v_lshl_add_u64 v[118:119], v[72:73], 0, v[58:59]
	v_add_u32_e32 v40, s18, v40
	v_lshl_add_u64 v[52:53], v[52:53], 0, s[20:21]
	v_lshl_add_u64 v[54:55], v[54:55], 0, s[22:23]
	s_waitcnt vmcnt(17)
	v_mov_b32_e32 v124, v81
	s_waitcnt vmcnt(16)
	v_mov_b32_e32 v125, v37
	v_mov_b32_e32 v122, v80
	v_mov_b32_e32 v123, v36
	s_waitcnt vmcnt(15)
	v_mov_b32_e32 v134, v21
	s_waitcnt vmcnt(14)
	v_mov_b32_e32 v135, v5
	v_pk_mul_f32 v[124:125], v[124:125], v[124:125]
	s_waitcnt vmcnt(13)
	v_mov_b32_e32 v142, v85
	s_waitcnt vmcnt(12)
	v_mov_b32_e32 v143, v89
	v_mov_b32_e32 v116, v82
	v_mov_b32_e32 v117, v38
	v_mov_b32_e32 v132, v20
	v_mov_b32_e32 v133, v4
	v_mov_b32_e32 v140, v84
	v_mov_b32_e32 v141, v88
	v_pk_mul_f32 v[134:135], v[134:135], v[134:135]
	s_waitcnt vmcnt(11)
	v_mov_b32_e32 v150, v25
	s_waitcnt vmcnt(10)
	v_mov_b32_e32 v151, v9
	v_pk_fma_f32 v[122:123], v[122:123], v[122:123], v[124:125]
	v_pk_mul_f32 v[124:125], v[142:143], v[142:143]
	s_waitcnt vmcnt(9)
	v_mov_b32_e32 v156, v93
	s_waitcnt vmcnt(8)
	v_mov_b32_e32 v157, v97
	v_mov_b32_e32 v120, v83
	v_mov_b32_e32 v121, v39
	v_mov_b32_e32 v126, v22
	v_mov_b32_e32 v127, v6
	v_mov_b32_e32 v136, v86
	v_mov_b32_e32 v137, v90
	v_mov_b32_e32 v148, v24
	v_mov_b32_e32 v149, v8
	v_mov_b32_e32 v154, v92
	v_mov_b32_e32 v155, v96
	v_pk_fma_f32 v[132:133], v[132:133], v[132:133], v[134:135]
	v_pk_mul_f32 v[134:135], v[150:151], v[150:151]
	s_waitcnt vmcnt(7)
	v_mov_b32_e32 v170, v29
	s_waitcnt vmcnt(6)
	v_mov_b32_e32 v171, v13
	v_pk_fma_f32 v[116:117], v[116:117], v[116:117], v[122:123]
	v_pk_fma_f32 v[122:123], v[140:141], v[140:141], v[124:125]
	v_pk_mul_f32 v[124:125], v[156:157], v[156:157]
	s_waitcnt vmcnt(5)
	v_mov_b32_e32 v174, v101
	s_waitcnt vmcnt(4)
	v_mov_b32_e32 v175, v105
	v_mov_b32_e32 v130, v23
	v_mov_b32_e32 v131, v7
	v_mov_b32_e32 v138, v87
	v_mov_b32_e32 v139, v91
	v_mov_b32_e32 v144, v26
	v_mov_b32_e32 v145, v10
	v_mov_b32_e32 v160, v28
	v_mov_b32_e32 v161, v12
	v_mov_b32_e32 v172, v100
	v_mov_b32_e32 v173, v104
	v_pk_fma_f32 v[126:127], v[126:127], v[126:127], v[132:133]
	v_pk_fma_f32 v[132:133], v[148:149], v[148:149], v[134:135]
	v_pk_mul_f32 v[134:135], v[170:171], v[170:171]
	s_waitcnt vmcnt(3)
	v_mov_b32_e32 v178, v33
	s_waitcnt vmcnt(2)
	v_mov_b32_e32 v179, v17
	s_waitcnt vmcnt(0)
	v_pk_add_f32 v[112:113], v[112:113], 1.0 op_sel_hi:[1,0]
	v_pk_fma_f32 v[116:117], v[120:121], v[120:121], v[116:117]
	v_pk_fma_f32 v[120:121], v[136:137], v[136:137], v[122:123]
	v_pk_fma_f32 v[122:123], v[154:155], v[154:155], v[124:125]
	v_pk_mul_f32 v[124:125], v[174:175], v[174:175]
	v_mov_b32_e32 v146, v27
	v_mov_b32_e32 v147, v11
	v_mov_b32_e32 v142, v94
	v_mov_b32_e32 v143, v98
	v_mov_b32_e32 v140, v102
	v_mov_b32_e32 v141, v106
	v_mov_b32_e32 v176, v32
	v_mov_b32_e32 v177, v16
	v_pk_add_f32 v[114:115], v[114:115], 1.0 op_sel_hi:[1,0]
	v_pk_fma_f32 v[126:127], v[130:131], v[130:131], v[126:127]
	v_pk_fma_f32 v[130:131], v[144:145], v[144:145], v[132:133]
	v_pk_fma_f32 v[132:133], v[160:161], v[160:161], v[134:135]
	v_pk_mul_f32 v[134:135], v[178:179], v[178:179]
	v_pk_mul_f32 v[0:1], v[0:1], v[112:113]
	v_pk_fma_f32 v[112:113], v[138:139], v[138:139], v[120:121]
	v_pk_fma_f32 v[120:121], v[172:173], v[172:173], v[124:125]
	v_mov_b32_e32 v152, v95
	v_mov_b32_e32 v153, v99
	v_mov_b32_e32 v150, v30
	v_mov_b32_e32 v151, v14
	v_mov_b32_e32 v156, v103
	v_mov_b32_e32 v157, v107
	v_mov_b32_e32 v148, v34
	v_mov_b32_e32 v149, v18
	v_pk_mul_f32 v[2:3], v[2:3], v[114:115]
	v_pk_fma_f32 v[114:115], v[142:143], v[142:143], v[122:123]
	v_pk_fma_f32 v[122:123], v[146:147], v[146:147], v[130:131]
	v_mov_b32_e32 v125, v116
	v_pk_fma_f32 v[134:135], v[176:177], v[176:177], v[134:135]
	v_pk_fma_f32 v[120:121], v[140:141], v[140:141], v[120:121]
	v_mov_b32_e32 v124, v112
	v_mov_b32_e32 v116, v113
	v_mov_b32_e32 v158, v31
	v_mov_b32_e32 v159, v15
	v_mov_b32_e32 v170, v35
	v_mov_b32_e32 v171, v19
	v_mov_b32_e32 v131, v126
	v_pk_fma_f32 v[132:133], v[150:151], v[150:151], v[132:133]
	v_pk_fma_f32 v[114:115], v[152:153], v[152:153], v[114:115]
	v_mov_b32_e32 v130, v122
	v_mov_b32_e32 v126, v123
	v_pk_fma_f32 v[122:123], v[148:149], v[148:149], v[134:135]
	v_pk_fma_f32 v[120:121], v[156:157], v[156:157], v[120:121]
	v_pk_add_f32 v[116:117], v[124:125], v[116:117]
	v_pk_fma_f32 v[112:113], v[158:159], v[158:159], v[132:133]
	v_pk_fma_f32 v[122:123], v[170:171], v[170:171], v[122:123]
	v_mov_b32_e32 v125, v114
	v_pk_add_f32 v[116:117], v[116:117], v[130:131]
	v_mov_b32_e32 v124, v120
	v_mov_b32_e32 v114, v121
	v_mov_b32_e32 v133, v112
	v_mov_b32_e32 v132, v122
	v_pk_add_f32 v[116:117], v[116:117], v[126:127]
	v_pk_add_f32 v[114:115], v[124:125], v[114:115]
	v_mov_b32_e32 v112, v123
	ds_bpermute_b32 v121, v74, v117
	ds_bpermute_b32 v120, v74, v116
	v_pk_add_f32 v[114:115], v[114:115], v[132:133]
	s_waitcnt lgkmcnt(0)
	v_pk_add_f32 v[116:117], v[116:117], v[120:121]
	v_pk_add_f32 v[112:113], v[114:115], v[112:113]
	ds_bpermute_b32 v115, v74, v113
	ds_bpermute_b32 v114, v74, v112
	ds_bpermute_b32 v121, v75, v117
	ds_bpermute_b32 v120, v75, v116
	s_waitcnt lgkmcnt(2)
	v_pk_add_f32 v[112:113], v[112:113], v[114:115]
	ds_bpermute_b32 v115, v75, v113
	ds_bpermute_b32 v114, v75, v112
	s_waitcnt lgkmcnt(2)
	v_pk_add_f32 v[116:117], v[116:117], v[120:121]
	ds_bpermute_b32 v121, v76, v117
	ds_bpermute_b32 v120, v76, v116
	s_waitcnt lgkmcnt(2)
	v_pk_add_f32 v[112:113], v[112:113], v[114:115]
	ds_bpermute_b32 v115, v76, v113
	ds_bpermute_b32 v114, v76, v112
	s_waitcnt lgkmcnt(2)
	v_pk_add_f32 v[116:117], v[116:117], v[120:121]
	ds_bpermute_b32 v121, v77, v117
	ds_bpermute_b32 v120, v77, v116
	s_waitcnt lgkmcnt(2)
	v_pk_add_f32 v[112:113], v[112:113], v[114:115]
	ds_bpermute_b32 v115, v77, v113
	ds_bpermute_b32 v114, v77, v112
	s_waitcnt lgkmcnt(2)
	v_pk_add_f32 v[116:117], v[116:117], v[120:121]
	ds_bpermute_b32 v121, v78, v117
	ds_bpermute_b32 v120, v78, v116
	s_waitcnt lgkmcnt(2)
	v_pk_add_f32 v[112:113], v[112:113], v[114:115]
	ds_bpermute_b32 v115, v78, v113
	ds_bpermute_b32 v114, v78, v112
	s_waitcnt lgkmcnt(2)
	v_pk_add_f32 v[116:117], v[116:117], v[120:121]
	ds_bpermute_b32 v121, v79, v117
	ds_bpermute_b32 v120, v79, v116
	s_waitcnt lgkmcnt(2)
	v_pk_add_f32 v[112:113], v[112:113], v[114:115]
	ds_bpermute_b32 v115, v79, v113
	ds_bpermute_b32 v114, v79, v112
	s_waitcnt lgkmcnt(2)
	v_pk_add_f32 v[116:117], v[116:117], v[120:121]
	s_waitcnt lgkmcnt(0)
	v_pk_add_f32 v[112:113], v[112:113], v[114:115]
	v_pk_fma_f32 v[116:117], v[116:117], s[28:29], v[64:65] op_sel_hi:[1,0,0]
	v_pk_fma_f32 v[112:113], v[112:113], s[28:29], v[64:65] op_sel_hi:[1,0,0]
	v_mul_f32_e32 v41, 0x4b800000, v117
	v_mul_f32_e32 v120, 0x4b800000, v116
	v_cmp_gt_f32_e32 vcc, s34, v116
	v_cmp_gt_f32_e64 s[4:5], s34, v117
	v_mul_f32_e32 v115, 0x4b800000, v113
	v_cndmask_b32_e32 v114, v116, v120, vcc
	v_cndmask_b32_e64 v41, v117, v41, s[4:5]
	v_rsq_f32_e32 v41, v41
	v_rsq_f32_e32 v114, v114
	v_mul_f32_e32 v116, 0x4b800000, v112
	v_cmp_gt_f32_e64 s[6:7], s34, v112
	v_cmp_gt_f32_e64 s[8:9], s34, v113
	s_nop 0
	v_cndmask_b32_e64 v112, v112, v116, s[6:7]
	v_cndmask_b32_e64 v113, v113, v115, s[8:9]
	v_rsq_f32_e32 v113, v113
	v_rsq_f32_e32 v115, v112
	v_mul_f32_e32 v112, 0x45800000, v41
	v_mul_f32_e32 v116, 0x45800000, v114
	v_cndmask_b32_e64 v112, v41, v112, s[4:5]
	v_cndmask_b32_e32 v114, v114, v116, vcc
	v_pk_mul_f32 v[80:81], v[80:81], v[112:113] op_sel_hi:[1,0]
	v_pk_mul_f32 v[82:83], v[82:83], v[112:113] op_sel_hi:[1,0]
	v_pk_mul_f32 v[84:85], v[84:85], v[114:115] op_sel_hi:[1,0]
	v_pk_mul_f32 v[86:87], v[86:87], v[114:115] op_sel_hi:[1,0]
	v_mul_f32_e32 v41, 0x45800000, v113
	v_mul_f32_e32 v117, 0x45800000, v115
	v_pk_fma_f32 v[80:81], v[80:81], v[0:1], v[108:109]
	v_pk_fma_f32 v[82:83], v[82:83], v[2:3], v[110:111]
	v_pk_fma_f32 v[84:85], v[84:85], v[0:1], v[108:109]
	v_pk_fma_f32 v[86:87], v[86:87], v[2:3], v[110:111]
	v_cndmask_b32_e64 v116, v113, v41, s[8:9]
	v_cndmask_b32_e64 v120, v115, v117, s[6:7]
	v_cvt_pk_bf16_f32 v80, v80, v81
	v_cvt_pk_bf16_f32 v81, v82, v83
	v_cvt_pk_bf16_f32 v82, v84, v85
	v_cvt_pk_bf16_f32 v83, v86, v87
	v_pk_mul_f32 v[84:85], v[92:93], v[116:117] op_sel_hi:[1,0]
	v_pk_mul_f32 v[86:87], v[94:95], v[116:117] op_sel_hi:[1,0]
	v_pk_mul_f32 v[92:93], v[100:101], v[120:121] op_sel_hi:[1,0]
	v_pk_mul_f32 v[94:95], v[102:103], v[120:121] op_sel_hi:[1,0]
	v_pk_fma_f32 v[84:85], v[84:85], v[0:1], v[108:109]
	v_pk_fma_f32 v[86:87], v[86:87], v[2:3], v[110:111]
	v_pk_fma_f32 v[0:1], v[92:93], v[0:1], v[108:109]
	v_pk_fma_f32 v[2:3], v[94:95], v[2:3], v[110:111]
	global_store_dwordx2 v[66:67], v[80:81], off offset:256
	global_store_dwordx2 v[66:67], v[82:83], off offset:2304
	v_cvt_pk_bf16_f32 v80, v84, v85
	v_cvt_pk_bf16_f32 v81, v86, v87
	v_cvt_pk_bf16_f32 v0, v0, v1
	v_cvt_pk_bf16_f32 v1, v2, v3
	global_store_dwordx2 v[68:69], v[80:81], off offset:256
	global_store_dwordx2 v[68:69], v[0:1], off offset:2304
	global_load_dwordx4 v[0:3], v[118:119], off
	s_nop 0
	global_load_dwordx4 v[80:83], v[70:71], off offset:1024
	global_load_dwordx4 v[84:87], v[46:47], off
	v_pk_mul_f32 v[36:37], v[36:37], v[112:113] op_sel_hi:[1,0]
	v_pk_mul_f32 v[38:39], v[38:39], v[112:113] op_sel_hi:[1,0]
	v_pk_mul_f32 v[88:89], v[88:89], v[114:115] op_sel_hi:[1,0]
	v_pk_mul_f32 v[90:91], v[90:91], v[114:115] op_sel_hi:[1,0]
	v_pk_mul_f32 v[94:95], v[96:97], v[116:117] op_sel_hi:[1,0]
	v_pk_mul_f32 v[96:97], v[98:99], v[116:117] op_sel_hi:[1,0]
	v_pk_mul_f32 v[98:99], v[104:105], v[120:121] op_sel_hi:[1,0]
	v_pk_mul_f32 v[100:101], v[106:107], v[120:121] op_sel_hi:[1,0]
	v_lshl_add_u64 v[92:93], v[72:73], 0, v[60:61]
	v_pk_mul_f32 v[20:21], v[20:21], v[112:113] op_sel_hi:[1,0]
	v_pk_mul_f32 v[22:23], v[22:23], v[112:113] op_sel_hi:[1,0]
	v_pk_mul_f32 v[24:25], v[24:25], v[114:115] op_sel_hi:[1,0]
	v_pk_mul_f32 v[26:27], v[26:27], v[114:115] op_sel_hi:[1,0]
	v_pk_mul_f32 v[28:29], v[28:29], v[116:117] op_sel_hi:[1,0]
	v_pk_mul_f32 v[30:31], v[30:31], v[116:117] op_sel_hi:[1,0]
	v_pk_mul_f32 v[32:33], v[32:33], v[120:121] op_sel_hi:[1,0]
	v_pk_mul_f32 v[34:35], v[34:35], v[120:121] op_sel_hi:[1,0]
	v_lshl_add_u64 v[72:73], v[72:73], 0, v[62:63]
	v_pk_mul_f32 v[4:5], v[4:5], v[112:113] op_sel_hi:[1,0]
	v_pk_mul_f32 v[6:7], v[6:7], v[112:113] op_sel_hi:[1,0]
	v_cmp_lt_i32_e32 vcc, s37, v40
	v_pk_mul_f32 v[8:9], v[8:9], v[114:115] op_sel_hi:[1,0]
	v_pk_mul_f32 v[10:11], v[10:11], v[114:115] op_sel_hi:[1,0]
	v_pk_mul_f32 v[12:13], v[12:13], v[116:117] op_sel_hi:[1,0]
	v_pk_mul_f32 v[14:15], v[14:15], v[116:117] op_sel_hi:[1,0]
	v_pk_mul_f32 v[16:17], v[16:17], v[120:121] op_sel_hi:[1,0]
	v_pk_mul_f32 v[18:19], v[18:19], v[120:121] op_sel_hi:[1,0]
	s_or_b64 s[24:25], vcc, s[24:25]
	s_waitcnt vmcnt(2)
	v_pk_add_f32 v[0:1], v[0:1], 1.0 op_sel_hi:[1,0]
	v_pk_add_f32 v[2:3], v[2:3], 1.0 op_sel_hi:[1,0]
	s_waitcnt vmcnt(0)
	v_pk_mul_f32 v[0:1], v[84:85], v[0:1]
	v_pk_mul_f32 v[2:3], v[86:87], v[2:3]
	v_pk_fma_f32 v[36:37], v[36:37], v[0:1], v[80:81]
	v_pk_fma_f32 v[38:39], v[38:39], v[2:3], v[82:83]
	v_pk_fma_f32 v[84:85], v[88:89], v[0:1], v[80:81]
	v_pk_fma_f32 v[86:87], v[90:91], v[2:3], v[82:83]
	v_pk_fma_f32 v[88:89], v[94:95], v[0:1], v[80:81]
	v_pk_fma_f32 v[90:91], v[96:97], v[2:3], v[82:83]
	v_pk_fma_f32 v[0:1], v[98:99], v[0:1], v[80:81]
	v_pk_fma_f32 v[2:3], v[100:101], v[2:3], v[82:83]
	v_cvt_pk_bf16_f32 v36, v36, v37
	v_cvt_pk_bf16_f32 v37, v38, v39
	v_cvt_pk_bf16_f32 v38, v84, v85
	v_cvt_pk_bf16_f32 v39, v86, v87
	v_cvt_pk_bf16_f32 v80, v88, v89
	v_cvt_pk_bf16_f32 v81, v90, v91
	v_cvt_pk_bf16_f32 v0, v0, v1
	v_cvt_pk_bf16_f32 v1, v2, v3
	global_store_dwordx2 v[66:67], v[36:37], off offset:768
	global_store_dwordx2 v[66:67], v[38:39], off offset:2816
	global_store_dwordx2 v[68:69], v[80:81], off offset:768
	global_store_dwordx2 v[68:69], v[0:1], off offset:2816
	global_load_dwordx4 v[0:3], v[92:93], off
	s_nop 0
	global_load_dwordx4 v[36:39], v[70:71], off offset:2048
	global_load_dwordx4 v[80:83], v[48:49], off
	s_waitcnt vmcnt(2)
	v_pk_add_f32 v[0:1], v[0:1], 1.0 op_sel_hi:[1,0]
	v_pk_add_f32 v[2:3], v[2:3], 1.0 op_sel_hi:[1,0]
	s_waitcnt vmcnt(0)
	v_pk_mul_f32 v[0:1], v[80:81], v[0:1]
	v_pk_mul_f32 v[2:3], v[82:83], v[2:3]
	v_pk_fma_f32 v[20:21], v[20:21], v[0:1], v[36:37]
	v_pk_fma_f32 v[22:23], v[22:23], v[2:3], v[38:39]
	v_pk_fma_f32 v[24:25], v[24:25], v[0:1], v[36:37]
	v_pk_fma_f32 v[26:27], v[26:27], v[2:3], v[38:39]
	v_pk_fma_f32 v[28:29], v[28:29], v[0:1], v[36:37]
	v_pk_fma_f32 v[30:31], v[30:31], v[2:3], v[38:39]
	v_pk_fma_f32 v[0:1], v[32:33], v[0:1], v[36:37]
	v_pk_fma_f32 v[2:3], v[34:35], v[2:3], v[38:39]
	v_cvt_pk_bf16_f32 v20, v20, v21
	v_cvt_pk_bf16_f32 v21, v22, v23
	v_cvt_pk_bf16_f32 v22, v24, v25
	v_cvt_pk_bf16_f32 v23, v26, v27
	v_cvt_pk_bf16_f32 v24, v28, v29
	v_cvt_pk_bf16_f32 v25, v30, v31
	v_cvt_pk_bf16_f32 v0, v0, v1
	v_cvt_pk_bf16_f32 v1, v2, v3
	global_store_dwordx2 v[66:67], v[20:21], off offset:1280
	global_store_dwordx2 v[66:67], v[22:23], off offset:3328
	global_store_dwordx2 v[68:69], v[24:25], off offset:1280
	global_store_dwordx2 v[68:69], v[0:1], off offset:3328
	global_load_dwordx4 v[0:3], v[72:73], off
	s_nop 0
	global_load_dwordx4 v[20:23], v[70:71], off offset:3072
	global_load_dwordx4 v[24:27], v[50:51], off
	s_waitcnt vmcnt(2)
	v_pk_add_f32 v[0:1], v[0:1], 1.0 op_sel_hi:[1,0]
	v_pk_add_f32 v[2:3], v[2:3], 1.0 op_sel_hi:[1,0]
	s_waitcnt vmcnt(0)
	v_pk_mul_f32 v[0:1], v[24:25], v[0:1]
	v_pk_mul_f32 v[2:3], v[26:27], v[2:3]
	v_pk_fma_f32 v[4:5], v[4:5], v[0:1], v[20:21]
	v_pk_fma_f32 v[6:7], v[6:7], v[2:3], v[22:23]
	v_pk_fma_f32 v[8:9], v[8:9], v[0:1], v[20:21]
	v_pk_fma_f32 v[10:11], v[10:11], v[2:3], v[22:23]
	v_pk_fma_f32 v[12:13], v[12:13], v[0:1], v[20:21]
	v_pk_fma_f32 v[14:15], v[14:15], v[2:3], v[22:23]
	v_pk_fma_f32 v[0:1], v[16:17], v[0:1], v[20:21]
	v_pk_fma_f32 v[2:3], v[18:19], v[2:3], v[22:23]
	v_cvt_pk_bf16_f32 v4, v4, v5
	v_cvt_pk_bf16_f32 v5, v6, v7
	v_cvt_pk_bf16_f32 v6, v8, v9
	v_cvt_pk_bf16_f32 v7, v10, v11
	v_cvt_pk_bf16_f32 v8, v12, v13
	v_cvt_pk_bf16_f32 v9, v14, v15
	v_cvt_pk_bf16_f32 v0, v0, v1
	v_cvt_pk_bf16_f32 v1, v2, v3
	global_store_dwordx2 v[66:67], v[4:5], off offset:1792
	global_store_dwordx2 v[66:67], v[6:7], off offset:3840
	global_store_dwordx2 v[68:69], v[8:9], off offset:1792
	global_store_dwordx2 v[68:69], v[0:1], off offset:3840
	s_andn2_b64 exec, exec, s[24:25]
	s_cbranch_execnz .LBB0_1513

.LBB0_2355:
	v_lshl_add_u64 v[16:17], s[12:13], 0, v[54:55]
	v_lshl_add_u64 v[4:5], s[12:13], 0, v[52:53]
	v_add_co_u32_e32 v8, vcc, 0x6b7a000, v16
	v_add_co_u32_e64 v66, s[4:5], s28, v4
	s_nop 0
	v_addc_co_u32_e32 v9, vcc, 0, v17, vcc
	v_addc_co_u32_e64 v67, s[4:5], 0, v5, s[4:5]
	v_add_u32_e32 v6, 0xfffff000, v40
	v_add_co_u32_e64 v68, s[4:5], s29, v4
	v_add_co_u32_e32 v12, vcc, s15, v16
	v_lshrrev_b32_e32 v6, 10, v6
	v_addc_co_u32_e64 v69, s[4:5], 0, v5, s[4:5]
	v_addc_co_u32_e32 v13, vcc, 0, v17, vcc
	v_add_u32_e32 v10, 11, v6
	v_cmp_lt_i32_e64 s[4:5], s2, v40
	v_add_co_u32_e32 v18, vcc, s25, v16
	global_load_dwordx4 v[0:3], v[44:45], off
	global_load_dwordx4 v[80:83], v[8:9], off offset:256 sc1
	global_load_dwordx4 v[36:39], v[8:9], off offset:1280 sc1
	global_load_dwordx4 v[20:23], v[8:9], off offset:2304 sc1
	global_load_dwordx4 v[4:7], v[8:9], off offset:3328 sc1
	v_cndmask_b32_e64 v14, 10, v10, s[4:5]
	v_addc_co_u32_e32 v19, vcc, 0, v17, vcc
	global_load_dwordx4 v[84:87], v[12:13], off offset:256 sc1
	global_load_dwordx4 v[88:91], v[12:13], off offset:1280 sc1
	global_load_dwordx4 v[24:27], v[12:13], off offset:2304 sc1
	global_load_dwordx4 v[8:11], v[12:13], off offset:3328 sc1
	v_mad_u64_u32 v[32:33], s[4:5], v14, s3, v[56:57]
	v_add_co_u32_e32 v108, vcc, s26, v16
	global_load_dwordx4 v[92:95], v[18:19], off offset:256 sc1
	global_load_dwordx4 v[96:99], v[18:19], off offset:1280 sc1
	global_load_dwordx4 v[28:31], v[18:19], off offset:2304 sc1
	global_load_dwordx4 v[12:15], v[18:19], off offset:3328 sc1
	v_lshl_add_u64 v[72:73], v[32:33], 0, s[22:23]
	v_lshl_add_u64 v[70:71], v[32:33], 0, v[42:43]
	v_addc_co_u32_e32 v109, vcc, 0, v17, vcc
	global_load_dwordx4 v[100:103], v[108:109], off offset:256 sc1
	global_load_dwordx4 v[104:107], v[108:109], off offset:1280 sc1
	global_load_dwordx4 v[32:35], v[108:109], off offset:2304 sc1
	global_load_dwordx4 v[16:19], v[108:109], off offset:3328 sc1
	v_lshl_add_u64 v[116:117], v[72:73], 0, v[42:43]
	global_load_dwordx4 v[108:111], v[70:71], off
	global_load_dwordx4 v[112:115], v[116:117], off
	v_lshl_add_u64 v[118:119], v[72:73], 0, v[58:59]
	v_add_u32_e32 v40, s14, v40
	v_lshl_add_u64 v[52:53], v[52:53], 0, s[16:17]
	v_lshl_add_u64 v[54:55], v[54:55], 0, s[18:19]
	s_waitcnt vmcnt(17)
	v_mov_b32_e32 v124, v81
	s_waitcnt vmcnt(16)
	v_mov_b32_e32 v125, v37
	v_mov_b32_e32 v122, v80
	v_mov_b32_e32 v123, v36
	s_waitcnt vmcnt(15)
	v_mov_b32_e32 v132, v21
	s_waitcnt vmcnt(14)
	v_mov_b32_e32 v133, v5
	v_pk_mul_f32 v[124:125], v[124:125], v[124:125]
	s_waitcnt vmcnt(13)
	v_mov_b32_e32 v140, v85
	s_waitcnt vmcnt(12)
	v_mov_b32_e32 v141, v89
	v_mov_b32_e32 v116, v82
	v_mov_b32_e32 v117, v38
	v_mov_b32_e32 v130, v20
	v_mov_b32_e32 v131, v4
	v_mov_b32_e32 v138, v84
	v_mov_b32_e32 v139, v88
	v_pk_mul_f32 v[132:133], v[132:133], v[132:133]
	s_waitcnt vmcnt(11)
	v_mov_b32_e32 v148, v25
	s_waitcnt vmcnt(10)
	v_mov_b32_e32 v149, v9
	v_pk_fma_f32 v[122:123], v[122:123], v[122:123], v[124:125]
	v_pk_mul_f32 v[124:125], v[140:141], v[140:141]
	s_waitcnt vmcnt(9)
	v_mov_b32_e32 v154, v93
	s_waitcnt vmcnt(8)
	v_mov_b32_e32 v155, v97
	v_mov_b32_e32 v120, v83
	v_mov_b32_e32 v121, v39
	v_mov_b32_e32 v126, v22
	v_mov_b32_e32 v127, v6
	v_mov_b32_e32 v134, v86
	v_mov_b32_e32 v135, v90
	v_mov_b32_e32 v146, v24
	v_mov_b32_e32 v147, v8
	v_mov_b32_e32 v152, v92
	v_mov_b32_e32 v153, v96
	v_pk_fma_f32 v[130:131], v[130:131], v[130:131], v[132:133]
	v_pk_mul_f32 v[132:133], v[148:149], v[148:149]
	s_waitcnt vmcnt(7)
	v_mov_b32_e32 v160, v29
	s_waitcnt vmcnt(6)
	v_mov_b32_e32 v161, v13
	v_pk_fma_f32 v[116:117], v[116:117], v[116:117], v[122:123]
	v_pk_fma_f32 v[122:123], v[138:139], v[138:139], v[124:125]
	v_pk_mul_f32 v[124:125], v[154:155], v[154:155]
	s_waitcnt vmcnt(5)
	v_mov_b32_e32 v166, v101
	s_waitcnt vmcnt(4)
	v_mov_b32_e32 v167, v105
	v_mov_b32_e32 v128, v23
	v_mov_b32_e32 v129, v7
	v_mov_b32_e32 v136, v87
	v_mov_b32_e32 v137, v91
	v_mov_b32_e32 v142, v26
	v_mov_b32_e32 v143, v10
	v_mov_b32_e32 v158, v28
	v_mov_b32_e32 v159, v12
	v_mov_b32_e32 v164, v100
	v_mov_b32_e32 v165, v104
	v_pk_fma_f32 v[126:127], v[126:127], v[126:127], v[130:131]
	v_pk_fma_f32 v[130:131], v[146:147], v[146:147], v[132:133]
	v_pk_mul_f32 v[132:133], v[160:161], v[160:161]
	s_waitcnt vmcnt(3)
	v_mov_b32_e32 v170, v33
	s_waitcnt vmcnt(2)
	v_mov_b32_e32 v171, v17
	s_waitcnt vmcnt(0)
	v_pk_add_f32 v[112:113], v[112:113], 1.0 op_sel_hi:[1,0]
	v_pk_fma_f32 v[116:117], v[120:121], v[120:121], v[116:117]
	v_pk_fma_f32 v[120:121], v[134:135], v[134:135], v[122:123]
	v_pk_fma_f32 v[122:123], v[152:153], v[152:153], v[124:125]
	v_pk_mul_f32 v[124:125], v[166:167], v[166:167]
	v_mov_b32_e32 v144, v27
	v_mov_b32_e32 v145, v11
	v_mov_b32_e32 v140, v94
	v_mov_b32_e32 v141, v98
	v_mov_b32_e32 v138, v102
	v_mov_b32_e32 v139, v106
	v_mov_b32_e32 v168, v32
	v_mov_b32_e32 v169, v16
	v_pk_add_f32 v[114:115], v[114:115], 1.0 op_sel_hi:[1,0]
	v_pk_fma_f32 v[126:127], v[128:129], v[128:129], v[126:127]
	v_pk_fma_f32 v[128:129], v[142:143], v[142:143], v[130:131]
	v_pk_fma_f32 v[130:131], v[158:159], v[158:159], v[132:133]
	v_pk_mul_f32 v[132:133], v[170:171], v[170:171]
	v_pk_mul_f32 v[0:1], v[0:1], v[112:113]
	v_pk_fma_f32 v[112:113], v[136:137], v[136:137], v[120:121]
	v_pk_fma_f32 v[120:121], v[164:165], v[164:165], v[124:125]
	v_mov_b32_e32 v150, v95
	v_mov_b32_e32 v151, v99
	v_mov_b32_e32 v148, v30
	v_mov_b32_e32 v149, v14
	v_mov_b32_e32 v154, v103
	v_mov_b32_e32 v155, v107
	v_mov_b32_e32 v146, v34
	v_mov_b32_e32 v147, v18
	v_pk_mul_f32 v[2:3], v[2:3], v[114:115]
	v_pk_fma_f32 v[114:115], v[140:141], v[140:141], v[122:123]
	v_pk_fma_f32 v[122:123], v[144:145], v[144:145], v[128:129]
	v_mov_b32_e32 v125, v116
	v_pk_fma_f32 v[132:133], v[168:169], v[168:169], v[132:133]
	v_pk_fma_f32 v[120:121], v[138:139], v[138:139], v[120:121]
	v_mov_b32_e32 v124, v112
	v_mov_b32_e32 v116, v113
	v_mov_b32_e32 v156, v31
	v_mov_b32_e32 v157, v15
	v_mov_b32_e32 v160, v35
	v_mov_b32_e32 v161, v19
	v_mov_b32_e32 v129, v126
	v_pk_fma_f32 v[130:131], v[148:149], v[148:149], v[130:131]
	v_pk_fma_f32 v[114:115], v[150:151], v[150:151], v[114:115]
	v_mov_b32_e32 v128, v122
	v_mov_b32_e32 v126, v123
	v_pk_fma_f32 v[122:123], v[146:147], v[146:147], v[132:133]
	v_pk_fma_f32 v[120:121], v[154:155], v[154:155], v[120:121]
	v_pk_add_f32 v[116:117], v[124:125], v[116:117]
	v_pk_fma_f32 v[112:113], v[156:157], v[156:157], v[130:131]
	v_pk_fma_f32 v[122:123], v[160:161], v[160:161], v[122:123]
	v_mov_b32_e32 v125, v114
	v_pk_add_f32 v[116:117], v[116:117], v[128:129]
	v_mov_b32_e32 v124, v120
	v_mov_b32_e32 v114, v121
	v_mov_b32_e32 v131, v112
	v_mov_b32_e32 v130, v122
	v_pk_add_f32 v[116:117], v[116:117], v[126:127]
	v_pk_add_f32 v[114:115], v[124:125], v[114:115]
	v_mov_b32_e32 v112, v123
	ds_bpermute_b32 v121, v74, v117
	ds_bpermute_b32 v120, v74, v116
	v_pk_add_f32 v[114:115], v[114:115], v[130:131]
	s_waitcnt lgkmcnt(0)
	v_pk_add_f32 v[116:117], v[116:117], v[120:121]
	v_pk_add_f32 v[112:113], v[114:115], v[112:113]
	ds_bpermute_b32 v115, v74, v113
	ds_bpermute_b32 v114, v74, v112
	ds_bpermute_b32 v121, v75, v117
	ds_bpermute_b32 v120, v75, v116
	s_waitcnt lgkmcnt(2)
	v_pk_add_f32 v[112:113], v[112:113], v[114:115]
	ds_bpermute_b32 v115, v75, v113
	ds_bpermute_b32 v114, v75, v112
	s_waitcnt lgkmcnt(2)
	v_pk_add_f32 v[116:117], v[116:117], v[120:121]
	ds_bpermute_b32 v121, v76, v117
	ds_bpermute_b32 v120, v76, v116
	s_waitcnt lgkmcnt(2)
	v_pk_add_f32 v[112:113], v[112:113], v[114:115]
	ds_bpermute_b32 v115, v76, v113
	ds_bpermute_b32 v114, v76, v112
	s_waitcnt lgkmcnt(2)
	v_pk_add_f32 v[116:117], v[116:117], v[120:121]
	ds_bpermute_b32 v121, v77, v117
	ds_bpermute_b32 v120, v77, v116
	s_waitcnt lgkmcnt(2)
	v_pk_add_f32 v[112:113], v[112:113], v[114:115]
	ds_bpermute_b32 v115, v77, v113
	ds_bpermute_b32 v114, v77, v112
	s_waitcnt lgkmcnt(2)
	v_pk_add_f32 v[116:117], v[116:117], v[120:121]
	ds_bpermute_b32 v121, v78, v117
	ds_bpermute_b32 v120, v78, v116
	s_waitcnt lgkmcnt(2)
	v_pk_add_f32 v[112:113], v[112:113], v[114:115]
	ds_bpermute_b32 v115, v78, v113
	ds_bpermute_b32 v114, v78, v112
	s_waitcnt lgkmcnt(2)
	v_pk_add_f32 v[116:117], v[116:117], v[120:121]
	ds_bpermute_b32 v121, v79, v117
	ds_bpermute_b32 v120, v79, v116
	s_waitcnt lgkmcnt(2)
	v_pk_add_f32 v[112:113], v[112:113], v[114:115]
	ds_bpermute_b32 v115, v79, v113
	ds_bpermute_b32 v114, v79, v112
	s_waitcnt lgkmcnt(2)
	v_pk_add_f32 v[116:117], v[116:117], v[120:121]
	s_waitcnt lgkmcnt(0)
	v_pk_add_f32 v[112:113], v[112:113], v[114:115]
	v_pk_fma_f32 v[116:117], v[116:117], s[24:25], v[64:65] op_sel_hi:[1,0,0]
	v_pk_fma_f32 v[112:113], v[112:113], s[24:25], v[64:65] op_sel_hi:[1,0,0]
	v_mul_f32_e32 v41, 0x4b800000, v117
	v_mul_f32_e32 v120, 0x4b800000, v116
	v_cmp_gt_f32_e32 vcc, s27, v116
	v_cmp_gt_f32_e64 s[4:5], s27, v117
	v_mul_f32_e32 v115, 0x4b800000, v113
	v_cndmask_b32_e32 v114, v116, v120, vcc
	v_cndmask_b32_e64 v41, v117, v41, s[4:5]
	v_rsq_f32_e32 v41, v41
	v_rsq_f32_e32 v114, v114
	v_mul_f32_e32 v116, 0x4b800000, v112
	v_cmp_gt_f32_e64 s[6:7], s27, v112
	v_cmp_gt_f32_e64 s[8:9], s27, v113
	s_nop 0
	v_cndmask_b32_e64 v112, v112, v116, s[6:7]
	v_cndmask_b32_e64 v113, v113, v115, s[8:9]
	v_rsq_f32_e32 v113, v113
	v_rsq_f32_e32 v115, v112
	v_mul_f32_e32 v112, 0x45800000, v41
	v_mul_f32_e32 v116, 0x45800000, v114
	v_cndmask_b32_e64 v112, v41, v112, s[4:5]
	v_cndmask_b32_e32 v114, v114, v116, vcc
	v_pk_mul_f32 v[80:81], v[80:81], v[112:113] op_sel_hi:[1,0]
	v_pk_mul_f32 v[82:83], v[82:83], v[112:113] op_sel_hi:[1,0]
	v_pk_mul_f32 v[84:85], v[84:85], v[114:115] op_sel_hi:[1,0]
	v_pk_mul_f32 v[86:87], v[86:87], v[114:115] op_sel_hi:[1,0]
	v_mul_f32_e32 v41, 0x45800000, v113
	v_mul_f32_e32 v117, 0x45800000, v115
	v_pk_fma_f32 v[80:81], v[80:81], v[0:1], v[108:109]
	v_pk_fma_f32 v[82:83], v[82:83], v[2:3], v[110:111]
	v_pk_fma_f32 v[84:85], v[84:85], v[0:1], v[108:109]
	v_pk_fma_f32 v[86:87], v[86:87], v[2:3], v[110:111]
	v_cndmask_b32_e64 v116, v113, v41, s[8:9]
	v_cndmask_b32_e64 v120, v115, v117, s[6:7]
	v_cvt_pk_bf16_f32 v80, v80, v81
	v_cvt_pk_bf16_f32 v81, v82, v83
	v_cvt_pk_bf16_f32 v82, v84, v85
	v_cvt_pk_bf16_f32 v83, v86, v87
	v_pk_mul_f32 v[84:85], v[92:93], v[116:117] op_sel_hi:[1,0]
	v_pk_mul_f32 v[86:87], v[94:95], v[116:117] op_sel_hi:[1,0]
	v_pk_mul_f32 v[92:93], v[100:101], v[120:121] op_sel_hi:[1,0]
	v_pk_mul_f32 v[94:95], v[102:103], v[120:121] op_sel_hi:[1,0]
	v_pk_fma_f32 v[84:85], v[84:85], v[0:1], v[108:109]
	v_pk_fma_f32 v[86:87], v[86:87], v[2:3], v[110:111]
	v_pk_fma_f32 v[0:1], v[92:93], v[0:1], v[108:109]
	v_pk_fma_f32 v[2:3], v[94:95], v[2:3], v[110:111]
	global_store_dwordx2 v[66:67], v[80:81], off offset:256
	global_store_dwordx2 v[66:67], v[82:83], off offset:2304
	v_cvt_pk_bf16_f32 v80, v84, v85
	v_cvt_pk_bf16_f32 v81, v86, v87
	v_cvt_pk_bf16_f32 v0, v0, v1
	v_cvt_pk_bf16_f32 v1, v2, v3
	global_store_dwordx2 v[68:69], v[80:81], off offset:256
	global_store_dwordx2 v[68:69], v[0:1], off offset:2304
	global_load_dwordx4 v[0:3], v[118:119], off
	s_nop 0
	global_load_dwordx4 v[80:83], v[70:71], off offset:1024
	global_load_dwordx4 v[84:87], v[46:47], off
	v_pk_mul_f32 v[36:37], v[36:37], v[112:113] op_sel_hi:[1,0]
	v_pk_mul_f32 v[38:39], v[38:39], v[112:113] op_sel_hi:[1,0]
	v_pk_mul_f32 v[88:89], v[88:89], v[114:115] op_sel_hi:[1,0]
	v_pk_mul_f32 v[90:91], v[90:91], v[114:115] op_sel_hi:[1,0]
	v_pk_mul_f32 v[94:95], v[96:97], v[116:117] op_sel_hi:[1,0]
	v_pk_mul_f32 v[96:97], v[98:99], v[116:117] op_sel_hi:[1,0]
	v_pk_mul_f32 v[98:99], v[104:105], v[120:121] op_sel_hi:[1,0]
	v_pk_mul_f32 v[100:101], v[106:107], v[120:121] op_sel_hi:[1,0]
	v_lshl_add_u64 v[92:93], v[72:73], 0, v[60:61]
	v_pk_mul_f32 v[20:21], v[20:21], v[112:113] op_sel_hi:[1,0]
	v_pk_mul_f32 v[22:23], v[22:23], v[112:113] op_sel_hi:[1,0]
	v_pk_mul_f32 v[24:25], v[24:25], v[114:115] op_sel_hi:[1,0]
	v_pk_mul_f32 v[26:27], v[26:27], v[114:115] op_sel_hi:[1,0]
	v_pk_mul_f32 v[28:29], v[28:29], v[116:117] op_sel_hi:[1,0]
	v_pk_mul_f32 v[30:31], v[30:31], v[116:117] op_sel_hi:[1,0]
	v_pk_mul_f32 v[32:33], v[32:33], v[120:121] op_sel_hi:[1,0]
	v_pk_mul_f32 v[34:35], v[34:35], v[120:121] op_sel_hi:[1,0]
	v_lshl_add_u64 v[72:73], v[72:73], 0, v[62:63]
	v_pk_mul_f32 v[4:5], v[4:5], v[112:113] op_sel_hi:[1,0]
	v_pk_mul_f32 v[6:7], v[6:7], v[112:113] op_sel_hi:[1,0]
	v_cmp_lt_i32_e32 vcc, s30, v40
	v_pk_mul_f32 v[8:9], v[8:9], v[114:115] op_sel_hi:[1,0]
	v_pk_mul_f32 v[10:11], v[10:11], v[114:115] op_sel_hi:[1,0]
	v_pk_mul_f32 v[12:13], v[12:13], v[116:117] op_sel_hi:[1,0]
	v_pk_mul_f32 v[14:15], v[14:15], v[116:117] op_sel_hi:[1,0]
	v_pk_mul_f32 v[16:17], v[16:17], v[120:121] op_sel_hi:[1,0]
	v_pk_mul_f32 v[18:19], v[18:19], v[120:121] op_sel_hi:[1,0]
	s_or_b64 s[20:21], vcc, s[20:21]
	s_waitcnt vmcnt(2)
	v_pk_add_f32 v[0:1], v[0:1], 1.0 op_sel_hi:[1,0]
	v_pk_add_f32 v[2:3], v[2:3], 1.0 op_sel_hi:[1,0]
	s_waitcnt vmcnt(0)
	v_pk_mul_f32 v[0:1], v[84:85], v[0:1]
	v_pk_mul_f32 v[2:3], v[86:87], v[2:3]
	v_pk_fma_f32 v[36:37], v[36:37], v[0:1], v[80:81]
	v_pk_fma_f32 v[38:39], v[38:39], v[2:3], v[82:83]
	v_pk_fma_f32 v[84:85], v[88:89], v[0:1], v[80:81]
	v_pk_fma_f32 v[86:87], v[90:91], v[2:3], v[82:83]
	v_pk_fma_f32 v[88:89], v[94:95], v[0:1], v[80:81]
	v_pk_fma_f32 v[90:91], v[96:97], v[2:3], v[82:83]
	v_pk_fma_f32 v[0:1], v[98:99], v[0:1], v[80:81]
	v_pk_fma_f32 v[2:3], v[100:101], v[2:3], v[82:83]
	v_cvt_pk_bf16_f32 v36, v36, v37
	v_cvt_pk_bf16_f32 v37, v38, v39
	v_cvt_pk_bf16_f32 v38, v84, v85
	v_cvt_pk_bf16_f32 v39, v86, v87
	v_cvt_pk_bf16_f32 v80, v88, v89
	v_cvt_pk_bf16_f32 v81, v90, v91
	v_cvt_pk_bf16_f32 v0, v0, v1
	v_cvt_pk_bf16_f32 v1, v2, v3
	global_store_dwordx2 v[66:67], v[36:37], off offset:768
	global_store_dwordx2 v[66:67], v[38:39], off offset:2816
	global_store_dwordx2 v[68:69], v[80:81], off offset:768
	global_store_dwordx2 v[68:69], v[0:1], off offset:2816
	global_load_dwordx4 v[0:3], v[92:93], off
	s_nop 0
	global_load_dwordx4 v[36:39], v[70:71], off offset:2048
	global_load_dwordx4 v[80:83], v[48:49], off
	s_waitcnt vmcnt(2)
	v_pk_add_f32 v[0:1], v[0:1], 1.0 op_sel_hi:[1,0]
	v_pk_add_f32 v[2:3], v[2:3], 1.0 op_sel_hi:[1,0]
	s_waitcnt vmcnt(0)
	v_pk_mul_f32 v[0:1], v[80:81], v[0:1]
	v_pk_mul_f32 v[2:3], v[82:83], v[2:3]
	v_pk_fma_f32 v[20:21], v[20:21], v[0:1], v[36:37]
	v_pk_fma_f32 v[22:23], v[22:23], v[2:3], v[38:39]
	v_pk_fma_f32 v[24:25], v[24:25], v[0:1], v[36:37]
	v_pk_fma_f32 v[26:27], v[26:27], v[2:3], v[38:39]
	v_pk_fma_f32 v[28:29], v[28:29], v[0:1], v[36:37]
	v_pk_fma_f32 v[30:31], v[30:31], v[2:3], v[38:39]
	v_pk_fma_f32 v[0:1], v[32:33], v[0:1], v[36:37]
	v_pk_fma_f32 v[2:3], v[34:35], v[2:3], v[38:39]
	v_cvt_pk_bf16_f32 v20, v20, v21
	v_cvt_pk_bf16_f32 v21, v22, v23
	v_cvt_pk_bf16_f32 v22, v24, v25
	v_cvt_pk_bf16_f32 v23, v26, v27
	v_cvt_pk_bf16_f32 v24, v28, v29
	v_cvt_pk_bf16_f32 v25, v30, v31
	v_cvt_pk_bf16_f32 v0, v0, v1
	v_cvt_pk_bf16_f32 v1, v2, v3
	global_store_dwordx2 v[66:67], v[20:21], off offset:1280
	global_store_dwordx2 v[66:67], v[22:23], off offset:3328
	global_store_dwordx2 v[68:69], v[24:25], off offset:1280
	global_store_dwordx2 v[68:69], v[0:1], off offset:3328
	global_load_dwordx4 v[0:3], v[72:73], off
	s_nop 0
	global_load_dwordx4 v[20:23], v[70:71], off offset:3072
	global_load_dwordx4 v[24:27], v[50:51], off
	s_waitcnt vmcnt(2)
	v_pk_add_f32 v[0:1], v[0:1], 1.0 op_sel_hi:[1,0]
	v_pk_add_f32 v[2:3], v[2:3], 1.0 op_sel_hi:[1,0]
	s_waitcnt vmcnt(0)
	v_pk_mul_f32 v[0:1], v[24:25], v[0:1]
	v_pk_mul_f32 v[2:3], v[26:27], v[2:3]
	v_pk_fma_f32 v[4:5], v[4:5], v[0:1], v[20:21]
	v_pk_fma_f32 v[6:7], v[6:7], v[2:3], v[22:23]
	v_pk_fma_f32 v[8:9], v[8:9], v[0:1], v[20:21]
	v_pk_fma_f32 v[10:11], v[10:11], v[2:3], v[22:23]
	v_pk_fma_f32 v[12:13], v[12:13], v[0:1], v[20:21]
	v_pk_fma_f32 v[14:15], v[14:15], v[2:3], v[22:23]
	v_pk_fma_f32 v[0:1], v[16:17], v[0:1], v[20:21]
	v_pk_fma_f32 v[2:3], v[18:19], v[2:3], v[22:23]
	v_cvt_pk_bf16_f32 v4, v4, v5
	v_cvt_pk_bf16_f32 v5, v6, v7
	v_cvt_pk_bf16_f32 v6, v8, v9
	v_cvt_pk_bf16_f32 v7, v10, v11
	v_cvt_pk_bf16_f32 v8, v12, v13
	v_cvt_pk_bf16_f32 v9, v14, v15
	v_cvt_pk_bf16_f32 v0, v0, v1
	v_cvt_pk_bf16_f32 v1, v2, v3
	global_store_dwordx2 v[66:67], v[4:5], off offset:1792
	global_store_dwordx2 v[66:67], v[6:7], off offset:3840
	global_store_dwordx2 v[68:69], v[8:9], off offset:1792
	global_store_dwordx2 v[68:69], v[0:1], off offset:3840
	s_andn2_b64 exec, exec, s[20:21]
	s_cbranch_execnz .LBB0_2355

.LBB0_2537:
	v_lshl_add_u64 v[16:17], s[12:13], 0, v[54:55]
	v_lshl_add_u64 v[4:5], s[12:13], 0, v[52:53]
	v_add_co_u32_e32 v8, vcc, 0x6b7a000, v16
	v_add_co_u32_e64 v66, s[4:5], s28, v4
	s_nop 0
	v_addc_co_u32_e32 v9, vcc, 0, v17, vcc
	v_addc_co_u32_e64 v67, s[4:5], 0, v5, s[4:5]
	v_add_u32_e32 v6, 0xfffff000, v40
	v_add_co_u32_e64 v68, s[4:5], s29, v4
	v_add_co_u32_e32 v12, vcc, s15, v16
	v_lshrrev_b32_e32 v6, 10, v6
	v_addc_co_u32_e64 v69, s[4:5], 0, v5, s[4:5]
	v_addc_co_u32_e32 v13, vcc, 0, v17, vcc
	v_add_u32_e32 v10, 16, v6
	v_cmp_lt_i32_e64 s[4:5], s2, v40
	v_add_co_u32_e32 v18, vcc, s25, v16
	global_load_dwordx4 v[0:3], v[44:45], off
	global_load_dwordx4 v[80:83], v[8:9], off offset:256 sc1
	global_load_dwordx4 v[36:39], v[8:9], off offset:1280 sc1
	global_load_dwordx4 v[20:23], v[8:9], off offset:2304 sc1
	global_load_dwordx4 v[4:7], v[8:9], off offset:3328 sc1
	v_cndmask_b32_e64 v14, 15, v10, s[4:5]
	v_addc_co_u32_e32 v19, vcc, 0, v17, vcc
	global_load_dwordx4 v[84:87], v[12:13], off offset:256 sc1
	global_load_dwordx4 v[88:91], v[12:13], off offset:1280 sc1
	global_load_dwordx4 v[24:27], v[12:13], off offset:2304 sc1
	global_load_dwordx4 v[8:11], v[12:13], off offset:3328 sc1
	v_mad_u64_u32 v[32:33], s[4:5], v14, s3, v[56:57]
	v_add_co_u32_e32 v108, vcc, s26, v16
	global_load_dwordx4 v[92:95], v[18:19], off offset:256 sc1
	global_load_dwordx4 v[96:99], v[18:19], off offset:1280 sc1
	global_load_dwordx4 v[28:31], v[18:19], off offset:2304 sc1
	global_load_dwordx4 v[12:15], v[18:19], off offset:3328 sc1
	v_lshl_add_u64 v[72:73], v[32:33], 0, s[22:23]
	v_lshl_add_u64 v[70:71], v[32:33], 0, v[42:43]
	v_addc_co_u32_e32 v109, vcc, 0, v17, vcc
	global_load_dwordx4 v[100:103], v[108:109], off offset:256 sc1
	global_load_dwordx4 v[104:107], v[108:109], off offset:1280 sc1
	global_load_dwordx4 v[32:35], v[108:109], off offset:2304 sc1
	global_load_dwordx4 v[16:19], v[108:109], off offset:3328 sc1
	v_lshl_add_u64 v[116:117], v[72:73], 0, v[42:43]
	global_load_dwordx4 v[108:111], v[70:71], off
	global_load_dwordx4 v[112:115], v[116:117], off
	v_lshl_add_u64 v[118:119], v[72:73], 0, v[58:59]
	v_add_u32_e32 v40, s14, v40
	v_lshl_add_u64 v[52:53], v[52:53], 0, s[16:17]
	v_lshl_add_u64 v[54:55], v[54:55], 0, s[18:19]
	s_waitcnt vmcnt(17)
	v_mov_b32_e32 v124, v81
	s_waitcnt vmcnt(16)
	v_mov_b32_e32 v125, v37
	v_mov_b32_e32 v122, v80
	v_mov_b32_e32 v123, v36
	s_waitcnt vmcnt(15)
	v_mov_b32_e32 v132, v21
	s_waitcnt vmcnt(14)
	v_mov_b32_e32 v133, v5
	v_pk_mul_f32 v[124:125], v[124:125], v[124:125]
	s_waitcnt vmcnt(13)
	v_mov_b32_e32 v140, v85
	s_waitcnt vmcnt(12)
	v_mov_b32_e32 v141, v89
	v_mov_b32_e32 v116, v82
	v_mov_b32_e32 v117, v38
	v_mov_b32_e32 v130, v20
	v_mov_b32_e32 v131, v4
	v_mov_b32_e32 v138, v84
	v_mov_b32_e32 v139, v88
	v_pk_mul_f32 v[132:133], v[132:133], v[132:133]
	s_waitcnt vmcnt(11)
	v_mov_b32_e32 v148, v25
	s_waitcnt vmcnt(10)
	v_mov_b32_e32 v149, v9
	v_pk_fma_f32 v[122:123], v[122:123], v[122:123], v[124:125]
	v_pk_mul_f32 v[124:125], v[140:141], v[140:141]
	s_waitcnt vmcnt(9)
	v_mov_b32_e32 v154, v93
	s_waitcnt vmcnt(8)
	v_mov_b32_e32 v155, v97
	v_mov_b32_e32 v120, v83
	v_mov_b32_e32 v121, v39
	v_mov_b32_e32 v126, v22
	v_mov_b32_e32 v127, v6
	v_mov_b32_e32 v134, v86
	v_mov_b32_e32 v135, v90
	v_mov_b32_e32 v146, v24
	v_mov_b32_e32 v147, v8
	v_mov_b32_e32 v152, v92
	v_mov_b32_e32 v153, v96
	v_pk_fma_f32 v[130:131], v[130:131], v[130:131], v[132:133]
	v_pk_mul_f32 v[132:133], v[148:149], v[148:149]
	s_waitcnt vmcnt(7)
	v_mov_b32_e32 v160, v29
	s_waitcnt vmcnt(6)
	v_mov_b32_e32 v161, v13
	v_pk_fma_f32 v[116:117], v[116:117], v[116:117], v[122:123]
	v_pk_fma_f32 v[122:123], v[138:139], v[138:139], v[124:125]
	v_pk_mul_f32 v[124:125], v[154:155], v[154:155]
	s_waitcnt vmcnt(5)
	v_mov_b32_e32 v166, v101
	s_waitcnt vmcnt(4)
	v_mov_b32_e32 v167, v105
	v_mov_b32_e32 v128, v23
	v_mov_b32_e32 v129, v7
	v_mov_b32_e32 v136, v87
	v_mov_b32_e32 v137, v91
	v_mov_b32_e32 v142, v26
	v_mov_b32_e32 v143, v10
	v_mov_b32_e32 v158, v28
	v_mov_b32_e32 v159, v12
	v_mov_b32_e32 v164, v100
	v_mov_b32_e32 v165, v104
	v_pk_fma_f32 v[126:127], v[126:127], v[126:127], v[130:131]
	v_pk_fma_f32 v[130:131], v[146:147], v[146:147], v[132:133]
	v_pk_mul_f32 v[132:133], v[160:161], v[160:161]
	s_waitcnt vmcnt(3)
	v_mov_b32_e32 v170, v33
	s_waitcnt vmcnt(2)
	v_mov_b32_e32 v171, v17
	s_waitcnt vmcnt(0)
	v_pk_add_f32 v[112:113], v[112:113], 1.0 op_sel_hi:[1,0]
	v_pk_fma_f32 v[116:117], v[120:121], v[120:121], v[116:117]
	v_pk_fma_f32 v[120:121], v[134:135], v[134:135], v[122:123]
	v_pk_fma_f32 v[122:123], v[152:153], v[152:153], v[124:125]
	v_pk_mul_f32 v[124:125], v[166:167], v[166:167]
	v_mov_b32_e32 v144, v27
	v_mov_b32_e32 v145, v11
	v_mov_b32_e32 v140, v94
	v_mov_b32_e32 v141, v98
	v_mov_b32_e32 v138, v102
	v_mov_b32_e32 v139, v106
	v_mov_b32_e32 v168, v32
	v_mov_b32_e32 v169, v16
	v_pk_add_f32 v[114:115], v[114:115], 1.0 op_sel_hi:[1,0]
	v_pk_fma_f32 v[126:127], v[128:129], v[128:129], v[126:127]
	v_pk_fma_f32 v[128:129], v[142:143], v[142:143], v[130:131]
	v_pk_fma_f32 v[130:131], v[158:159], v[158:159], v[132:133]
	v_pk_mul_f32 v[132:133], v[170:171], v[170:171]
	v_pk_mul_f32 v[0:1], v[0:1], v[112:113]
	v_pk_fma_f32 v[112:113], v[136:137], v[136:137], v[120:121]
	v_pk_fma_f32 v[120:121], v[164:165], v[164:165], v[124:125]
	v_mov_b32_e32 v150, v95
	v_mov_b32_e32 v151, v99
	v_mov_b32_e32 v148, v30
	v_mov_b32_e32 v149, v14
	v_mov_b32_e32 v154, v103
	v_mov_b32_e32 v155, v107
	v_mov_b32_e32 v146, v34
	v_mov_b32_e32 v147, v18
	v_pk_mul_f32 v[2:3], v[2:3], v[114:115]
	v_pk_fma_f32 v[114:115], v[140:141], v[140:141], v[122:123]
	v_pk_fma_f32 v[122:123], v[144:145], v[144:145], v[128:129]
	v_mov_b32_e32 v125, v116
	v_pk_fma_f32 v[132:133], v[168:169], v[168:169], v[132:133]
	v_pk_fma_f32 v[120:121], v[138:139], v[138:139], v[120:121]
	v_mov_b32_e32 v124, v112
	v_mov_b32_e32 v116, v113
	v_mov_b32_e32 v156, v31
	v_mov_b32_e32 v157, v15
	v_mov_b32_e32 v160, v35
	v_mov_b32_e32 v161, v19
	v_mov_b32_e32 v129, v126
	v_pk_fma_f32 v[130:131], v[148:149], v[148:149], v[130:131]
	v_pk_fma_f32 v[114:115], v[150:151], v[150:151], v[114:115]
	v_mov_b32_e32 v128, v122
	v_mov_b32_e32 v126, v123
	v_pk_fma_f32 v[122:123], v[146:147], v[146:147], v[132:133]
	v_pk_fma_f32 v[120:121], v[154:155], v[154:155], v[120:121]
	v_pk_add_f32 v[116:117], v[124:125], v[116:117]
	v_pk_fma_f32 v[112:113], v[156:157], v[156:157], v[130:131]
	v_pk_fma_f32 v[122:123], v[160:161], v[160:161], v[122:123]
	v_mov_b32_e32 v125, v114
	v_pk_add_f32 v[116:117], v[116:117], v[128:129]
	v_mov_b32_e32 v124, v120
	v_mov_b32_e32 v114, v121
	v_mov_b32_e32 v131, v112
	v_mov_b32_e32 v130, v122
	v_pk_add_f32 v[116:117], v[116:117], v[126:127]
	v_pk_add_f32 v[114:115], v[124:125], v[114:115]
	v_mov_b32_e32 v112, v123
	ds_bpermute_b32 v121, v74, v117
	ds_bpermute_b32 v120, v74, v116
	v_pk_add_f32 v[114:115], v[114:115], v[130:131]
	s_waitcnt lgkmcnt(0)
	v_pk_add_f32 v[116:117], v[116:117], v[120:121]
	v_pk_add_f32 v[112:113], v[114:115], v[112:113]
	ds_bpermute_b32 v115, v74, v113
	ds_bpermute_b32 v114, v74, v112
	ds_bpermute_b32 v121, v75, v117
	ds_bpermute_b32 v120, v75, v116
	s_waitcnt lgkmcnt(2)
	v_pk_add_f32 v[112:113], v[112:113], v[114:115]
	ds_bpermute_b32 v115, v75, v113
	ds_bpermute_b32 v114, v75, v112
	s_waitcnt lgkmcnt(2)
	v_pk_add_f32 v[116:117], v[116:117], v[120:121]
	ds_bpermute_b32 v121, v76, v117
	ds_bpermute_b32 v120, v76, v116
	s_waitcnt lgkmcnt(2)
	v_pk_add_f32 v[112:113], v[112:113], v[114:115]
	ds_bpermute_b32 v115, v76, v113
	ds_bpermute_b32 v114, v76, v112
	s_waitcnt lgkmcnt(2)
	v_pk_add_f32 v[116:117], v[116:117], v[120:121]
	ds_bpermute_b32 v121, v77, v117
	ds_bpermute_b32 v120, v77, v116
	s_waitcnt lgkmcnt(2)
	v_pk_add_f32 v[112:113], v[112:113], v[114:115]
	ds_bpermute_b32 v115, v77, v113
	ds_bpermute_b32 v114, v77, v112
	s_waitcnt lgkmcnt(2)
	v_pk_add_f32 v[116:117], v[116:117], v[120:121]
	ds_bpermute_b32 v121, v78, v117
	ds_bpermute_b32 v120, v78, v116
	s_waitcnt lgkmcnt(2)
	v_pk_add_f32 v[112:113], v[112:113], v[114:115]
	ds_bpermute_b32 v115, v78, v113
	ds_bpermute_b32 v114, v78, v112
	s_waitcnt lgkmcnt(2)
	v_pk_add_f32 v[116:117], v[116:117], v[120:121]
	ds_bpermute_b32 v121, v79, v117
	ds_bpermute_b32 v120, v79, v116
	s_waitcnt lgkmcnt(2)
	v_pk_add_f32 v[112:113], v[112:113], v[114:115]
	ds_bpermute_b32 v115, v79, v113
	ds_bpermute_b32 v114, v79, v112
	s_waitcnt lgkmcnt(2)
	v_pk_add_f32 v[116:117], v[116:117], v[120:121]
	s_waitcnt lgkmcnt(0)
	v_pk_add_f32 v[112:113], v[112:113], v[114:115]
	v_pk_fma_f32 v[116:117], v[116:117], s[24:25], v[64:65] op_sel_hi:[1,0,0]
	v_pk_fma_f32 v[112:113], v[112:113], s[24:25], v[64:65] op_sel_hi:[1,0,0]
	v_mul_f32_e32 v41, 0x4b800000, v117
	v_mul_f32_e32 v120, 0x4b800000, v116
	v_cmp_gt_f32_e32 vcc, s27, v116
	v_cmp_gt_f32_e64 s[4:5], s27, v117
	v_mul_f32_e32 v115, 0x4b800000, v113
	v_cndmask_b32_e32 v114, v116, v120, vcc
	v_cndmask_b32_e64 v41, v117, v41, s[4:5]
	v_rsq_f32_e32 v41, v41
	v_rsq_f32_e32 v114, v114
	v_mul_f32_e32 v116, 0x4b800000, v112
	v_cmp_gt_f32_e64 s[6:7], s27, v112
	v_cmp_gt_f32_e64 s[8:9], s27, v113
	s_nop 0
	v_cndmask_b32_e64 v112, v112, v116, s[6:7]
	v_cndmask_b32_e64 v113, v113, v115, s[8:9]
	v_rsq_f32_e32 v113, v113
	v_rsq_f32_e32 v115, v112
	v_mul_f32_e32 v112, 0x45800000, v41
	v_mul_f32_e32 v116, 0x45800000, v114
	v_cndmask_b32_e64 v112, v41, v112, s[4:5]
	v_cndmask_b32_e32 v114, v114, v116, vcc
	v_pk_mul_f32 v[80:81], v[80:81], v[112:113] op_sel_hi:[1,0]
	v_pk_mul_f32 v[82:83], v[82:83], v[112:113] op_sel_hi:[1,0]
	v_pk_mul_f32 v[84:85], v[84:85], v[114:115] op_sel_hi:[1,0]
	v_pk_mul_f32 v[86:87], v[86:87], v[114:115] op_sel_hi:[1,0]
	v_mul_f32_e32 v41, 0x45800000, v113
	v_mul_f32_e32 v117, 0x45800000, v115
	v_pk_fma_f32 v[80:81], v[80:81], v[0:1], v[108:109]
	v_pk_fma_f32 v[82:83], v[82:83], v[2:3], v[110:111]
	v_pk_fma_f32 v[84:85], v[84:85], v[0:1], v[108:109]
	v_pk_fma_f32 v[86:87], v[86:87], v[2:3], v[110:111]
	v_cndmask_b32_e64 v116, v113, v41, s[8:9]
	v_cndmask_b32_e64 v120, v115, v117, s[6:7]
	v_cvt_pk_bf16_f32 v80, v80, v81
	v_cvt_pk_bf16_f32 v81, v82, v83
	v_cvt_pk_bf16_f32 v82, v84, v85
	v_cvt_pk_bf16_f32 v83, v86, v87
	v_pk_mul_f32 v[84:85], v[92:93], v[116:117] op_sel_hi:[1,0]
	v_pk_mul_f32 v[86:87], v[94:95], v[116:117] op_sel_hi:[1,0]
	v_pk_mul_f32 v[92:93], v[100:101], v[120:121] op_sel_hi:[1,0]
	v_pk_mul_f32 v[94:95], v[102:103], v[120:121] op_sel_hi:[1,0]
	v_pk_fma_f32 v[84:85], v[84:85], v[0:1], v[108:109]
	v_pk_fma_f32 v[86:87], v[86:87], v[2:3], v[110:111]
	v_pk_fma_f32 v[0:1], v[92:93], v[0:1], v[108:109]
	v_pk_fma_f32 v[2:3], v[94:95], v[2:3], v[110:111]
	global_store_dwordx2 v[66:67], v[80:81], off offset:256
	global_store_dwordx2 v[66:67], v[82:83], off offset:2304
	v_cvt_pk_bf16_f32 v80, v84, v85
	v_cvt_pk_bf16_f32 v81, v86, v87
	v_cvt_pk_bf16_f32 v0, v0, v1
	v_cvt_pk_bf16_f32 v1, v2, v3
	global_store_dwordx2 v[68:69], v[80:81], off offset:256
	global_store_dwordx2 v[68:69], v[0:1], off offset:2304
	global_load_dwordx4 v[0:3], v[118:119], off
	s_nop 0
	global_load_dwordx4 v[80:83], v[70:71], off offset:1024
	global_load_dwordx4 v[84:87], v[46:47], off
	v_pk_mul_f32 v[36:37], v[36:37], v[112:113] op_sel_hi:[1,0]
	v_pk_mul_f32 v[38:39], v[38:39], v[112:113] op_sel_hi:[1,0]
	v_pk_mul_f32 v[88:89], v[88:89], v[114:115] op_sel_hi:[1,0]
	v_pk_mul_f32 v[90:91], v[90:91], v[114:115] op_sel_hi:[1,0]
	v_pk_mul_f32 v[94:95], v[96:97], v[116:117] op_sel_hi:[1,0]
	v_pk_mul_f32 v[96:97], v[98:99], v[116:117] op_sel_hi:[1,0]
	v_pk_mul_f32 v[98:99], v[104:105], v[120:121] op_sel_hi:[1,0]
	v_pk_mul_f32 v[100:101], v[106:107], v[120:121] op_sel_hi:[1,0]
	v_lshl_add_u64 v[92:93], v[72:73], 0, v[60:61]
	v_pk_mul_f32 v[20:21], v[20:21], v[112:113] op_sel_hi:[1,0]
	v_pk_mul_f32 v[22:23], v[22:23], v[112:113] op_sel_hi:[1,0]
	v_pk_mul_f32 v[24:25], v[24:25], v[114:115] op_sel_hi:[1,0]
	v_pk_mul_f32 v[26:27], v[26:27], v[114:115] op_sel_hi:[1,0]
	v_pk_mul_f32 v[28:29], v[28:29], v[116:117] op_sel_hi:[1,0]
	v_pk_mul_f32 v[30:31], v[30:31], v[116:117] op_sel_hi:[1,0]
	v_pk_mul_f32 v[32:33], v[32:33], v[120:121] op_sel_hi:[1,0]
	v_pk_mul_f32 v[34:35], v[34:35], v[120:121] op_sel_hi:[1,0]
	v_lshl_add_u64 v[72:73], v[72:73], 0, v[62:63]
	v_pk_mul_f32 v[4:5], v[4:5], v[112:113] op_sel_hi:[1,0]
	v_pk_mul_f32 v[6:7], v[6:7], v[112:113] op_sel_hi:[1,0]
	v_cmp_lt_i32_e32 vcc, s30, v40
	v_pk_mul_f32 v[8:9], v[8:9], v[114:115] op_sel_hi:[1,0]
	v_pk_mul_f32 v[10:11], v[10:11], v[114:115] op_sel_hi:[1,0]
	v_pk_mul_f32 v[12:13], v[12:13], v[116:117] op_sel_hi:[1,0]
	v_pk_mul_f32 v[14:15], v[14:15], v[116:117] op_sel_hi:[1,0]
	v_pk_mul_f32 v[16:17], v[16:17], v[120:121] op_sel_hi:[1,0]
	v_pk_mul_f32 v[18:19], v[18:19], v[120:121] op_sel_hi:[1,0]
	s_or_b64 s[20:21], vcc, s[20:21]
	s_waitcnt vmcnt(2)
	v_pk_add_f32 v[0:1], v[0:1], 1.0 op_sel_hi:[1,0]
	v_pk_add_f32 v[2:3], v[2:3], 1.0 op_sel_hi:[1,0]
	s_waitcnt vmcnt(0)
	v_pk_mul_f32 v[0:1], v[84:85], v[0:1]
	v_pk_mul_f32 v[2:3], v[86:87], v[2:3]
	v_pk_fma_f32 v[36:37], v[36:37], v[0:1], v[80:81]
	v_pk_fma_f32 v[38:39], v[38:39], v[2:3], v[82:83]
	v_pk_fma_f32 v[84:85], v[88:89], v[0:1], v[80:81]
	v_pk_fma_f32 v[86:87], v[90:91], v[2:3], v[82:83]
	v_pk_fma_f32 v[88:89], v[94:95], v[0:1], v[80:81]
	v_pk_fma_f32 v[90:91], v[96:97], v[2:3], v[82:83]
	v_pk_fma_f32 v[0:1], v[98:99], v[0:1], v[80:81]
	v_pk_fma_f32 v[2:3], v[100:101], v[2:3], v[82:83]
	v_cvt_pk_bf16_f32 v36, v36, v37
	v_cvt_pk_bf16_f32 v37, v38, v39
	v_cvt_pk_bf16_f32 v38, v84, v85
	v_cvt_pk_bf16_f32 v39, v86, v87
	v_cvt_pk_bf16_f32 v80, v88, v89
	v_cvt_pk_bf16_f32 v81, v90, v91
	v_cvt_pk_bf16_f32 v0, v0, v1
	v_cvt_pk_bf16_f32 v1, v2, v3
	global_store_dwordx2 v[66:67], v[36:37], off offset:768
	global_store_dwordx2 v[66:67], v[38:39], off offset:2816
	global_store_dwordx2 v[68:69], v[80:81], off offset:768
	global_store_dwordx2 v[68:69], v[0:1], off offset:2816
	global_load_dwordx4 v[0:3], v[92:93], off
	s_nop 0
	global_load_dwordx4 v[36:39], v[70:71], off offset:2048
	global_load_dwordx4 v[80:83], v[48:49], off
	s_waitcnt vmcnt(2)
	v_pk_add_f32 v[0:1], v[0:1], 1.0 op_sel_hi:[1,0]
	v_pk_add_f32 v[2:3], v[2:3], 1.0 op_sel_hi:[1,0]
	s_waitcnt vmcnt(0)
	v_pk_mul_f32 v[0:1], v[80:81], v[0:1]
	v_pk_mul_f32 v[2:3], v[82:83], v[2:3]
	v_pk_fma_f32 v[20:21], v[20:21], v[0:1], v[36:37]
	v_pk_fma_f32 v[22:23], v[22:23], v[2:3], v[38:39]
	v_pk_fma_f32 v[24:25], v[24:25], v[0:1], v[36:37]
	v_pk_fma_f32 v[26:27], v[26:27], v[2:3], v[38:39]
	v_pk_fma_f32 v[28:29], v[28:29], v[0:1], v[36:37]
	v_pk_fma_f32 v[30:31], v[30:31], v[2:3], v[38:39]
	v_pk_fma_f32 v[0:1], v[32:33], v[0:1], v[36:37]
	v_pk_fma_f32 v[2:3], v[34:35], v[2:3], v[38:39]
	v_cvt_pk_bf16_f32 v20, v20, v21
	v_cvt_pk_bf16_f32 v21, v22, v23
	v_cvt_pk_bf16_f32 v22, v24, v25
	v_cvt_pk_bf16_f32 v23, v26, v27
	v_cvt_pk_bf16_f32 v24, v28, v29
	v_cvt_pk_bf16_f32 v25, v30, v31
	v_cvt_pk_bf16_f32 v0, v0, v1
	v_cvt_pk_bf16_f32 v1, v2, v3
	global_store_dwordx2 v[66:67], v[20:21], off offset:1280
	global_store_dwordx2 v[66:67], v[22:23], off offset:3328
	global_store_dwordx2 v[68:69], v[24:25], off offset:1280
	global_store_dwordx2 v[68:69], v[0:1], off offset:3328
	global_load_dwordx4 v[0:3], v[72:73], off
	s_nop 0
	global_load_dwordx4 v[20:23], v[70:71], off offset:3072
	global_load_dwordx4 v[24:27], v[50:51], off
	s_waitcnt vmcnt(2)
	v_pk_add_f32 v[0:1], v[0:1], 1.0 op_sel_hi:[1,0]
	v_pk_add_f32 v[2:3], v[2:3], 1.0 op_sel_hi:[1,0]
	s_waitcnt vmcnt(0)
	v_pk_mul_f32 v[0:1], v[24:25], v[0:1]
	v_pk_mul_f32 v[2:3], v[26:27], v[2:3]
	v_pk_fma_f32 v[4:5], v[4:5], v[0:1], v[20:21]
	v_pk_fma_f32 v[6:7], v[6:7], v[2:3], v[22:23]
	v_pk_fma_f32 v[8:9], v[8:9], v[0:1], v[20:21]
	v_pk_fma_f32 v[10:11], v[10:11], v[2:3], v[22:23]
	v_pk_fma_f32 v[12:13], v[12:13], v[0:1], v[20:21]
	v_pk_fma_f32 v[14:15], v[14:15], v[2:3], v[22:23]
	v_pk_fma_f32 v[0:1], v[16:17], v[0:1], v[20:21]
	v_pk_fma_f32 v[2:3], v[18:19], v[2:3], v[22:23]
	v_cvt_pk_bf16_f32 v4, v4, v5
	v_cvt_pk_bf16_f32 v5, v6, v7
	v_cvt_pk_bf16_f32 v6, v8, v9
	v_cvt_pk_bf16_f32 v7, v10, v11
	v_cvt_pk_bf16_f32 v8, v12, v13
	v_cvt_pk_bf16_f32 v9, v14, v15
	v_cvt_pk_bf16_f32 v0, v0, v1
	v_cvt_pk_bf16_f32 v1, v2, v3
	global_store_dwordx2 v[66:67], v[4:5], off offset:1792
	global_store_dwordx2 v[66:67], v[6:7], off offset:3840
	global_store_dwordx2 v[68:69], v[8:9], off offset:1792
	global_store_dwordx2 v[68:69], v[0:1], off offset:3840
	s_andn2_b64 exec, exec, s[20:21]
	s_cbranch_execnz .LBB0_2537

.LBB0_2972:
	v_lshl_add_u64 v[16:17], v[40:41], 0, v[34:35]
	v_add_co_u32_e64 v18, s[2:3], s11, v16
	v_add_co_u32_e32 v46, vcc, 0x6b7a000, v16
	s_nop 0
	v_addc_co_u32_e64 v19, s[2:3], 0, v17, s[2:3]
	v_add_co_u32_e64 v82, s[2:3], s19, v16
	v_addc_co_u32_e32 v47, vcc, 0, v17, vcc
	s_nop 0
	v_addc_co_u32_e64 v83, s[2:3], 0, v17, s[2:3]
	s_waitcnt vmcnt(2)
	v_add_co_u32_e64 v84, s[2:3], s20, v16
	global_load_dwordx4 v[0:3], v[36:37], off
	s_nop 0
	v_addc_co_u32_e64 v85, s[2:3], 0, v17, s[2:3]
	global_load_dwordx4 v[58:61], v[18:19], off offset:256 sc1
	global_load_dwordx4 v[62:65], v[18:19], off offset:1280 sc1
	global_load_dwordx4 v[20:23], v[18:19], off offset:2304 sc1
	global_load_dwordx4 v[4:7], v[18:19], off offset:3328 sc1
	global_load_dwordx4 v[66:69], v[82:83], off offset:256 sc1
	global_load_dwordx4 v[70:73], v[82:83], off offset:1280 sc1
	global_load_dwordx4 v[24:27], v[82:83], off offset:2304 sc1
	global_load_dwordx4 v[8:11], v[82:83], off offset:3328 sc1
	global_load_dwordx4 v[74:77], v[84:85], off offset:256 sc1
	global_load_dwordx4 v[78:81], v[84:85], off offset:1280 sc1
	global_load_dwordx4 v[28:31], v[84:85], off offset:2304 sc1
	global_load_dwordx4 v[12:15], v[84:85], off offset:3328 sc1
	s_nop 0
	global_load_dwordx4 v[82:85], v[46:47], off offset:256 sc1
	global_load_dwordx4 v[86:89], v[46:47], off offset:1280 sc1
	global_load_dwordx4 v[90:93], v[46:47], off offset:2304 sc1
	global_load_dwordx4 v[16:19], v[46:47], off offset:3328 sc1
	v_lshl_add_u64 v[44:45], v[38:39], 0, v[34:35]
	v_add_co_u32_e64 v48, s[2:3], s17, v44
	v_add_u32_e32 v32, s10, v32
	s_nop 0
	v_addc_co_u32_e64 v49, s[2:3], 0, v45, s[2:3]
	v_add_co_u32_e64 v50, s[2:3], s22, v44
	v_lshl_add_u64 v[38:39], v[38:39], 0, s[12:13]
	s_nop 0
	v_addc_co_u32_e64 v51, s[2:3], 0, v45, s[2:3]
	v_lshl_add_u64 v[40:41], v[40:41], 0, s[12:13]
	s_waitcnt vmcnt(15)
	v_mov_b32_e32 v94, v59
	s_waitcnt vmcnt(14)
	v_mov_b32_e32 v95, v63
	s_waitcnt vmcnt(13)
	v_mov_b32_e32 v102, v21
	s_waitcnt vmcnt(12)
	v_mov_b32_e32 v103, v5
	s_waitcnt vmcnt(11)
	v_mov_b32_e32 v110, v67
	s_waitcnt vmcnt(10)
	v_mov_b32_e32 v111, v71
	s_waitcnt vmcnt(9)
	v_mov_b32_e32 v118, v25
	s_waitcnt vmcnt(8)
	v_mov_b32_e32 v119, v9
	s_waitcnt vmcnt(7)
	v_mov_b32_e32 v126, v75
	s_waitcnt vmcnt(6)
	v_mov_b32_e32 v127, v79
	v_mov_b32_e32 v46, v58
	v_mov_b32_e32 v47, v62
	v_mov_b32_e32 v100, v20
	v_mov_b32_e32 v101, v4
	v_mov_b32_e32 v108, v66
	v_mov_b32_e32 v109, v70
	v_mov_b32_e32 v116, v24
	v_mov_b32_e32 v117, v8
	v_mov_b32_e32 v124, v74
	v_mov_b32_e32 v125, v78
	s_waitcnt vmcnt(5)
	v_mov_b32_e32 v134, v29
	s_waitcnt vmcnt(4)
	v_mov_b32_e32 v135, v13
	s_waitcnt vmcnt(3)
	v_mov_b32_e32 v142, v83
	s_waitcnt vmcnt(2)
	v_mov_b32_e32 v143, v87
	s_waitcnt vmcnt(1)
	v_mov_b32_e32 v150, v91
	s_waitcnt vmcnt(0)
	v_mov_b32_e32 v151, v17
	v_pk_mul_f32 v[94:95], v[94:95], v[94:95]
	v_pk_mul_f32 v[102:103], v[102:103], v[102:103]
	v_pk_mul_f32 v[110:111], v[110:111], v[110:111]
	v_pk_mul_f32 v[118:119], v[118:119], v[118:119]
	v_pk_mul_f32 v[126:127], v[126:127], v[126:127]
	v_mov_b32_e32 v96, v60
	v_mov_b32_e32 v97, v64
	v_mov_b32_e32 v112, v68
	v_mov_b32_e32 v113, v72
	v_mov_b32_e32 v120, v26
	v_mov_b32_e32 v121, v10
	v_mov_b32_e32 v128, v76
	v_mov_b32_e32 v129, v80
	v_mov_b32_e32 v132, v28
	v_mov_b32_e32 v133, v12
	v_mov_b32_e32 v140, v82
	v_mov_b32_e32 v141, v86
	v_mov_b32_e32 v148, v90
	v_mov_b32_e32 v149, v16
	v_pk_mul_f32 v[134:135], v[134:135], v[134:135]
	v_pk_mul_f32 v[142:143], v[142:143], v[142:143]
	v_pk_mul_f32 v[150:151], v[150:151], v[150:151]
	v_pk_fma_f32 v[46:47], v[46:47], v[46:47], v[94:95]
	v_pk_fma_f32 v[94:95], v[100:101], v[100:101], v[102:103]
	v_pk_fma_f32 v[100:101], v[108:109], v[108:109], v[110:111]
	v_pk_fma_f32 v[102:103], v[116:117], v[116:117], v[118:119]
	v_pk_fma_f32 v[108:109], v[124:125], v[124:125], v[126:127]
	v_mov_b32_e32 v98, v61
	v_mov_b32_e32 v99, v65
	v_mov_b32_e32 v104, v22
	v_mov_b32_e32 v105, v6
	v_mov_b32_e32 v114, v69
	v_mov_b32_e32 v115, v73
	v_mov_b32_e32 v122, v27
	v_mov_b32_e32 v123, v11
	v_mov_b32_e32 v130, v77
	v_mov_b32_e32 v131, v81
	v_mov_b32_e32 v136, v30
	v_mov_b32_e32 v137, v14
	v_mov_b32_e32 v144, v84
	v_mov_b32_e32 v145, v88
	v_mov_b32_e32 v152, v92
	v_mov_b32_e32 v153, v18
	v_pk_fma_f32 v[110:111], v[132:133], v[132:133], v[134:135]
	v_pk_fma_f32 v[116:117], v[140:141], v[140:141], v[142:143]
	v_pk_fma_f32 v[118:119], v[148:149], v[148:149], v[150:151]
	v_pk_fma_f32 v[46:47], v[96:97], v[96:97], v[46:47]
	v_pk_fma_f32 v[96:97], v[112:113], v[112:113], v[100:101]
	v_pk_fma_f32 v[100:101], v[120:121], v[120:121], v[102:103]
	v_pk_fma_f32 v[102:103], v[128:129], v[128:129], v[108:109]
	v_mov_b32_e32 v106, v23
	v_mov_b32_e32 v107, v7
	v_mov_b32_e32 v138, v31
	v_mov_b32_e32 v139, v15
	v_mov_b32_e32 v146, v85
	v_mov_b32_e32 v147, v89
	v_mov_b32_e32 v154, v93
	v_mov_b32_e32 v155, v19
	v_pk_fma_f32 v[94:95], v[104:105], v[104:105], v[94:95]
	v_pk_fma_f32 v[104:105], v[136:137], v[136:137], v[110:111]
	v_pk_fma_f32 v[108:109], v[144:145], v[144:145], v[116:117]
	v_pk_fma_f32 v[110:111], v[152:153], v[152:153], v[118:119]
	v_pk_fma_f32 v[46:47], v[98:99], v[98:99], v[46:47]
	v_pk_fma_f32 v[96:97], v[114:115], v[114:115], v[96:97]
	v_pk_fma_f32 v[98:99], v[122:123], v[122:123], v[100:101]
	v_pk_fma_f32 v[100:101], v[130:131], v[130:131], v[102:103]
	v_pk_fma_f32 v[94:95], v[106:107], v[106:107], v[94:95]
	v_pk_fma_f32 v[102:103], v[138:139], v[138:139], v[104:105]
	v_pk_fma_f32 v[104:105], v[146:147], v[146:147], v[108:109]
	v_pk_fma_f32 v[106:107], v[154:155], v[154:155], v[110:111]
	v_mov_b32_e32 v110, v100
	v_mov_b32_e32 v111, v96
	v_mov_b32_e32 v96, v101
	v_mov_b32_e32 v108, v46
	v_mov_b32_e32 v46, v94
	v_mov_b32_e32 v100, v102
	v_mov_b32_e32 v101, v98
	v_mov_b32_e32 v109, v104
	v_mov_b32_e32 v104, v47
	v_mov_b32_e32 v47, v106
	v_mov_b32_e32 v106, v95
	v_pk_add_f32 v[94:95], v[110:111], v[96:97]
	v_mov_b32_e32 v98, v103
	v_pk_add_f32 v[96:97], v[108:109], v[104:105]
	v_pk_add_f32 v[94:95], v[94:95], v[100:101]
	v_pk_add_f32 v[46:47], v[96:97], v[46:47]
	v_pk_add_f32 v[94:95], v[94:95], v[98:99]
	v_pk_add_f32 v[46:47], v[46:47], v[106:107]
	ds_bpermute_b32 v97, v52, v95
	ds_bpermute_b32 v96, v52, v94
	ds_bpermute_b32 v99, v52, v47
	ds_bpermute_b32 v98, v52, v46
	s_waitcnt lgkmcnt(2)
	v_pk_add_f32 v[94:95], v[94:95], v[96:97]
	ds_bpermute_b32 v97, v53, v95
	s_waitcnt lgkmcnt(1)
	v_pk_add_f32 v[46:47], v[46:47], v[98:99]
	ds_bpermute_b32 v96, v53, v94
	ds_bpermute_b32 v99, v53, v47
	ds_bpermute_b32 v98, v53, v46
	s_waitcnt lgkmcnt(2)
	v_pk_add_f32 v[94:95], v[94:95], v[96:97]
	ds_bpermute_b32 v97, v54, v95
	s_waitcnt lgkmcnt(1)
	v_pk_add_f32 v[46:47], v[46:47], v[98:99]
	ds_bpermute_b32 v96, v54, v94
	ds_bpermute_b32 v99, v54, v47
	ds_bpermute_b32 v98, v54, v46
	s_waitcnt lgkmcnt(2)
	v_pk_add_f32 v[94:95], v[94:95], v[96:97]
	ds_bpermute_b32 v97, v55, v95
	s_waitcnt lgkmcnt(1)
	v_pk_add_f32 v[46:47], v[46:47], v[98:99]
	ds_bpermute_b32 v96, v55, v94
	ds_bpermute_b32 v99, v55, v47
	ds_bpermute_b32 v98, v55, v46
	s_waitcnt lgkmcnt(2)
	v_pk_add_f32 v[94:95], v[94:95], v[96:97]
	ds_bpermute_b32 v97, v56, v95
	s_waitcnt lgkmcnt(1)
	v_pk_add_f32 v[46:47], v[46:47], v[98:99]
	ds_bpermute_b32 v96, v56, v94
	ds_bpermute_b32 v99, v56, v47
	ds_bpermute_b32 v98, v56, v46
	s_waitcnt lgkmcnt(2)
	v_pk_add_f32 v[94:95], v[94:95], v[96:97]
	ds_bpermute_b32 v97, v57, v95
	s_waitcnt lgkmcnt(1)
	v_pk_add_f32 v[46:47], v[46:47], v[98:99]
	ds_bpermute_b32 v96, v57, v94
	ds_bpermute_b32 v99, v57, v47
	ds_bpermute_b32 v98, v57, v46
	s_waitcnt lgkmcnt(2)
	v_pk_add_f32 v[94:95], v[94:95], v[96:97]
	s_nop 0
	v_pk_fma_f32 v[94:95], v[94:95], s[16:17], v[42:43] op_sel_hi:[1,0,0]
	s_waitcnt lgkmcnt(0)
	v_pk_add_f32 v[46:47], v[46:47], v[98:99]
	v_mul_f32_e32 v33, 0x4b800000, v95
	v_pk_fma_f32 v[46:47], v[46:47], s[16:17], v[42:43] op_sel_hi:[1,0,0]
	v_cmp_gt_f32_e64 s[2:3], s18, v95
	v_mul_f32_e32 v96, 0x4b800000, v94
	v_cmp_gt_f32_e32 vcc, s18, v94
	v_mul_f32_e32 v97, 0x4b800000, v47
	v_mul_f32_e32 v98, 0x4b800000, v46
	v_cmp_gt_f32_e64 s[4:5], s18, v46
	v_cndmask_b32_e64 v33, v95, v33, s[2:3]
	v_cmp_gt_f32_e64 s[6:7], s18, v47
	v_cndmask_b32_e32 v94, v94, v96, vcc
	v_cndmask_b32_e64 v46, v46, v98, s[4:5]
	v_cndmask_b32_e64 v47, v47, v97, s[6:7]
	v_rsq_f32_e32 v33, v33
	v_rsq_f32_e32 v94, v94
	v_rsq_f32_e32 v47, v47
	v_rsq_f32_e32 v95, v46
	v_mul_f32_e32 v46, 0x45800000, v33
	v_mul_f32_e32 v96, 0x45800000, v94
	v_mul_f32_e32 v97, 0x45800000, v47
	v_mul_f32_e32 v98, 0x45800000, v95
	v_cndmask_b32_e64 v46, v33, v46, s[2:3]
	v_cndmask_b32_e32 v94, v94, v96, vcc
	v_cndmask_b32_e64 v96, v47, v97, s[6:7]
	v_cndmask_b32_e64 v98, v95, v98, s[4:5]
	v_pk_mul_f32 v[66:67], v[66:67], v[46:47] op_sel_hi:[1,0]
	v_pk_mul_f32 v[68:69], v[68:69], v[46:47] op_sel_hi:[1,0]
	v_pk_mul_f32 v[74:75], v[74:75], v[94:95] op_sel_hi:[1,0]
	v_pk_mul_f32 v[76:77], v[76:77], v[94:95] op_sel_hi:[1,0]
	v_pk_mul_f32 v[82:83], v[82:83], v[96:97] op_sel_hi:[1,0]
	v_pk_mul_f32 v[84:85], v[84:85], v[96:97] op_sel_hi:[1,0]
	v_pk_mul_f32 v[100:101], v[58:59], v[98:99] op_sel_hi:[1,0]
	v_pk_mul_f32 v[102:103], v[60:61], v[98:99] op_sel_hi:[1,0]
	v_pk_mul_f32 v[58:59], v[0:1], v[66:67]
	v_pk_mul_f32 v[60:61], v[2:3], v[68:69]
	v_pk_mul_f32 v[66:67], v[0:1], v[74:75]
	v_pk_mul_f32 v[68:69], v[2:3], v[76:77]
	v_pk_mul_f32 v[74:75], v[0:1], v[82:83]
	v_pk_mul_f32 v[76:77], v[2:3], v[84:85]
	v_pk_mul_f32 v[0:1], v[0:1], v[100:101]
	v_pk_mul_f32 v[2:3], v[2:3], v[102:103]
	global_store_dwordx4 v[48:49], v[58:61], off
	global_store_dwordx4 v[50:51], v[66:69], off
	global_store_dwordx4 v[44:45], v[74:77], off
	global_store_dwordx4 v[48:49], v[0:3], off offset:-4096
	global_load_dwordx4 v[0:3], v[36:37], off offset:1024
	v_pk_mul_f32 v[58:59], v[86:87], v[96:97] op_sel_hi:[1,0]
	v_pk_mul_f32 v[60:61], v[88:89], v[96:97] op_sel_hi:[1,0]
	v_add_co_u32_e32 v74, vcc, s21, v44
	v_pk_mul_f32 v[66:67], v[70:71], v[46:47] op_sel_hi:[1,0]
	v_pk_mul_f32 v[68:69], v[72:73], v[46:47] op_sel_hi:[1,0]
	v_pk_mul_f32 v[70:71], v[78:79], v[94:95] op_sel_hi:[1,0]
	v_pk_mul_f32 v[72:73], v[80:81], v[94:95] op_sel_hi:[1,0]
	v_pk_mul_f32 v[62:63], v[62:63], v[98:99] op_sel_hi:[1,0]
	v_pk_mul_f32 v[64:65], v[64:65], v[98:99] op_sel_hi:[1,0]
	v_addc_co_u32_e32 v75, vcc, 0, v45, vcc
	v_cmp_lt_i32_e32 vcc, s23, v32
	s_or_b64 s[14:15], vcc, s[14:15]
	s_waitcnt vmcnt(0)
	v_pk_mul_f32 v[58:59], v[58:59], v[0:1]
	v_pk_mul_f32 v[60:61], v[60:61], v[2:3]
	v_pk_mul_f32 v[62:63], v[62:63], v[0:1]
	v_pk_mul_f32 v[64:65], v[64:65], v[2:3]
	v_pk_mul_f32 v[66:67], v[66:67], v[0:1]
	v_pk_mul_f32 v[68:69], v[68:69], v[2:3]
	v_pk_mul_f32 v[0:1], v[70:71], v[0:1]
	v_pk_mul_f32 v[2:3], v[72:73], v[2:3]
	global_store_dwordx4 v[44:45], v[58:61], off offset:1024
	global_store_dwordx4 v[74:75], v[62:65], off offset:1024
	global_store_dwordx4 v[48:49], v[66:69], off offset:1024
	global_store_dwordx4 v[50:51], v[0:3], off offset:1024
	global_load_dwordx4 v[0:3], v[36:37], off offset:2048
	v_pk_mul_f32 v[58:59], v[24:25], v[46:47] op_sel_hi:[1,0]
	v_pk_mul_f32 v[60:61], v[26:27], v[46:47] op_sel_hi:[1,0]
	v_pk_mul_f32 v[24:25], v[90:91], v[96:97] op_sel_hi:[1,0]
	v_pk_mul_f32 v[26:27], v[92:93], v[96:97] op_sel_hi:[1,0]
	v_pk_mul_f32 v[62:63], v[28:29], v[94:95] op_sel_hi:[1,0]
	v_pk_mul_f32 v[64:65], v[30:31], v[94:95] op_sel_hi:[1,0]
	v_pk_mul_f32 v[28:29], v[20:21], v[98:99] op_sel_hi:[1,0]
	v_pk_mul_f32 v[30:31], v[22:23], v[98:99] op_sel_hi:[1,0]
	s_waitcnt vmcnt(0)
	v_pk_mul_f32 v[20:21], v[24:25], v[0:1]
	v_pk_mul_f32 v[22:23], v[26:27], v[2:3]
	v_pk_mul_f32 v[24:25], v[28:29], v[0:1]
	v_pk_mul_f32 v[26:27], v[30:31], v[2:3]
	v_pk_mul_f32 v[28:29], v[58:59], v[0:1]
	v_pk_mul_f32 v[30:31], v[60:61], v[2:3]
	v_pk_mul_f32 v[0:1], v[62:63], v[0:1]
	v_pk_mul_f32 v[2:3], v[64:65], v[2:3]
	global_store_dwordx4 v[44:45], v[20:23], off offset:2048
	global_store_dwordx4 v[74:75], v[24:27], off offset:2048
	global_store_dwordx4 v[48:49], v[28:31], off offset:2048
	global_store_dwordx4 v[50:51], v[0:3], off offset:2048
	global_load_dwordx4 v[0:3], v[36:37], off offset:3072
	v_pk_mul_f32 v[20:21], v[8:9], v[46:47] op_sel_hi:[1,0]
	v_pk_mul_f32 v[22:23], v[10:11], v[46:47] op_sel_hi:[1,0]
	v_pk_mul_f32 v[8:9], v[16:17], v[96:97] op_sel_hi:[1,0]
	v_pk_mul_f32 v[10:11], v[18:19], v[96:97] op_sel_hi:[1,0]
	v_pk_mul_f32 v[24:25], v[12:13], v[94:95] op_sel_hi:[1,0]
	v_pk_mul_f32 v[26:27], v[14:15], v[94:95] op_sel_hi:[1,0]
	v_pk_mul_f32 v[12:13], v[4:5], v[98:99] op_sel_hi:[1,0]
	v_pk_mul_f32 v[14:15], v[6:7], v[98:99] op_sel_hi:[1,0]
	s_waitcnt vmcnt(0)
	v_pk_mul_f32 v[4:5], v[8:9], v[0:1]
	v_pk_mul_f32 v[6:7], v[10:11], v[2:3]
	v_pk_mul_f32 v[8:9], v[12:13], v[0:1]
	v_pk_mul_f32 v[10:11], v[14:15], v[2:3]
	v_pk_mul_f32 v[12:13], v[20:21], v[0:1]
	v_pk_mul_f32 v[14:15], v[22:23], v[2:3]
	v_pk_mul_f32 v[0:1], v[24:25], v[0:1]
	v_pk_mul_f32 v[2:3], v[26:27], v[2:3]
	global_store_dwordx4 v[44:45], v[4:7], off offset:3072
	global_store_dwordx4 v[74:75], v[8:11], off offset:3072
	global_store_dwordx4 v[48:49], v[12:15], off offset:3072
	global_store_dwordx4 v[50:51], v[0:3], off offset:3072
	s_andn2_b64 exec, exec, s[14:15]
	s_cbranch_execnz .LBB0_2972
